# GEMM LDS-DMA pieces addressed as SGPR base + 32-bit VGPR offset where the 64-bit VGPR address was single-use (8 of 16 v_lshl_add_u64 per K-iteration removed)
# speedup vs baseline: 1.0030x; 1.0002x over previous
.LBB0_324:
	s_bfe_u32 s58, s74, 0x20006
	s_lshl_b32 s59, s16, 6
	s_lshl_b32 s60, s58, 5
	s_cmpk_lt_u32 s74, 0x100
	s_mov_b64 s[34:35], 0x80
	s_cselect_b64 s[18:19], -1, 0
	v_lshl_add_u64 v[6:7], v[6:7], 0, s[34:35]
	s_add_i32 m0, s28, 0x18000
	s_waitcnt vmcnt(2)
	s_barrier
	global_load_lds_dwordx4 v[6:7], off
	v_lshl_add_u64 v[4:5], v[4:5], 0, s[34:35]
	s_add_i32 m0, s28, 0x1a000
	s_add_i32 s61, s28, 0x8000
	s_add_i32 s62, s28, 0xa000
	global_load_lds_dwordx4 v[4:5], off
	v_lshl_add_u64 v[2:3], v[2:3], 0, s[34:35]
	s_mov_b32 m0, s61
	s_add_u32 s10, s8, 0x40080
	global_load_lds_dwordx4 v[2:3], off
	v_lshl_add_u64 v[0:1], v[0:1], 0, s[34:35]
	s_mov_b32 m0, s62
	s_addc_u32 s11, s9, 0
	global_load_lds_dwordx4 v[0:1], off
	s_add_i32 m0, s28, 0x1c000
	v_lshlrev_b32_e32 v3, 6, v8
	global_load_lds_dwordx4 v146, s[10:11]
	v_lshl_add_u64 v[0:1], s[10:11], 0, v[150:151]
	s_add_i32 m0, s28, 0x1e000
	s_movk_i32 s10, 0x3c0
	global_load_lds_dwordx4 v[0:1], off
	v_and_b32_e32 v1, 64, v244
	v_xor_b32_e32 v0, 16, v244
	v_add_u32_e32 v1, 64, v1
	v_cmp_lt_i32_e32 vcc, v0, v1
	s_waitcnt vmcnt(6)
	s_add_i32 s63, 0, 0x10000
	s_add_i32 s64, 0, 0x14000
	v_cndmask_b32_e32 v0, v244, v0, vcc
	v_lshlrev_b32_e32 v166, 2, v0
	v_xor_b32_e32 v0, 32, v244
	v_cmp_lt_i32_e32 vcc, v0, v1
	v_and_b32_e32 v1, 0xfffffc00, v12
	v_lshl_add_u32 v2, s16, 13, v1
	v_cndmask_b32_e32 v0, v244, v0, vcc
	v_lshlrev_b32_e32 v167, 2, v0
	v_and_b32_e32 v0, 48, v8
	v_and_or_b32 v0, v3, s10, v0
	v_lshlrev_b32_e32 v3, 2, v8
	v_and_b32_e32 v3, 32, v3
	v_lshl_add_u32 v1, s58, 12, v1
	v_bitop3_b32 v2, v0, v2, v3 bitop3:0xde
	v_bitop3_b32 v168, v0, v1, v3 bitop3:0xde
	v_lshlrev_b32_e32 v0, 14, v13
	v_and_b32_e32 v0, 0xffff8000, v0
	v_lshl_add_u32 v0, v14, 11, v0
	v_and_b32_e32 v1, 1, v13
	v_lshl_or_b32 v0, v1, 6, v0
	v_lshl_add_u32 v154, v15, 1, v0
	v_lshlrev_b32_e32 v0, 14, v9
	v_and_b32_e32 v0, 0xffff8000, v0
	v_lshl_add_u32 v0, v10, 11, v0
	v_and_b32_e32 v1, 1, v9
	v_lshl_or_b32 v0, v1, 6, v0
	v_mov_b32_e32 v155, v153
	v_lshl_add_u32 v156, v11, 1, v0
	v_mov_b32_e32 v157, v153
	v_add_u32_e32 v169, s63, v168
	v_add_u32_e32 v170, s64, v168
	v_add_u32_e32 v171, 0, v2
	s_movk_i32 s65, 0x200
	s_movk_i32 s66, 0x1200
	s_movk_i32 s67, 0x5f
	s_movk_i32 s68, 0x6f
	s_movk_i32 s69, 0x7f
	s_mov_b64 s[36:37], 0xbe00000
	s_movk_i32 s70, 0xf400
	s_mov_b32 s71, 0x9c00000
	v_mov_b32_e32 v172, 0x358637bd
	s_mov_b32 s72, 0x800000
	s_add_i32 s73, 0, 0x20000
	s_mov_b64 s[38:39], 0x7800000
	s_mov_b64 s[40:41], 0x5800000
	v_mov_b32_e32 v173, 0xac00000
	v_mov_b32_e32 v174, 0x8a00000
	v_mov_b32_e32 v175, 0x1200
	v_mov_b32_e32 v176, 0x900
	v_mov_b32_e32 v177, 0x3e38aa3b
	s_mov_b32 s30, 0
	s_barrier
	s_branch .LBB0_327

.LBB0_342:
	s_and_b64 s[10:11], s[48:49], exec
	s_cselect_b32 s50, s45, s5
	s_cselect_b32 s51, s44, s4
	s_cselect_b32 s53, s47, s9
	s_cselect_b32 s54, s46, s8
	s_add_u32 s55, s8, 0x100
	s_addc_u32 s78, s9, 0
	s_add_u32 s4, s4, 0x40080
	v_mov_b32_e32 v0, 0
	s_addc_u32 s5, s5, 0
	s_mov_b32 s79, -2
	ds_read_b128 v[128:131], v169
	ds_read_b128 v[132:135], v169 offset:1024
	ds_read_b128 v[136:139], v169 offset:2048
	ds_read_b128 v[140:143], v169 offset:3072
	ds_read_b128 v[158:161], v170
	ds_read_b128 v[162:165], v170 offset:1024
	ds_read_b128 v[178:181], v170 offset:2048
	ds_read_b128 v[182:185], v170 offset:3072
	s_add_u32 s8, s4, 0xfffc0080
	s_addc_u32 s9, s5, -1
	s_cmp_eq_u32 s79, 12
	s_cselect_b32 s11, s50, s9
	s_cselect_b32 s10, s51, s8
	s_cselect_b32 s9, s53, s78
	s_cselect_b32 s8, s54, s55
	s_add_i32 m0, s28, 0xc000
	ds_read_b128 v[186:189], v171
	ds_read_b128 v[190:193], v171 offset:1024
	ds_read_b128 v[194:197], v171 offset:2048
	ds_read_b128 v[198:201], v171 offset:3072
	ds_read_b128 v[202:205], v171 offset:4096
	ds_read_b128 v[206:209], v171 offset:5120
	ds_read_b128 v[210:213], v171 offset:6144
	ds_read_b128 v[214:217], v171 offset:7168
	global_load_lds_dwordx4 v156, s[4:5]
	s_add_i32 m0, s28, 0xe000
	s_nop 0
	global_load_lds_dwordx4 v154, s[4:5]
	s_waitcnt vmcnt(8)
	s_waitcnt lgkmcnt(0)
	s_barrier
	s_waitcnt lgkmcnt(0)
	v_mfma_f32_16x16x32_bf16 v[124:127], v[128:131], v[186:189], 0
	v_mfma_f32_16x16x32_bf16 v[120:123], v[136:139], v[186:189], 0
	v_mfma_f32_16x16x32_bf16 v[108:111], v[128:131], v[194:197], 0
	v_mfma_f32_16x16x32_bf16 v[104:107], v[136:139], v[194:197], 0
	v_mfma_f32_16x16x32_bf16 v[92:95], v[128:131], v[202:205], 0
	v_mfma_f32_16x16x32_bf16 v[88:91], v[136:139], v[202:205], 0
	v_mfma_f32_16x16x32_bf16 v[76:79], v[128:131], v[210:213], 0
	v_mfma_f32_16x16x32_bf16 v[72:75], v[136:139], v[210:213], 0
	v_mfma_f32_16x16x32_bf16 v[124:127], v[132:135], v[190:193], v[124:127]
	v_mfma_f32_16x16x32_bf16 v[120:123], v[140:143], v[190:193], v[120:123]
	v_mfma_f32_16x16x32_bf16 v[108:111], v[132:135], v[198:201], v[108:111]
	v_mfma_f32_16x16x32_bf16 v[104:107], v[140:143], v[198:201], v[104:107]
	v_mfma_f32_16x16x32_bf16 v[92:95], v[132:135], v[206:209], v[92:95]
	v_mfma_f32_16x16x32_bf16 v[88:91], v[140:143], v[206:209], v[88:91]
	v_mfma_f32_16x16x32_bf16 v[76:79], v[132:135], v[214:217], v[76:79]
	v_mfma_f32_16x16x32_bf16 v[72:75], v[140:143], v[214:217], v[72:75]
	v_mfma_f32_16x16x32_bf16 v[116:119], v[158:161], v[186:189], 0
	v_mfma_f32_16x16x32_bf16 v[112:115], v[178:181], v[186:189], 0
	v_mfma_f32_16x16x32_bf16 v[100:103], v[158:161], v[194:197], 0
	v_mfma_f32_16x16x32_bf16 v[96:99], v[178:181], v[194:197], 0
	v_mfma_f32_16x16x32_bf16 v[84:87], v[158:161], v[202:205], 0
	v_mfma_f32_16x16x32_bf16 v[80:83], v[178:181], v[202:205], 0
	v_mfma_f32_16x16x32_bf16 v[68:71], v[158:161], v[210:213], 0
	v_mfma_f32_16x16x32_bf16 v[64:67], v[178:181], v[210:213], 0
	v_mfma_f32_16x16x32_bf16 v[116:119], v[162:165], v[190:193], v[116:119]
	v_mfma_f32_16x16x32_bf16 v[112:115], v[182:185], v[190:193], v[112:115]
	v_mfma_f32_16x16x32_bf16 v[100:103], v[162:165], v[198:201], v[100:103]
	v_mfma_f32_16x16x32_bf16 v[96:99], v[182:185], v[198:201], v[96:99]
	v_mfma_f32_16x16x32_bf16 v[84:87], v[162:165], v[206:209], v[84:87]
	v_mfma_f32_16x16x32_bf16 v[80:83], v[182:185], v[206:209], v[80:83]
	v_mfma_f32_16x16x32_bf16 v[68:71], v[162:165], v[214:217], v[68:71]
	v_mfma_f32_16x16x32_bf16 v[64:67], v[182:185], v[214:217], v[64:67]
	s_barrier
	s_add_i32 s26, s63, s13
	v_lshl_add_u64 v[218:219], s[8:9], 0, v[146:147]
	s_mov_b32 m0, s26
	ds_read_b128 v[186:189], v171 offset:16384
	ds_read_b128 v[190:193], v171 offset:17408
	ds_read_b128 v[194:197], v171 offset:18432
	ds_read_b128 v[198:201], v171 offset:19456
	ds_read_b128 v[202:205], v171 offset:20480
	ds_read_b128 v[206:209], v171 offset:21504
	ds_read_b128 v[210:213], v171 offset:22528
	ds_read_b128 v[214:217], v171 offset:23552
	global_load_lds_dwordx4 v[218:219], off
	s_add_i32 m0, s26, 0x2000
	s_add_u32 s26, s8, 0x40000
	v_lshl_add_u64 v[220:221], s[8:9], 0, v[150:151]
	s_addc_u32 s27, s9, 0
	s_add_i32 s77, s64, s13
	global_load_lds_dwordx4 v[220:221], off
	s_mov_b32 m0, s77
	v_lshl_add_u64 v[224:225], s[10:11], 0, v[148:149]
	global_load_lds_dwordx4 v146, s[26:27]
	s_add_i32 m0, s77, 0x2000
	s_nop 0
	global_load_lds_dwordx4 v150, s[26:27]
	v_lshl_add_u64 v[222:223], s[10:11], 0, v[144:145]
	s_mov_b32 m0, s28
	s_nop 0
	global_load_lds_dwordx4 v[222:223], off
	s_mov_b32 m0, s29
	s_nop 0
	global_load_lds_dwordx4 v[224:225], off
	s_waitcnt vmcnt(8)
	s_waitcnt lgkmcnt(0)
	s_barrier
	s_waitcnt lgkmcnt(0)
	v_mfma_f32_16x16x32_bf16 v[60:63], v[128:131], v[186:189], 0
	v_mfma_f32_16x16x32_bf16 v[56:59], v[136:139], v[186:189], 0
	v_mfma_f32_16x16x32_bf16 v[44:47], v[128:131], v[194:197], 0
	v_mfma_f32_16x16x32_bf16 v[40:43], v[136:139], v[194:197], 0
	v_mfma_f32_16x16x32_bf16 v[28:31], v[128:131], v[202:205], 0
	v_mfma_f32_16x16x32_bf16 v[24:27], v[136:139], v[202:205], 0
	v_mfma_f32_16x16x32_bf16 v[12:15], v[128:131], v[210:213], 0
	v_mfma_f32_16x16x32_bf16 v[8:11], v[136:139], v[210:213], 0
	v_mfma_f32_16x16x32_bf16 v[60:63], v[132:135], v[190:193], v[60:63]
	v_mfma_f32_16x16x32_bf16 v[56:59], v[140:143], v[190:193], v[56:59]
	v_mfma_f32_16x16x32_bf16 v[44:47], v[132:135], v[198:201], v[44:47]
	v_mfma_f32_16x16x32_bf16 v[40:43], v[140:143], v[198:201], v[40:43]
	v_mfma_f32_16x16x32_bf16 v[28:31], v[132:135], v[206:209], v[28:31]
	v_mfma_f32_16x16x32_bf16 v[24:27], v[140:143], v[206:209], v[24:27]
	v_mfma_f32_16x16x32_bf16 v[12:15], v[132:135], v[214:217], v[12:15]
	v_mfma_f32_16x16x32_bf16 v[8:11], v[140:143], v[214:217], v[8:11]
	v_mfma_f32_16x16x32_bf16 v[52:55], v[158:161], v[186:189], 0
	v_mfma_f32_16x16x32_bf16 v[48:51], v[178:181], v[186:189], 0
	v_mfma_f32_16x16x32_bf16 v[36:39], v[158:161], v[194:197], 0
	v_mfma_f32_16x16x32_bf16 v[32:35], v[178:181], v[194:197], 0
	v_mfma_f32_16x16x32_bf16 v[20:23], v[158:161], v[202:205], 0
	v_mfma_f32_16x16x32_bf16 v[16:19], v[178:181], v[202:205], 0
	v_mfma_f32_16x16x32_bf16 v[4:7], v[158:161], v[210:213], 0
	v_mfma_f32_16x16x32_bf16 v[0:3], v[178:181], v[210:213], 0
	v_mfma_f32_16x16x32_bf16 v[52:55], v[162:165], v[190:193], v[52:55]
	v_mfma_f32_16x16x32_bf16 v[48:51], v[182:185], v[190:193], v[48:51]
	v_mfma_f32_16x16x32_bf16 v[36:39], v[162:165], v[198:201], v[36:39]
	v_mfma_f32_16x16x32_bf16 v[32:35], v[182:185], v[198:201], v[32:35]
	v_mfma_f32_16x16x32_bf16 v[20:23], v[162:165], v[206:209], v[20:23]
	v_mfma_f32_16x16x32_bf16 v[16:19], v[182:185], v[206:209], v[16:19]
	v_mfma_f32_16x16x32_bf16 v[4:7], v[162:165], v[214:217], v[4:7]
	v_mfma_f32_16x16x32_bf16 v[0:3], v[182:185], v[214:217], v[0:3]
	s_barrier
	s_add_i32 s26, 0, 0x18000
	s_add_i32 s27, 0, 0x1c000
	v_add_u32_e32 v140, s26, v168
	v_add_u32_e32 v152, s27, v168
	ds_read_b128 v[128:131], v140
	ds_read_b128 v[132:135], v140 offset:1024
	ds_read_b128 v[136:139], v140 offset:2048
	ds_read_b128 v[140:143], v140 offset:3072
	ds_read_b128 v[158:161], v152
	ds_read_b128 v[162:165], v152 offset:1024
	ds_read_b128 v[178:181], v152 offset:2048
	ds_read_b128 v[182:185], v152 offset:3072
	s_add_u32 s10, s10, 0x40000
	s_addc_u32 s11, s11, 0
	s_mov_b32 m0, s56
	ds_read_b128 v[186:189], v171 offset:32768
	ds_read_b128 v[190:193], v171 offset:33792
	ds_read_b128 v[194:197], v171 offset:34816
	ds_read_b128 v[198:201], v171 offset:35840
	ds_read_b128 v[202:205], v171 offset:36864
	ds_read_b128 v[206:209], v171 offset:37888
	ds_read_b128 v[210:213], v171 offset:38912
	ds_read_b128 v[214:217], v171 offset:39936
	global_load_lds_dwordx4 v144, s[10:11]
	s_mov_b32 m0, s57
	s_nop 0
	global_load_lds_dwordx4 v148, s[10:11]
	s_waitcnt vmcnt(8)
	s_waitcnt lgkmcnt(0)
	s_barrier
	s_waitcnt lgkmcnt(0)
	v_mfma_f32_16x16x32_bf16 v[124:127], v[128:131], v[186:189], v[124:127]
	v_mfma_f32_16x16x32_bf16 v[120:123], v[136:139], v[186:189], v[120:123]
	v_mfma_f32_16x16x32_bf16 v[108:111], v[128:131], v[194:197], v[108:111]
	v_mfma_f32_16x16x32_bf16 v[104:107], v[136:139], v[194:197], v[104:107]
	v_mfma_f32_16x16x32_bf16 v[92:95], v[128:131], v[202:205], v[92:95]
	v_mfma_f32_16x16x32_bf16 v[88:91], v[136:139], v[202:205], v[88:91]
	v_mfma_f32_16x16x32_bf16 v[76:79], v[128:131], v[210:213], v[76:79]
	v_mfma_f32_16x16x32_bf16 v[72:75], v[136:139], v[210:213], v[72:75]
	v_mfma_f32_16x16x32_bf16 v[124:127], v[132:135], v[190:193], v[124:127]
	v_mfma_f32_16x16x32_bf16 v[120:123], v[140:143], v[190:193], v[120:123]
	v_mfma_f32_16x16x32_bf16 v[108:111], v[132:135], v[198:201], v[108:111]
	v_mfma_f32_16x16x32_bf16 v[104:107], v[140:143], v[198:201], v[104:107]
	v_mfma_f32_16x16x32_bf16 v[92:95], v[132:135], v[206:209], v[92:95]
	v_mfma_f32_16x16x32_bf16 v[88:91], v[140:143], v[206:209], v[88:91]
	v_mfma_f32_16x16x32_bf16 v[76:79], v[132:135], v[214:217], v[76:79]
	v_mfma_f32_16x16x32_bf16 v[72:75], v[140:143], v[214:217], v[72:75]
	v_mfma_f32_16x16x32_bf16 v[116:119], v[158:161], v[186:189], v[116:119]
	v_mfma_f32_16x16x32_bf16 v[112:115], v[178:181], v[186:189], v[112:115]
	v_mfma_f32_16x16x32_bf16 v[100:103], v[158:161], v[194:197], v[100:103]
	v_mfma_f32_16x16x32_bf16 v[96:99], v[178:181], v[194:197], v[96:99]
	v_mfma_f32_16x16x32_bf16 v[84:87], v[158:161], v[202:205], v[84:87]
	v_mfma_f32_16x16x32_bf16 v[80:83], v[178:181], v[202:205], v[80:83]
	v_mfma_f32_16x16x32_bf16 v[68:71], v[158:161], v[210:213], v[68:71]
	v_mfma_f32_16x16x32_bf16 v[64:67], v[178:181], v[210:213], v[64:67]
	v_mfma_f32_16x16x32_bf16 v[116:119], v[162:165], v[190:193], v[116:119]
	v_mfma_f32_16x16x32_bf16 v[112:115], v[182:185], v[190:193], v[112:115]
	v_mfma_f32_16x16x32_bf16 v[100:103], v[162:165], v[198:201], v[100:103]
	v_mfma_f32_16x16x32_bf16 v[96:99], v[182:185], v[198:201], v[96:99]
	v_mfma_f32_16x16x32_bf16 v[84:87], v[162:165], v[206:209], v[84:87]
	v_mfma_f32_16x16x32_bf16 v[80:83], v[182:185], v[206:209], v[80:83]
	v_mfma_f32_16x16x32_bf16 v[68:71], v[162:165], v[214:217], v[68:71]
	v_mfma_f32_16x16x32_bf16 v[64:67], v[182:185], v[214:217], v[64:67]
	s_barrier
	s_add_i32 s10, s26, s13
	v_lshl_add_u64 v[218:219], v[218:219], 0, s[34:35]
	s_mov_b32 m0, s10
	ds_read_b128 v[186:189], v171 offset:49152
	ds_read_b128 v[190:193], v171 offset:50176
	ds_read_b128 v[194:197], v171 offset:51200
	ds_read_b128 v[198:201], v171 offset:52224
	ds_read_b128 v[202:205], v171 offset:53248
	ds_read_b128 v[206:209], v171 offset:54272
	ds_read_b128 v[210:213], v171 offset:55296
	ds_read_b128 v[214:217], v171 offset:56320
	global_load_lds_dwordx4 v[218:219], off
	s_add_i32 m0, s10, 0x2000
	s_add_u32 s8, s8, 0x40080
	v_lshl_add_u64 v[218:219], v[220:221], 0, s[34:35]
	s_addc_u32 s9, s9, 0
	s_add_i32 s10, s27, s13
	global_load_lds_dwordx4 v[218:219], off
	s_mov_b32 m0, s10
	s_nop 0
	global_load_lds_dwordx4 v146, s[8:9]
	s_add_i32 m0, s10, 0x2000
	s_nop 0
	global_load_lds_dwordx4 v150, s[8:9]
	v_lshl_add_u64 v[218:219], v[222:223], 0, s[34:35]
	s_mov_b32 m0, s61
	s_nop 0
	global_load_lds_dwordx4 v[218:219], off
	v_lshl_add_u64 v[218:219], v[224:225], 0, s[34:35]
	s_mov_b32 m0, s62
	s_nop 0
	global_load_lds_dwordx4 v[218:219], off
	s_waitcnt vmcnt(8)
	s_waitcnt lgkmcnt(0)
	s_barrier
	s_waitcnt lgkmcnt(0)
	v_mfma_f32_16x16x32_bf16 v[60:63], v[128:131], v[186:189], v[60:63]
	v_mfma_f32_16x16x32_bf16 v[56:59], v[136:139], v[186:189], v[56:59]
	v_mfma_f32_16x16x32_bf16 v[44:47], v[128:131], v[194:197], v[44:47]
	v_mfma_f32_16x16x32_bf16 v[40:43], v[136:139], v[194:197], v[40:43]
	v_mfma_f32_16x16x32_bf16 v[28:31], v[128:131], v[202:205], v[28:31]
	v_mfma_f32_16x16x32_bf16 v[24:27], v[136:139], v[202:205], v[24:27]
	v_mfma_f32_16x16x32_bf16 v[12:15], v[128:131], v[210:213], v[12:15]
	v_mfma_f32_16x16x32_bf16 v[8:11], v[136:139], v[210:213], v[8:11]
	v_mfma_f32_16x16x32_bf16 v[60:63], v[132:135], v[190:193], v[60:63]
	v_mfma_f32_16x16x32_bf16 v[56:59], v[140:143], v[190:193], v[56:59]
	v_mfma_f32_16x16x32_bf16 v[44:47], v[132:135], v[198:201], v[44:47]
	v_mfma_f32_16x16x32_bf16 v[40:43], v[140:143], v[198:201], v[40:43]
	v_mfma_f32_16x16x32_bf16 v[28:31], v[132:135], v[206:209], v[28:31]
	v_mfma_f32_16x16x32_bf16 v[24:27], v[140:143], v[206:209], v[24:27]
	v_mfma_f32_16x16x32_bf16 v[12:15], v[132:135], v[214:217], v[12:15]
	v_mfma_f32_16x16x32_bf16 v[8:11], v[140:143], v[214:217], v[8:11]
	v_mfma_f32_16x16x32_bf16 v[52:55], v[158:161], v[186:189], v[52:55]
	v_mfma_f32_16x16x32_bf16 v[48:51], v[178:181], v[186:189], v[48:51]
	v_mfma_f32_16x16x32_bf16 v[36:39], v[158:161], v[194:197], v[36:39]
	v_mfma_f32_16x16x32_bf16 v[32:35], v[178:181], v[194:197], v[32:35]
	v_mfma_f32_16x16x32_bf16 v[20:23], v[158:161], v[202:205], v[20:23]
	v_mfma_f32_16x16x32_bf16 v[16:19], v[178:181], v[202:205], v[16:19]
	v_mfma_f32_16x16x32_bf16 v[4:7], v[158:161], v[210:213], v[4:7]
	v_mfma_f32_16x16x32_bf16 v[0:3], v[178:181], v[210:213], v[0:3]
	v_mfma_f32_16x16x32_bf16 v[52:55], v[162:165], v[190:193], v[52:55]
	v_mfma_f32_16x16x32_bf16 v[48:51], v[182:185], v[190:193], v[48:51]
	v_mfma_f32_16x16x32_bf16 v[36:39], v[162:165], v[198:201], v[36:39]
	v_mfma_f32_16x16x32_bf16 v[32:35], v[182:185], v[198:201], v[32:35]
	v_mfma_f32_16x16x32_bf16 v[20:23], v[162:165], v[206:209], v[20:23]
	v_mfma_f32_16x16x32_bf16 v[16:19], v[182:185], v[206:209], v[16:19]
	v_mfma_f32_16x16x32_bf16 v[4:7], v[162:165], v[214:217], v[4:7]
	v_mfma_f32_16x16x32_bf16 v[0:3], v[182:185], v[214:217], v[0:3]
	s_barrier
	s_add_i32 s79, s79, 2
	s_add_u32 s55, s55, 0x100
	s_addc_u32 s78, s78, 0
	s_add_u32 s4, s4, 0x100
	s_addc_u32 s5, s5, 0
.LBB0_343:
	ds_read_b128 v[128:131], v169
	ds_read_b128 v[132:135], v169 offset:1024
	ds_read_b128 v[136:139], v169 offset:2048
	ds_read_b128 v[140:143], v169 offset:3072
	ds_read_b128 v[158:161], v170
	ds_read_b128 v[162:165], v170 offset:1024
	ds_read_b128 v[178:181], v170 offset:2048
	ds_read_b128 v[182:185], v170 offset:3072
	s_add_u32 s8, s4, 0xfffc0080
	s_addc_u32 s9, s5, -1
	s_cmp_eq_u32 s79, 12
	s_cselect_b32 s11, s50, s9
	s_cselect_b32 s10, s51, s8
	s_cselect_b32 s9, s53, s78
	s_cselect_b32 s8, s54, s55
	s_add_i32 m0, s28, 0xc000
	ds_read_b128 v[186:189], v171
	ds_read_b128 v[190:193], v171 offset:1024
	ds_read_b128 v[194:197], v171 offset:2048
	ds_read_b128 v[198:201], v171 offset:3072
	ds_read_b128 v[202:205], v171 offset:4096
	ds_read_b128 v[206:209], v171 offset:5120
	ds_read_b128 v[210:213], v171 offset:6144
	ds_read_b128 v[214:217], v171 offset:7168
	global_load_lds_dwordx4 v156, s[4:5]
	s_add_i32 m0, s28, 0xe000
	s_nop 0
	global_load_lds_dwordx4 v154, s[4:5]
	s_waitcnt vmcnt(8)
	s_waitcnt lgkmcnt(0)
	s_barrier
	s_waitcnt lgkmcnt(0)
	v_mfma_f32_16x16x32_bf16 v[124:127], v[128:131], v[186:189], v[124:127]
	v_mfma_f32_16x16x32_bf16 v[120:123], v[136:139], v[186:189], v[120:123]
	v_mfma_f32_16x16x32_bf16 v[108:111], v[128:131], v[194:197], v[108:111]
	v_mfma_f32_16x16x32_bf16 v[104:107], v[136:139], v[194:197], v[104:107]
	v_mfma_f32_16x16x32_bf16 v[92:95], v[128:131], v[202:205], v[92:95]
	v_mfma_f32_16x16x32_bf16 v[88:91], v[136:139], v[202:205], v[88:91]
	v_mfma_f32_16x16x32_bf16 v[76:79], v[128:131], v[210:213], v[76:79]
	v_mfma_f32_16x16x32_bf16 v[72:75], v[136:139], v[210:213], v[72:75]
	v_mfma_f32_16x16x32_bf16 v[124:127], v[132:135], v[190:193], v[124:127]
	v_mfma_f32_16x16x32_bf16 v[120:123], v[140:143], v[190:193], v[120:123]
	v_mfma_f32_16x16x32_bf16 v[108:111], v[132:135], v[198:201], v[108:111]
	v_mfma_f32_16x16x32_bf16 v[104:107], v[140:143], v[198:201], v[104:107]
	v_mfma_f32_16x16x32_bf16 v[92:95], v[132:135], v[206:209], v[92:95]
	v_mfma_f32_16x16x32_bf16 v[88:91], v[140:143], v[206:209], v[88:91]
	v_mfma_f32_16x16x32_bf16 v[76:79], v[132:135], v[214:217], v[76:79]
	v_mfma_f32_16x16x32_bf16 v[72:75], v[140:143], v[214:217], v[72:75]
	v_mfma_f32_16x16x32_bf16 v[116:119], v[158:161], v[186:189], v[116:119]
	v_mfma_f32_16x16x32_bf16 v[112:115], v[178:181], v[186:189], v[112:115]
	v_mfma_f32_16x16x32_bf16 v[100:103], v[158:161], v[194:197], v[100:103]
	v_mfma_f32_16x16x32_bf16 v[96:99], v[178:181], v[194:197], v[96:99]
	v_mfma_f32_16x16x32_bf16 v[84:87], v[158:161], v[202:205], v[84:87]
	v_mfma_f32_16x16x32_bf16 v[80:83], v[178:181], v[202:205], v[80:83]
	v_mfma_f32_16x16x32_bf16 v[68:71], v[158:161], v[210:213], v[68:71]
	v_mfma_f32_16x16x32_bf16 v[64:67], v[178:181], v[210:213], v[64:67]
	v_mfma_f32_16x16x32_bf16 v[116:119], v[162:165], v[190:193], v[116:119]
	v_mfma_f32_16x16x32_bf16 v[112:115], v[182:185], v[190:193], v[112:115]
	v_mfma_f32_16x16x32_bf16 v[100:103], v[162:165], v[198:201], v[100:103]
	v_mfma_f32_16x16x32_bf16 v[96:99], v[182:185], v[198:201], v[96:99]
	v_mfma_f32_16x16x32_bf16 v[84:87], v[162:165], v[206:209], v[84:87]
	v_mfma_f32_16x16x32_bf16 v[80:83], v[182:185], v[206:209], v[80:83]
	v_mfma_f32_16x16x32_bf16 v[68:71], v[162:165], v[214:217], v[68:71]
	v_mfma_f32_16x16x32_bf16 v[64:67], v[182:185], v[214:217], v[64:67]
	s_barrier
	s_add_i32 s26, s63, s13
	v_lshl_add_u64 v[218:219], s[8:9], 0, v[146:147]
	s_mov_b32 m0, s26
	ds_read_b128 v[186:189], v171 offset:16384
	ds_read_b128 v[190:193], v171 offset:17408
	ds_read_b128 v[194:197], v171 offset:18432
	ds_read_b128 v[198:201], v171 offset:19456
	ds_read_b128 v[202:205], v171 offset:20480
	ds_read_b128 v[206:209], v171 offset:21504
	ds_read_b128 v[210:213], v171 offset:22528
	ds_read_b128 v[214:217], v171 offset:23552
	global_load_lds_dwordx4 v[218:219], off
	s_add_i32 m0, s26, 0x2000
	s_add_u32 s26, s8, 0x40000
	v_lshl_add_u64 v[220:221], s[8:9], 0, v[150:151]
	s_addc_u32 s27, s9, 0
	s_add_i32 s77, s64, s13
	global_load_lds_dwordx4 v[220:221], off
	s_mov_b32 m0, s77
	v_lshl_add_u64 v[224:225], s[10:11], 0, v[148:149]
	global_load_lds_dwordx4 v146, s[26:27]
	s_add_i32 m0, s77, 0x2000
	s_nop 0
	global_load_lds_dwordx4 v150, s[26:27]
	v_lshl_add_u64 v[222:223], s[10:11], 0, v[144:145]
	s_mov_b32 m0, s28
	s_nop 0
	global_load_lds_dwordx4 v[222:223], off
	s_mov_b32 m0, s29
	s_nop 0
	global_load_lds_dwordx4 v[224:225], off
	s_waitcnt vmcnt(8)
	s_waitcnt lgkmcnt(0)
	s_barrier
	s_waitcnt lgkmcnt(0)
	v_mfma_f32_16x16x32_bf16 v[60:63], v[128:131], v[186:189], v[60:63]
	v_mfma_f32_16x16x32_bf16 v[56:59], v[136:139], v[186:189], v[56:59]
	v_mfma_f32_16x16x32_bf16 v[44:47], v[128:131], v[194:197], v[44:47]
	v_mfma_f32_16x16x32_bf16 v[40:43], v[136:139], v[194:197], v[40:43]
	v_mfma_f32_16x16x32_bf16 v[28:31], v[128:131], v[202:205], v[28:31]
	v_mfma_f32_16x16x32_bf16 v[24:27], v[136:139], v[202:205], v[24:27]
	v_mfma_f32_16x16x32_bf16 v[12:15], v[128:131], v[210:213], v[12:15]
	v_mfma_f32_16x16x32_bf16 v[8:11], v[136:139], v[210:213], v[8:11]
	v_mfma_f32_16x16x32_bf16 v[60:63], v[132:135], v[190:193], v[60:63]
	v_mfma_f32_16x16x32_bf16 v[56:59], v[140:143], v[190:193], v[56:59]
	v_mfma_f32_16x16x32_bf16 v[44:47], v[132:135], v[198:201], v[44:47]
	v_mfma_f32_16x16x32_bf16 v[40:43], v[140:143], v[198:201], v[40:43]
	v_mfma_f32_16x16x32_bf16 v[28:31], v[132:135], v[206:209], v[28:31]
	v_mfma_f32_16x16x32_bf16 v[24:27], v[140:143], v[206:209], v[24:27]
	v_mfma_f32_16x16x32_bf16 v[12:15], v[132:135], v[214:217], v[12:15]
	v_mfma_f32_16x16x32_bf16 v[8:11], v[140:143], v[214:217], v[8:11]
	v_mfma_f32_16x16x32_bf16 v[52:55], v[158:161], v[186:189], v[52:55]
	v_mfma_f32_16x16x32_bf16 v[48:51], v[178:181], v[186:189], v[48:51]
	v_mfma_f32_16x16x32_bf16 v[36:39], v[158:161], v[194:197], v[36:39]
	v_mfma_f32_16x16x32_bf16 v[32:35], v[178:181], v[194:197], v[32:35]
	v_mfma_f32_16x16x32_bf16 v[20:23], v[158:161], v[202:205], v[20:23]
	v_mfma_f32_16x16x32_bf16 v[16:19], v[178:181], v[202:205], v[16:19]
	v_mfma_f32_16x16x32_bf16 v[4:7], v[158:161], v[210:213], v[4:7]
	v_mfma_f32_16x16x32_bf16 v[0:3], v[178:181], v[210:213], v[0:3]
	v_mfma_f32_16x16x32_bf16 v[52:55], v[162:165], v[190:193], v[52:55]
	v_mfma_f32_16x16x32_bf16 v[48:51], v[182:185], v[190:193], v[48:51]
	v_mfma_f32_16x16x32_bf16 v[36:39], v[162:165], v[198:201], v[36:39]
	v_mfma_f32_16x16x32_bf16 v[32:35], v[182:185], v[198:201], v[32:35]
	v_mfma_f32_16x16x32_bf16 v[20:23], v[162:165], v[206:209], v[20:23]
	v_mfma_f32_16x16x32_bf16 v[16:19], v[182:185], v[206:209], v[16:19]
	v_mfma_f32_16x16x32_bf16 v[4:7], v[162:165], v[214:217], v[4:7]
	v_mfma_f32_16x16x32_bf16 v[0:3], v[182:185], v[214:217], v[0:3]
	s_barrier
	s_add_i32 s26, 0, 0x18000
	s_add_i32 s27, 0, 0x1c000
	v_add_u32_e32 v140, s26, v168
	v_add_u32_e32 v152, s27, v168
	ds_read_b128 v[128:131], v140
	ds_read_b128 v[132:135], v140 offset:1024
	ds_read_b128 v[136:139], v140 offset:2048
	ds_read_b128 v[140:143], v140 offset:3072
	ds_read_b128 v[158:161], v152
	ds_read_b128 v[162:165], v152 offset:1024
	ds_read_b128 v[178:181], v152 offset:2048
	ds_read_b128 v[182:185], v152 offset:3072
	s_add_u32 s10, s10, 0x40000
	s_addc_u32 s11, s11, 0
	s_mov_b32 m0, s56
	ds_read_b128 v[186:189], v171 offset:32768
	ds_read_b128 v[190:193], v171 offset:33792
	ds_read_b128 v[194:197], v171 offset:34816
	ds_read_b128 v[198:201], v171 offset:35840
	ds_read_b128 v[202:205], v171 offset:36864
	ds_read_b128 v[206:209], v171 offset:37888
	ds_read_b128 v[210:213], v171 offset:38912
	ds_read_b128 v[214:217], v171 offset:39936
	global_load_lds_dwordx4 v144, s[10:11]
	v_lshl_add_u64 v[226:227], s[10:11], 0, v[148:149]
	s_mov_b32 m0, s57
	s_nop 0
	global_load_lds_dwordx4 v[226:227], off
	s_waitcnt vmcnt(8)
	s_waitcnt lgkmcnt(0)
	s_barrier
	s_waitcnt lgkmcnt(0)
	v_mfma_f32_16x16x32_bf16 v[124:127], v[128:131], v[186:189], v[124:127]
	v_mfma_f32_16x16x32_bf16 v[120:123], v[136:139], v[186:189], v[120:123]
	v_mfma_f32_16x16x32_bf16 v[108:111], v[128:131], v[194:197], v[108:111]
	v_mfma_f32_16x16x32_bf16 v[104:107], v[136:139], v[194:197], v[104:107]
	v_mfma_f32_16x16x32_bf16 v[92:95], v[128:131], v[202:205], v[92:95]
	v_mfma_f32_16x16x32_bf16 v[88:91], v[136:139], v[202:205], v[88:91]
	v_mfma_f32_16x16x32_bf16 v[76:79], v[128:131], v[210:213], v[76:79]
	v_mfma_f32_16x16x32_bf16 v[72:75], v[136:139], v[210:213], v[72:75]
	v_mfma_f32_16x16x32_bf16 v[124:127], v[132:135], v[190:193], v[124:127]
	v_mfma_f32_16x16x32_bf16 v[120:123], v[140:143], v[190:193], v[120:123]
	v_mfma_f32_16x16x32_bf16 v[108:111], v[132:135], v[198:201], v[108:111]
	v_mfma_f32_16x16x32_bf16 v[104:107], v[140:143], v[198:201], v[104:107]
	v_mfma_f32_16x16x32_bf16 v[92:95], v[132:135], v[206:209], v[92:95]
	v_mfma_f32_16x16x32_bf16 v[88:91], v[140:143], v[206:209], v[88:91]
	v_mfma_f32_16x16x32_bf16 v[76:79], v[132:135], v[214:217], v[76:79]
	v_mfma_f32_16x16x32_bf16 v[72:75], v[140:143], v[214:217], v[72:75]
	v_mfma_f32_16x16x32_bf16 v[116:119], v[158:161], v[186:189], v[116:119]
	v_mfma_f32_16x16x32_bf16 v[112:115], v[178:181], v[186:189], v[112:115]
	v_mfma_f32_16x16x32_bf16 v[100:103], v[158:161], v[194:197], v[100:103]
	v_mfma_f32_16x16x32_bf16 v[96:99], v[178:181], v[194:197], v[96:99]
	v_mfma_f32_16x16x32_bf16 v[84:87], v[158:161], v[202:205], v[84:87]
	v_mfma_f32_16x16x32_bf16 v[80:83], v[178:181], v[202:205], v[80:83]
	v_mfma_f32_16x16x32_bf16 v[68:71], v[158:161], v[210:213], v[68:71]
	v_mfma_f32_16x16x32_bf16 v[64:67], v[178:181], v[210:213], v[64:67]
	v_mfma_f32_16x16x32_bf16 v[116:119], v[162:165], v[190:193], v[116:119]
	v_mfma_f32_16x16x32_bf16 v[112:115], v[182:185], v[190:193], v[112:115]
	v_mfma_f32_16x16x32_bf16 v[100:103], v[162:165], v[198:201], v[100:103]
	v_mfma_f32_16x16x32_bf16 v[96:99], v[182:185], v[198:201], v[96:99]
	v_mfma_f32_16x16x32_bf16 v[84:87], v[162:165], v[206:209], v[84:87]
	v_mfma_f32_16x16x32_bf16 v[80:83], v[182:185], v[206:209], v[80:83]
	v_mfma_f32_16x16x32_bf16 v[68:71], v[162:165], v[214:217], v[68:71]
	v_mfma_f32_16x16x32_bf16 v[64:67], v[182:185], v[214:217], v[64:67]
	s_barrier
	s_add_i32 s10, s26, s13
	v_lshl_add_u64 v[218:219], v[218:219], 0, s[34:35]
	s_mov_b32 m0, s10
	ds_read_b128 v[186:189], v171 offset:49152
	ds_read_b128 v[190:193], v171 offset:50176
	ds_read_b128 v[194:197], v171 offset:51200
	ds_read_b128 v[198:201], v171 offset:52224
	ds_read_b128 v[202:205], v171 offset:53248
	ds_read_b128 v[206:209], v171 offset:54272
	ds_read_b128 v[210:213], v171 offset:55296
	ds_read_b128 v[214:217], v171 offset:56320
	global_load_lds_dwordx4 v[218:219], off
	s_add_i32 m0, s10, 0x2000
	s_add_u32 s8, s8, 0x40080
	v_lshl_add_u64 v[218:219], v[220:221], 0, s[34:35]
	s_addc_u32 s9, s9, 0
	s_add_i32 s10, s27, s13
	global_load_lds_dwordx4 v[218:219], off
	s_mov_b32 m0, s10
	s_nop 0
	global_load_lds_dwordx4 v146, s[8:9]
	s_add_i32 m0, s10, 0x2000
	s_nop 0
	global_load_lds_dwordx4 v150, s[8:9]
	v_lshl_add_u64 v[218:219], v[222:223], 0, s[34:35]
	s_mov_b32 m0, s61
	s_nop 0
	global_load_lds_dwordx4 v[218:219], off
	v_lshl_add_u64 v[218:219], v[224:225], 0, s[34:35]
	s_mov_b32 m0, s62
	s_nop 0
	global_load_lds_dwordx4 v[218:219], off
	s_waitcnt vmcnt(8)
	s_waitcnt lgkmcnt(0)
	s_barrier
	s_waitcnt lgkmcnt(0)
	v_mfma_f32_16x16x32_bf16 v[60:63], v[128:131], v[186:189], v[60:63]
	v_mfma_f32_16x16x32_bf16 v[56:59], v[136:139], v[186:189], v[56:59]
	v_mfma_f32_16x16x32_bf16 v[44:47], v[128:131], v[194:197], v[44:47]
	v_mfma_f32_16x16x32_bf16 v[40:43], v[136:139], v[194:197], v[40:43]
	v_mfma_f32_16x16x32_bf16 v[28:31], v[128:131], v[202:205], v[28:31]
	v_mfma_f32_16x16x32_bf16 v[24:27], v[136:139], v[202:205], v[24:27]
	v_mfma_f32_16x16x32_bf16 v[12:15], v[128:131], v[210:213], v[12:15]
	v_mfma_f32_16x16x32_bf16 v[8:11], v[136:139], v[210:213], v[8:11]
	v_mfma_f32_16x16x32_bf16 v[60:63], v[132:135], v[190:193], v[60:63]
	v_mfma_f32_16x16x32_bf16 v[56:59], v[140:143], v[190:193], v[56:59]
	v_mfma_f32_16x16x32_bf16 v[44:47], v[132:135], v[198:201], v[44:47]
	v_mfma_f32_16x16x32_bf16 v[40:43], v[140:143], v[198:201], v[40:43]
	v_mfma_f32_16x16x32_bf16 v[28:31], v[132:135], v[206:209], v[28:31]
	v_mfma_f32_16x16x32_bf16 v[24:27], v[140:143], v[206:209], v[24:27]
	v_mfma_f32_16x16x32_bf16 v[12:15], v[132:135], v[214:217], v[12:15]
	v_mfma_f32_16x16x32_bf16 v[8:11], v[140:143], v[214:217], v[8:11]
	v_mfma_f32_16x16x32_bf16 v[52:55], v[158:161], v[186:189], v[52:55]
	v_mfma_f32_16x16x32_bf16 v[48:51], v[178:181], v[186:189], v[48:51]
	v_mfma_f32_16x16x32_bf16 v[36:39], v[158:161], v[194:197], v[36:39]
	v_mfma_f32_16x16x32_bf16 v[32:35], v[178:181], v[194:197], v[32:35]
	v_mfma_f32_16x16x32_bf16 v[20:23], v[158:161], v[202:205], v[20:23]
	v_mfma_f32_16x16x32_bf16 v[16:19], v[178:181], v[202:205], v[16:19]
	v_mfma_f32_16x16x32_bf16 v[4:7], v[158:161], v[210:213], v[4:7]
	v_mfma_f32_16x16x32_bf16 v[0:3], v[178:181], v[210:213], v[0:3]
	v_mfma_f32_16x16x32_bf16 v[52:55], v[162:165], v[190:193], v[52:55]
	v_mfma_f32_16x16x32_bf16 v[48:51], v[182:185], v[190:193], v[48:51]
	v_mfma_f32_16x16x32_bf16 v[36:39], v[162:165], v[198:201], v[36:39]
	v_mfma_f32_16x16x32_bf16 v[32:35], v[182:185], v[198:201], v[32:35]
	v_mfma_f32_16x16x32_bf16 v[20:23], v[162:165], v[206:209], v[20:23]
	v_mfma_f32_16x16x32_bf16 v[16:19], v[182:185], v[206:209], v[16:19]
	v_mfma_f32_16x16x32_bf16 v[4:7], v[162:165], v[214:217], v[4:7]
	v_mfma_f32_16x16x32_bf16 v[0:3], v[182:185], v[214:217], v[0:3]
	s_barrier
	s_add_i32 s79, s79, 2
	s_add_u32 s55, s55, 0x100
	s_addc_u32 s78, s78, 0
	s_add_u32 s4, s4, 0x100
	s_addc_u32 s5, s5, 0
	s_cmp_gt_u32 s79, 13
	s_cbranch_scc0 .LBB0_343
	s_and_b64 vcc, exec, s[18:19]
	s_cbranch_vccz .LBB0_346
	s_barrier

.LBB0_813:
	s_bfe_u32 s26, s74, 0x20006
	s_lshl_b32 s79, s5, 6
	s_lshl_b32 s80, s26, 5
	s_cmpk_lt_u32 s74, 0x100
	s_mov_b64 s[10:11], 0x80
	s_cselect_b64 s[8:9], -1, 0
	v_lshl_add_u64 v[6:7], v[6:7], 0, s[10:11]
	s_add_i32 m0, s28, 0x18000
	s_waitcnt vmcnt(2)
	s_barrier
	global_load_lds_dwordx4 v[6:7], off
	v_lshl_add_u64 v[4:5], v[4:5], 0, s[10:11]
	s_add_i32 m0, s28, 0x1a000
	s_add_i32 s81, s28, 0x8000
	s_add_i32 s82, s28, 0xa000
	global_load_lds_dwordx4 v[4:5], off
	v_lshl_add_u64 v[2:3], v[2:3], 0, s[10:11]
	s_mov_b32 m0, s81
	s_add_u32 s12, s70, 0x40080
	global_load_lds_dwordx4 v[2:3], off
	v_lshl_add_u64 v[0:1], v[0:1], 0, s[10:11]
	s_mov_b32 m0, s82
	s_addc_u32 s13, s71, 0
	global_load_lds_dwordx4 v[0:1], off
	s_add_i32 m0, s28, 0x1c000
	v_and_b32_e32 v17, 64, v244
	global_load_lds_dwordx4 v194, s[12:13]
	s_add_i32 m0, s28, 0x1e000
	v_xor_b32_e32 v16, 16, v244
	global_load_lds_dwordx4 v198, s[12:13]
	v_add_u32_e32 v17, 64, v17
	v_cmp_lt_i32_e32 vcc, v16, v17
	v_and_b32_e32 v1, 0xfffffc00, v12
	v_lshl_add_u32 v2, s5, 13, v1
	v_cndmask_b32_e32 v0, v244, v16, vcc
	v_lshlrev_b32_e32 v226, 2, v0
	v_xor_b32_e32 v0, 32, v244
	v_cmp_lt_i32_e32 vcc, v0, v17
	v_lshlrev_b32_e32 v3, 6, v8
	s_movk_i32 s5, 0x3c0
	v_cndmask_b32_e32 v0, v244, v0, vcc
	v_lshlrev_b32_e32 v227, 2, v0
	v_and_b32_e32 v0, 48, v8
	v_and_or_b32 v0, v3, s5, v0
	v_lshlrev_b32_e32 v3, 2, v8
	v_and_b32_e32 v3, 32, v3
	v_lshl_add_u32 v1, s26, 12, v1
	v_bitop3_b32 v2, v0, v2, v3 bitop3:0xde
	v_bitop3_b32 v228, v0, v1, v3 bitop3:0xde
	v_lshlrev_b32_e32 v0, 14, v13
	v_and_b32_e32 v0, 0xffff8000, v0
	v_lshl_add_u32 v0, v14, 11, v0
	v_and_b32_e32 v1, 1, v13
	v_lshl_or_b32 v0, v1, 6, v0
	v_lshl_add_u32 v200, v15, 1, v0
	v_lshlrev_b32_e32 v0, 14, v9
	v_and_b32_e32 v0, 0xffff8000, v0
	s_waitcnt vmcnt(6)
	v_lshl_add_u32 v0, v10, 11, v0
	v_and_b32_e32 v1, 1, v9
	v_lshl_or_b32 v0, v1, 6, v0
	s_add_i32 s83, 0, 0x10000
	s_add_i32 s84, 0, 0x14000
	v_mov_b32_e32 v201, v195
	v_lshl_add_u32 v202, v11, 1, v0
	v_mov_b32_e32 v203, v195
	v_add_u32_e32 v229, s83, v228
	v_add_u32_e32 v230, s84, v228
	v_add_u32_e32 v231, 0, v2
	s_mov_b64 s[12:13], 0x2000
	s_mov_b64 s[14:15], 0x1000
	s_movk_i32 s85, 0x1000
	s_mov_b32 s86, 0x21800000
	s_mov_b64 s[16:17], 0x10000
	s_mov_b64 s[18:19], 0x10200
	s_mov_b64 s[34:35], 0x1800000
	s_lshl_b32 s87, s26, 2
	s_mov_b64 s[36:37], 0x20000
	s_mov_b32 s88, 0x20000
	s_mov_b64 s[38:39], 0x20200
	s_mov_b64 s[40:41], 0x30000
	s_mov_b64 s[42:43], 0x30200
	s_mov_b64 s[44:45], 0x80000
	s_mov_b64 s[46:47], 0x80200
	s_mov_b64 s[48:49], 0x90000
	s_mov_b64 s[50:51], 0x90200
	s_mov_b64 s[52:53], 0xa0000
	s_mov_b64 s[54:55], 0xa0200
	s_mov_b64 s[56:57], 0xb0000
	s_mov_b64 s[58:59], 0xb0200
	v_mov_b32_e32 v232, 0x21800000
	s_mov_b64 s[64:65], s[70:71]
	s_mov_b64 s[62:63], s[68:69]
	s_barrier
	s_branch .LBB0_816

.LBB0_818:
	s_add_u32 s5, s70, 0x100
	s_addc_u32 s61, s71, 0
	s_add_u32 s68, s68, 0x40080
	v_mov_b32_e32 v0, 0
	s_addc_u32 s69, s69, 0
	s_mov_b32 s91, -2
	s_waitcnt lgkmcnt(0)
	ds_read_b128 v[104:107], v229
	ds_read_b128 v[108:111], v229 offset:1024
	ds_read_b128 v[128:131], v229 offset:2048
	ds_read_b128 v[132:135], v229 offset:3072
	ds_read_b128 v[144:147], v230
	ds_read_b128 v[148:151], v230 offset:1024
	ds_read_b128 v[152:155], v230 offset:2048
	ds_read_b128 v[156:159], v230 offset:3072
	s_add_u32 s26, s68, 0xfffc0080
	s_addc_u32 s27, s69, -1
	s_cmp_eq_u32 s91, 12
	s_cselect_b32 s73, s63, s27
	s_cselect_b32 s72, s62, s26
	s_cselect_b32 s71, s65, s61
	s_cselect_b32 s70, s64, s5
	s_add_i32 m0, s28, 0xc000
	ds_read_b128 v[160:163], v231
	ds_read_b128 v[164:167], v231 offset:1024
	ds_read_b128 v[168:171], v231 offset:2048
	ds_read_b128 v[172:175], v231 offset:3072
	ds_read_b128 v[176:179], v231 offset:4096
	ds_read_b128 v[180:183], v231 offset:5120
	ds_read_b128 v[184:187], v231 offset:6144
	ds_read_b128 v[188:191], v231 offset:7168
	global_load_lds_dwordx4 v202, s[68:69]
	s_add_i32 m0, s28, 0xe000
	s_nop 0
	global_load_lds_dwordx4 v200, s[68:69]
	s_waitcnt vmcnt(8)
	s_waitcnt lgkmcnt(0)
	s_barrier
	s_waitcnt lgkmcnt(0)
	v_mfma_f32_16x16x32_bf16 v[140:143], v[104:107], v[160:163], 0
	v_mfma_f32_16x16x32_bf16 v[136:139], v[128:131], v[160:163], 0
	v_mfma_f32_16x16x32_bf16 v[116:119], v[104:107], v[168:171], 0
	v_mfma_f32_16x16x32_bf16 v[112:115], v[128:131], v[168:171], 0
	v_mfma_f32_16x16x32_bf16 v[92:95], v[104:107], v[176:179], 0
	v_mfma_f32_16x16x32_bf16 v[88:91], v[128:131], v[176:179], 0
	v_mfma_f32_16x16x32_bf16 v[76:79], v[104:107], v[184:187], 0
	v_mfma_f32_16x16x32_bf16 v[72:75], v[128:131], v[184:187], 0
	v_mfma_f32_16x16x32_bf16 v[140:143], v[108:111], v[164:167], v[140:143]
	v_mfma_f32_16x16x32_bf16 v[136:139], v[132:135], v[164:167], v[136:139]
	v_mfma_f32_16x16x32_bf16 v[116:119], v[108:111], v[172:175], v[116:119]
	v_mfma_f32_16x16x32_bf16 v[112:115], v[132:135], v[172:175], v[112:115]
	v_mfma_f32_16x16x32_bf16 v[92:95], v[108:111], v[180:183], v[92:95]
	v_mfma_f32_16x16x32_bf16 v[88:91], v[132:135], v[180:183], v[88:91]
	v_mfma_f32_16x16x32_bf16 v[76:79], v[108:111], v[188:191], v[76:79]
	v_mfma_f32_16x16x32_bf16 v[72:75], v[132:135], v[188:191], v[72:75]
	v_mfma_f32_16x16x32_bf16 v[124:127], v[144:147], v[160:163], 0
	v_mfma_f32_16x16x32_bf16 v[120:123], v[152:155], v[160:163], 0
	v_mfma_f32_16x16x32_bf16 v[100:103], v[144:147], v[168:171], 0
	v_mfma_f32_16x16x32_bf16 v[96:99], v[152:155], v[168:171], 0
	v_mfma_f32_16x16x32_bf16 v[84:87], v[144:147], v[176:179], 0
	v_mfma_f32_16x16x32_bf16 v[80:83], v[152:155], v[176:179], 0
	v_mfma_f32_16x16x32_bf16 v[68:71], v[144:147], v[184:187], 0
	v_mfma_f32_16x16x32_bf16 v[64:67], v[152:155], v[184:187], 0
	v_mfma_f32_16x16x32_bf16 v[124:127], v[148:151], v[164:167], v[124:127]
	v_mfma_f32_16x16x32_bf16 v[120:123], v[156:159], v[164:167], v[120:123]
	v_mfma_f32_16x16x32_bf16 v[100:103], v[148:151], v[172:175], v[100:103]
	v_mfma_f32_16x16x32_bf16 v[96:99], v[156:159], v[172:175], v[96:99]
	v_mfma_f32_16x16x32_bf16 v[84:87], v[148:151], v[180:183], v[84:87]
	v_mfma_f32_16x16x32_bf16 v[80:83], v[156:159], v[180:183], v[80:83]
	v_mfma_f32_16x16x32_bf16 v[68:71], v[148:151], v[188:191], v[68:71]
	v_mfma_f32_16x16x32_bf16 v[64:67], v[156:159], v[188:191], v[64:67]
	s_barrier
	s_add_i32 s26, s83, s3
	v_lshl_add_u64 v[204:205], s[70:71], 0, v[194:195]
	s_mov_b32 m0, s26
	ds_read_b128 v[160:163], v231 offset:16384
	ds_read_b128 v[164:167], v231 offset:17408
	ds_read_b128 v[168:171], v231 offset:18432
	ds_read_b128 v[172:175], v231 offset:19456
	ds_read_b128 v[176:179], v231 offset:20480
	ds_read_b128 v[180:183], v231 offset:21504
	ds_read_b128 v[184:187], v231 offset:22528
	ds_read_b128 v[188:191], v231 offset:23552
	global_load_lds_dwordx4 v[204:205], off
	s_add_i32 m0, s26, 0x2000
	s_add_u32 s26, s70, 0x40000
	v_lshl_add_u64 v[206:207], s[70:71], 0, v[198:199]
	s_addc_u32 s27, s71, 0
	s_add_i32 s77, s84, s3
	global_load_lds_dwordx4 v[206:207], off
	s_mov_b32 m0, s77
	v_lshl_add_u64 v[210:211], s[72:73], 0, v[196:197]
	global_load_lds_dwordx4 v194, s[26:27]
	s_add_i32 m0, s77, 0x2000
	s_nop 0
	global_load_lds_dwordx4 v198, s[26:27]
	v_lshl_add_u64 v[208:209], s[72:73], 0, v[192:193]
	s_mov_b32 m0, s28
	s_nop 0
	global_load_lds_dwordx4 v[208:209], off
	s_mov_b32 m0, s29
	s_nop 0
	global_load_lds_dwordx4 v[210:211], off
	s_waitcnt vmcnt(8)
	s_waitcnt lgkmcnt(0)
	s_barrier
	s_waitcnt lgkmcnt(0)
	v_mfma_f32_16x16x32_bf16 v[60:63], v[104:107], v[160:163], 0
	v_mfma_f32_16x16x32_bf16 v[56:59], v[128:131], v[160:163], 0
	v_mfma_f32_16x16x32_bf16 v[44:47], v[104:107], v[168:171], 0
	v_mfma_f32_16x16x32_bf16 v[40:43], v[128:131], v[168:171], 0
	v_mfma_f32_16x16x32_bf16 v[28:31], v[104:107], v[176:179], 0
	v_mfma_f32_16x16x32_bf16 v[24:27], v[128:131], v[176:179], 0
	v_mfma_f32_16x16x32_bf16 v[12:15], v[104:107], v[184:187], 0
	v_mfma_f32_16x16x32_bf16 v[8:11], v[128:131], v[184:187], 0
	v_mfma_f32_16x16x32_bf16 v[60:63], v[108:111], v[164:167], v[60:63]
	v_mfma_f32_16x16x32_bf16 v[56:59], v[132:135], v[164:167], v[56:59]
	v_mfma_f32_16x16x32_bf16 v[44:47], v[108:111], v[172:175], v[44:47]
	v_mfma_f32_16x16x32_bf16 v[40:43], v[132:135], v[172:175], v[40:43]
	v_mfma_f32_16x16x32_bf16 v[28:31], v[108:111], v[180:183], v[28:31]
	v_mfma_f32_16x16x32_bf16 v[24:27], v[132:135], v[180:183], v[24:27]
	v_mfma_f32_16x16x32_bf16 v[12:15], v[108:111], v[188:191], v[12:15]
	v_mfma_f32_16x16x32_bf16 v[8:11], v[132:135], v[188:191], v[8:11]
	v_mfma_f32_16x16x32_bf16 v[52:55], v[144:147], v[160:163], 0
	v_mfma_f32_16x16x32_bf16 v[48:51], v[152:155], v[160:163], 0
	v_mfma_f32_16x16x32_bf16 v[36:39], v[144:147], v[168:171], 0
	v_mfma_f32_16x16x32_bf16 v[32:35], v[152:155], v[168:171], 0
	v_mfma_f32_16x16x32_bf16 v[20:23], v[144:147], v[176:179], 0
	v_mfma_f32_16x16x32_bf16 v[16:19], v[152:155], v[176:179], 0
	v_mfma_f32_16x16x32_bf16 v[4:7], v[144:147], v[184:187], 0
	v_mfma_f32_16x16x32_bf16 v[0:3], v[152:155], v[184:187], 0
	v_mfma_f32_16x16x32_bf16 v[52:55], v[148:151], v[164:167], v[52:55]
	v_mfma_f32_16x16x32_bf16 v[48:51], v[156:159], v[164:167], v[48:51]
	v_mfma_f32_16x16x32_bf16 v[36:39], v[148:151], v[172:175], v[36:39]
	v_mfma_f32_16x16x32_bf16 v[32:35], v[156:159], v[172:175], v[32:35]
	v_mfma_f32_16x16x32_bf16 v[20:23], v[148:151], v[180:183], v[20:23]
	v_mfma_f32_16x16x32_bf16 v[16:19], v[156:159], v[180:183], v[16:19]
	v_mfma_f32_16x16x32_bf16 v[4:7], v[148:151], v[188:191], v[4:7]
	v_mfma_f32_16x16x32_bf16 v[0:3], v[156:159], v[188:191], v[0:3]
	s_barrier
	s_add_i32 s77, 0, 0x18000
	s_add_i32 s92, 0, 0x1c000
	v_add_u32_e32 v132, s77, v228
	v_add_u32_e32 v156, s92, v228
	ds_read_b128 v[104:107], v132
	ds_read_b128 v[108:111], v132 offset:1024
	ds_read_b128 v[128:131], v132 offset:2048
	ds_read_b128 v[132:135], v132 offset:3072
	ds_read_b128 v[144:147], v156
	ds_read_b128 v[148:151], v156 offset:1024
	ds_read_b128 v[152:155], v156 offset:2048
	ds_read_b128 v[156:159], v156 offset:3072
	s_add_u32 s26, s72, 0x40000
	s_addc_u32 s27, s73, 0
	s_mov_b32 m0, s30
	ds_read_b128 v[160:163], v231 offset:32768
	ds_read_b128 v[164:167], v231 offset:33792
	ds_read_b128 v[168:171], v231 offset:34816
	ds_read_b128 v[172:175], v231 offset:35840
	ds_read_b128 v[176:179], v231 offset:36864
	ds_read_b128 v[180:183], v231 offset:37888
	ds_read_b128 v[184:187], v231 offset:38912
	ds_read_b128 v[188:191], v231 offset:39936
	global_load_lds_dwordx4 v192, s[26:27]
	s_mov_b32 m0, s31
	s_nop 0
	global_load_lds_dwordx4 v196, s[26:27]
	s_waitcnt vmcnt(8)
	s_waitcnt lgkmcnt(0)
	s_barrier
	s_waitcnt lgkmcnt(0)
	v_mfma_f32_16x16x32_bf16 v[140:143], v[104:107], v[160:163], v[140:143]
	v_mfma_f32_16x16x32_bf16 v[136:139], v[128:131], v[160:163], v[136:139]
	v_mfma_f32_16x16x32_bf16 v[116:119], v[104:107], v[168:171], v[116:119]
	v_mfma_f32_16x16x32_bf16 v[112:115], v[128:131], v[168:171], v[112:115]
	v_mfma_f32_16x16x32_bf16 v[92:95], v[104:107], v[176:179], v[92:95]
	v_mfma_f32_16x16x32_bf16 v[88:91], v[128:131], v[176:179], v[88:91]
	v_mfma_f32_16x16x32_bf16 v[76:79], v[104:107], v[184:187], v[76:79]
	v_mfma_f32_16x16x32_bf16 v[72:75], v[128:131], v[184:187], v[72:75]
	v_mfma_f32_16x16x32_bf16 v[140:143], v[108:111], v[164:167], v[140:143]
	v_mfma_f32_16x16x32_bf16 v[136:139], v[132:135], v[164:167], v[136:139]
	v_mfma_f32_16x16x32_bf16 v[116:119], v[108:111], v[172:175], v[116:119]
	v_mfma_f32_16x16x32_bf16 v[112:115], v[132:135], v[172:175], v[112:115]
	v_mfma_f32_16x16x32_bf16 v[92:95], v[108:111], v[180:183], v[92:95]
	v_mfma_f32_16x16x32_bf16 v[88:91], v[132:135], v[180:183], v[88:91]
	v_mfma_f32_16x16x32_bf16 v[76:79], v[108:111], v[188:191], v[76:79]
	v_mfma_f32_16x16x32_bf16 v[72:75], v[132:135], v[188:191], v[72:75]
	v_mfma_f32_16x16x32_bf16 v[124:127], v[144:147], v[160:163], v[124:127]
	v_mfma_f32_16x16x32_bf16 v[120:123], v[152:155], v[160:163], v[120:123]
	v_mfma_f32_16x16x32_bf16 v[100:103], v[144:147], v[168:171], v[100:103]
	v_mfma_f32_16x16x32_bf16 v[96:99], v[152:155], v[168:171], v[96:99]
	v_mfma_f32_16x16x32_bf16 v[84:87], v[144:147], v[176:179], v[84:87]
	v_mfma_f32_16x16x32_bf16 v[80:83], v[152:155], v[176:179], v[80:83]
	v_mfma_f32_16x16x32_bf16 v[68:71], v[144:147], v[184:187], v[68:71]
	v_mfma_f32_16x16x32_bf16 v[64:67], v[152:155], v[184:187], v[64:67]
	v_mfma_f32_16x16x32_bf16 v[124:127], v[148:151], v[164:167], v[124:127]
	v_mfma_f32_16x16x32_bf16 v[120:123], v[156:159], v[164:167], v[120:123]
	v_mfma_f32_16x16x32_bf16 v[100:103], v[148:151], v[172:175], v[100:103]
	v_mfma_f32_16x16x32_bf16 v[96:99], v[156:159], v[172:175], v[96:99]
	v_mfma_f32_16x16x32_bf16 v[84:87], v[148:151], v[180:183], v[84:87]
	v_mfma_f32_16x16x32_bf16 v[80:83], v[156:159], v[180:183], v[80:83]
	v_mfma_f32_16x16x32_bf16 v[68:71], v[148:151], v[188:191], v[68:71]
	v_mfma_f32_16x16x32_bf16 v[64:67], v[156:159], v[188:191], v[64:67]
	s_barrier
	s_add_i32 s26, s77, s3
	v_lshl_add_u64 v[204:205], v[204:205], 0, s[10:11]
	s_mov_b32 m0, s26
	ds_read_b128 v[160:163], v231 offset:49152
	ds_read_b128 v[164:167], v231 offset:50176
	ds_read_b128 v[168:171], v231 offset:51200
	ds_read_b128 v[172:175], v231 offset:52224
	ds_read_b128 v[176:179], v231 offset:53248
	ds_read_b128 v[180:183], v231 offset:54272
	ds_read_b128 v[184:187], v231 offset:55296
	ds_read_b128 v[188:191], v231 offset:56320
	global_load_lds_dwordx4 v[204:205], off
	s_add_i32 m0, s26, 0x2000
	s_add_u32 s26, s70, 0x40080
	v_lshl_add_u64 v[204:205], v[206:207], 0, s[10:11]
	s_addc_u32 s27, s71, 0
	s_add_i32 s70, s92, s3
	global_load_lds_dwordx4 v[204:205], off
	s_mov_b32 m0, s70
	s_nop 0
	global_load_lds_dwordx4 v194, s[26:27]
	s_add_i32 m0, s70, 0x2000
	s_nop 0
	global_load_lds_dwordx4 v198, s[26:27]
	v_lshl_add_u64 v[204:205], v[208:209], 0, s[10:11]
	s_mov_b32 m0, s81
	s_nop 0
	global_load_lds_dwordx4 v[204:205], off
	v_lshl_add_u64 v[204:205], v[210:211], 0, s[10:11]
	s_mov_b32 m0, s82
	s_nop 0
	global_load_lds_dwordx4 v[204:205], off
	s_waitcnt vmcnt(8)
	s_waitcnt lgkmcnt(0)
	s_barrier
	s_waitcnt lgkmcnt(0)
	v_mfma_f32_16x16x32_bf16 v[60:63], v[104:107], v[160:163], v[60:63]
	v_mfma_f32_16x16x32_bf16 v[56:59], v[128:131], v[160:163], v[56:59]
	v_mfma_f32_16x16x32_bf16 v[44:47], v[104:107], v[168:171], v[44:47]
	v_mfma_f32_16x16x32_bf16 v[40:43], v[128:131], v[168:171], v[40:43]
	v_mfma_f32_16x16x32_bf16 v[28:31], v[104:107], v[176:179], v[28:31]
	v_mfma_f32_16x16x32_bf16 v[24:27], v[128:131], v[176:179], v[24:27]
	v_mfma_f32_16x16x32_bf16 v[12:15], v[104:107], v[184:187], v[12:15]
	v_mfma_f32_16x16x32_bf16 v[8:11], v[128:131], v[184:187], v[8:11]
	v_mfma_f32_16x16x32_bf16 v[60:63], v[108:111], v[164:167], v[60:63]
	v_mfma_f32_16x16x32_bf16 v[56:59], v[132:135], v[164:167], v[56:59]
	v_mfma_f32_16x16x32_bf16 v[44:47], v[108:111], v[172:175], v[44:47]
	v_mfma_f32_16x16x32_bf16 v[40:43], v[132:135], v[172:175], v[40:43]
	v_mfma_f32_16x16x32_bf16 v[28:31], v[108:111], v[180:183], v[28:31]
	v_mfma_f32_16x16x32_bf16 v[24:27], v[132:135], v[180:183], v[24:27]
	v_mfma_f32_16x16x32_bf16 v[12:15], v[108:111], v[188:191], v[12:15]
	v_mfma_f32_16x16x32_bf16 v[8:11], v[132:135], v[188:191], v[8:11]
	v_mfma_f32_16x16x32_bf16 v[52:55], v[144:147], v[160:163], v[52:55]
	v_mfma_f32_16x16x32_bf16 v[48:51], v[152:155], v[160:163], v[48:51]
	v_mfma_f32_16x16x32_bf16 v[36:39], v[144:147], v[168:171], v[36:39]
	v_mfma_f32_16x16x32_bf16 v[32:35], v[152:155], v[168:171], v[32:35]
	v_mfma_f32_16x16x32_bf16 v[20:23], v[144:147], v[176:179], v[20:23]
	v_mfma_f32_16x16x32_bf16 v[16:19], v[152:155], v[176:179], v[16:19]
	v_mfma_f32_16x16x32_bf16 v[4:7], v[144:147], v[184:187], v[4:7]
	v_mfma_f32_16x16x32_bf16 v[0:3], v[152:155], v[184:187], v[0:3]
	v_mfma_f32_16x16x32_bf16 v[52:55], v[148:151], v[164:167], v[52:55]
	v_mfma_f32_16x16x32_bf16 v[48:51], v[156:159], v[164:167], v[48:51]
	v_mfma_f32_16x16x32_bf16 v[36:39], v[148:151], v[172:175], v[36:39]
	v_mfma_f32_16x16x32_bf16 v[32:35], v[156:159], v[172:175], v[32:35]
	v_mfma_f32_16x16x32_bf16 v[20:23], v[148:151], v[180:183], v[20:23]
	v_mfma_f32_16x16x32_bf16 v[16:19], v[156:159], v[180:183], v[16:19]
	v_mfma_f32_16x16x32_bf16 v[4:7], v[148:151], v[188:191], v[4:7]
	v_mfma_f32_16x16x32_bf16 v[0:3], v[156:159], v[188:191], v[0:3]
	s_barrier
	s_add_i32 s91, s91, 2
	s_add_u32 s5, s5, 0x100
	s_addc_u32 s61, s61, 0
	s_add_u32 s68, s68, 0x100
	s_addc_u32 s69, s69, 0
.LBB0_819:
	ds_read_b128 v[104:107], v229
	ds_read_b128 v[108:111], v229 offset:1024
	ds_read_b128 v[128:131], v229 offset:2048
	ds_read_b128 v[132:135], v229 offset:3072
	ds_read_b128 v[144:147], v230
	ds_read_b128 v[148:151], v230 offset:1024
	ds_read_b128 v[152:155], v230 offset:2048
	ds_read_b128 v[156:159], v230 offset:3072
	s_add_u32 s26, s68, 0xfffc0080
	s_addc_u32 s27, s69, -1
	s_cmp_eq_u32 s91, 12
	s_cselect_b32 s73, s63, s27
	s_cselect_b32 s72, s62, s26
	s_cselect_b32 s71, s65, s61
	s_cselect_b32 s70, s64, s5
	s_add_i32 m0, s28, 0xc000
	ds_read_b128 v[160:163], v231
	ds_read_b128 v[164:167], v231 offset:1024
	ds_read_b128 v[168:171], v231 offset:2048
	ds_read_b128 v[172:175], v231 offset:3072
	ds_read_b128 v[176:179], v231 offset:4096
	ds_read_b128 v[180:183], v231 offset:5120
	ds_read_b128 v[184:187], v231 offset:6144
	ds_read_b128 v[188:191], v231 offset:7168
	global_load_lds_dwordx4 v202, s[68:69]
	s_add_i32 m0, s28, 0xe000
	s_nop 0
	global_load_lds_dwordx4 v200, s[68:69]
	s_waitcnt vmcnt(8)
	s_waitcnt lgkmcnt(0)
	s_barrier
	s_waitcnt lgkmcnt(0)
	v_mfma_f32_16x16x32_bf16 v[140:143], v[104:107], v[160:163], v[140:143]
	v_mfma_f32_16x16x32_bf16 v[136:139], v[128:131], v[160:163], v[136:139]
	v_mfma_f32_16x16x32_bf16 v[116:119], v[104:107], v[168:171], v[116:119]
	v_mfma_f32_16x16x32_bf16 v[112:115], v[128:131], v[168:171], v[112:115]
	v_mfma_f32_16x16x32_bf16 v[92:95], v[104:107], v[176:179], v[92:95]
	v_mfma_f32_16x16x32_bf16 v[88:91], v[128:131], v[176:179], v[88:91]
	v_mfma_f32_16x16x32_bf16 v[76:79], v[104:107], v[184:187], v[76:79]
	v_mfma_f32_16x16x32_bf16 v[72:75], v[128:131], v[184:187], v[72:75]
	v_mfma_f32_16x16x32_bf16 v[140:143], v[108:111], v[164:167], v[140:143]
	v_mfma_f32_16x16x32_bf16 v[136:139], v[132:135], v[164:167], v[136:139]
	v_mfma_f32_16x16x32_bf16 v[116:119], v[108:111], v[172:175], v[116:119]
	v_mfma_f32_16x16x32_bf16 v[112:115], v[132:135], v[172:175], v[112:115]
	v_mfma_f32_16x16x32_bf16 v[92:95], v[108:111], v[180:183], v[92:95]
	v_mfma_f32_16x16x32_bf16 v[88:91], v[132:135], v[180:183], v[88:91]
	v_mfma_f32_16x16x32_bf16 v[76:79], v[108:111], v[188:191], v[76:79]
	v_mfma_f32_16x16x32_bf16 v[72:75], v[132:135], v[188:191], v[72:75]
	v_mfma_f32_16x16x32_bf16 v[124:127], v[144:147], v[160:163], v[124:127]
	v_mfma_f32_16x16x32_bf16 v[120:123], v[152:155], v[160:163], v[120:123]
	v_mfma_f32_16x16x32_bf16 v[100:103], v[144:147], v[168:171], v[100:103]
	v_mfma_f32_16x16x32_bf16 v[96:99], v[152:155], v[168:171], v[96:99]
	v_mfma_f32_16x16x32_bf16 v[84:87], v[144:147], v[176:179], v[84:87]
	v_mfma_f32_16x16x32_bf16 v[80:83], v[152:155], v[176:179], v[80:83]
	v_mfma_f32_16x16x32_bf16 v[68:71], v[144:147], v[184:187], v[68:71]
	v_mfma_f32_16x16x32_bf16 v[64:67], v[152:155], v[184:187], v[64:67]
	v_mfma_f32_16x16x32_bf16 v[124:127], v[148:151], v[164:167], v[124:127]
	v_mfma_f32_16x16x32_bf16 v[120:123], v[156:159], v[164:167], v[120:123]
	v_mfma_f32_16x16x32_bf16 v[100:103], v[148:151], v[172:175], v[100:103]
	v_mfma_f32_16x16x32_bf16 v[96:99], v[156:159], v[172:175], v[96:99]
	v_mfma_f32_16x16x32_bf16 v[84:87], v[148:151], v[180:183], v[84:87]
	v_mfma_f32_16x16x32_bf16 v[80:83], v[156:159], v[180:183], v[80:83]
	v_mfma_f32_16x16x32_bf16 v[68:71], v[148:151], v[188:191], v[68:71]
	v_mfma_f32_16x16x32_bf16 v[64:67], v[156:159], v[188:191], v[64:67]
	s_barrier
	s_add_i32 s26, s83, s3
	v_lshl_add_u64 v[204:205], s[70:71], 0, v[194:195]
	s_mov_b32 m0, s26
	ds_read_b128 v[160:163], v231 offset:16384
	ds_read_b128 v[164:167], v231 offset:17408
	ds_read_b128 v[168:171], v231 offset:18432
	ds_read_b128 v[172:175], v231 offset:19456
	ds_read_b128 v[176:179], v231 offset:20480
	ds_read_b128 v[180:183], v231 offset:21504
	ds_read_b128 v[184:187], v231 offset:22528
	ds_read_b128 v[188:191], v231 offset:23552
	global_load_lds_dwordx4 v[204:205], off
	s_add_i32 m0, s26, 0x2000
	s_add_u32 s26, s70, 0x40000
	v_lshl_add_u64 v[206:207], s[70:71], 0, v[198:199]
	s_addc_u32 s27, s71, 0
	s_add_i32 s77, s84, s3
	global_load_lds_dwordx4 v[206:207], off
	s_mov_b32 m0, s77
	v_lshl_add_u64 v[210:211], s[72:73], 0, v[196:197]
	global_load_lds_dwordx4 v194, s[26:27]
	s_add_i32 m0, s77, 0x2000
	s_nop 0
	global_load_lds_dwordx4 v198, s[26:27]
	v_lshl_add_u64 v[208:209], s[72:73], 0, v[192:193]
	s_mov_b32 m0, s28
	s_nop 0
	global_load_lds_dwordx4 v[208:209], off
	s_mov_b32 m0, s29
	s_nop 0
	global_load_lds_dwordx4 v[210:211], off
	s_waitcnt vmcnt(8)
	s_waitcnt lgkmcnt(0)
	s_barrier
	s_waitcnt lgkmcnt(0)
	v_mfma_f32_16x16x32_bf16 v[60:63], v[104:107], v[160:163], v[60:63]
	v_mfma_f32_16x16x32_bf16 v[56:59], v[128:131], v[160:163], v[56:59]
	v_mfma_f32_16x16x32_bf16 v[44:47], v[104:107], v[168:171], v[44:47]
	v_mfma_f32_16x16x32_bf16 v[40:43], v[128:131], v[168:171], v[40:43]
	v_mfma_f32_16x16x32_bf16 v[28:31], v[104:107], v[176:179], v[28:31]
	v_mfma_f32_16x16x32_bf16 v[24:27], v[128:131], v[176:179], v[24:27]
	v_mfma_f32_16x16x32_bf16 v[12:15], v[104:107], v[184:187], v[12:15]
	v_mfma_f32_16x16x32_bf16 v[8:11], v[128:131], v[184:187], v[8:11]
	v_mfma_f32_16x16x32_bf16 v[60:63], v[108:111], v[164:167], v[60:63]
	v_mfma_f32_16x16x32_bf16 v[56:59], v[132:135], v[164:167], v[56:59]
	v_mfma_f32_16x16x32_bf16 v[44:47], v[108:111], v[172:175], v[44:47]
	v_mfma_f32_16x16x32_bf16 v[40:43], v[132:135], v[172:175], v[40:43]
	v_mfma_f32_16x16x32_bf16 v[28:31], v[108:111], v[180:183], v[28:31]
	v_mfma_f32_16x16x32_bf16 v[24:27], v[132:135], v[180:183], v[24:27]
	v_mfma_f32_16x16x32_bf16 v[12:15], v[108:111], v[188:191], v[12:15]
	v_mfma_f32_16x16x32_bf16 v[8:11], v[132:135], v[188:191], v[8:11]
	v_mfma_f32_16x16x32_bf16 v[52:55], v[144:147], v[160:163], v[52:55]
	v_mfma_f32_16x16x32_bf16 v[48:51], v[152:155], v[160:163], v[48:51]
	v_mfma_f32_16x16x32_bf16 v[36:39], v[144:147], v[168:171], v[36:39]
	v_mfma_f32_16x16x32_bf16 v[32:35], v[152:155], v[168:171], v[32:35]
	v_mfma_f32_16x16x32_bf16 v[20:23], v[144:147], v[176:179], v[20:23]
	v_mfma_f32_16x16x32_bf16 v[16:19], v[152:155], v[176:179], v[16:19]
	v_mfma_f32_16x16x32_bf16 v[4:7], v[144:147], v[184:187], v[4:7]
	v_mfma_f32_16x16x32_bf16 v[0:3], v[152:155], v[184:187], v[0:3]
	v_mfma_f32_16x16x32_bf16 v[52:55], v[148:151], v[164:167], v[52:55]
	v_mfma_f32_16x16x32_bf16 v[48:51], v[156:159], v[164:167], v[48:51]
	v_mfma_f32_16x16x32_bf16 v[36:39], v[148:151], v[172:175], v[36:39]
	v_mfma_f32_16x16x32_bf16 v[32:35], v[156:159], v[172:175], v[32:35]
	v_mfma_f32_16x16x32_bf16 v[20:23], v[148:151], v[180:183], v[20:23]
	v_mfma_f32_16x16x32_bf16 v[16:19], v[156:159], v[180:183], v[16:19]
	v_mfma_f32_16x16x32_bf16 v[4:7], v[148:151], v[188:191], v[4:7]
	v_mfma_f32_16x16x32_bf16 v[0:3], v[156:159], v[188:191], v[0:3]
	s_barrier
	s_add_i32 s77, 0, 0x18000
	s_add_i32 s92, 0, 0x1c000
	v_add_u32_e32 v132, s77, v228
	v_add_u32_e32 v156, s92, v228
	ds_read_b128 v[104:107], v132
	ds_read_b128 v[108:111], v132 offset:1024
	ds_read_b128 v[128:131], v132 offset:2048
	ds_read_b128 v[132:135], v132 offset:3072
	ds_read_b128 v[144:147], v156
	ds_read_b128 v[148:151], v156 offset:1024
	ds_read_b128 v[152:155], v156 offset:2048
	ds_read_b128 v[156:159], v156 offset:3072
	s_add_u32 s26, s72, 0x40000
	s_addc_u32 s27, s73, 0
	s_mov_b32 m0, s30
	ds_read_b128 v[160:163], v231 offset:32768
	ds_read_b128 v[164:167], v231 offset:33792
	ds_read_b128 v[168:171], v231 offset:34816
	ds_read_b128 v[172:175], v231 offset:35840
	ds_read_b128 v[176:179], v231 offset:36864
	ds_read_b128 v[180:183], v231 offset:37888
	ds_read_b128 v[184:187], v231 offset:38912
	ds_read_b128 v[188:191], v231 offset:39936
	global_load_lds_dwordx4 v192, s[26:27]
	s_mov_b32 m0, s31
	s_nop 0
	global_load_lds_dwordx4 v196, s[26:27]
	s_waitcnt vmcnt(8)
	s_waitcnt lgkmcnt(0)
	s_barrier
	s_waitcnt lgkmcnt(0)
	v_mfma_f32_16x16x32_bf16 v[140:143], v[104:107], v[160:163], v[140:143]
	v_mfma_f32_16x16x32_bf16 v[136:139], v[128:131], v[160:163], v[136:139]
	v_mfma_f32_16x16x32_bf16 v[116:119], v[104:107], v[168:171], v[116:119]
	v_mfma_f32_16x16x32_bf16 v[112:115], v[128:131], v[168:171], v[112:115]
	v_mfma_f32_16x16x32_bf16 v[92:95], v[104:107], v[176:179], v[92:95]
	v_mfma_f32_16x16x32_bf16 v[88:91], v[128:131], v[176:179], v[88:91]
	v_mfma_f32_16x16x32_bf16 v[76:79], v[104:107], v[184:187], v[76:79]
	v_mfma_f32_16x16x32_bf16 v[72:75], v[128:131], v[184:187], v[72:75]
	v_mfma_f32_16x16x32_bf16 v[140:143], v[108:111], v[164:167], v[140:143]
	v_mfma_f32_16x16x32_bf16 v[136:139], v[132:135], v[164:167], v[136:139]
	v_mfma_f32_16x16x32_bf16 v[116:119], v[108:111], v[172:175], v[116:119]
	v_mfma_f32_16x16x32_bf16 v[112:115], v[132:135], v[172:175], v[112:115]
	v_mfma_f32_16x16x32_bf16 v[92:95], v[108:111], v[180:183], v[92:95]
	v_mfma_f32_16x16x32_bf16 v[88:91], v[132:135], v[180:183], v[88:91]
	v_mfma_f32_16x16x32_bf16 v[76:79], v[108:111], v[188:191], v[76:79]
	v_mfma_f32_16x16x32_bf16 v[72:75], v[132:135], v[188:191], v[72:75]
	v_mfma_f32_16x16x32_bf16 v[124:127], v[144:147], v[160:163], v[124:127]
	v_mfma_f32_16x16x32_bf16 v[120:123], v[152:155], v[160:163], v[120:123]
	v_mfma_f32_16x16x32_bf16 v[100:103], v[144:147], v[168:171], v[100:103]
	v_mfma_f32_16x16x32_bf16 v[96:99], v[152:155], v[168:171], v[96:99]
	v_mfma_f32_16x16x32_bf16 v[84:87], v[144:147], v[176:179], v[84:87]
	v_mfma_f32_16x16x32_bf16 v[80:83], v[152:155], v[176:179], v[80:83]
	v_mfma_f32_16x16x32_bf16 v[68:71], v[144:147], v[184:187], v[68:71]
	v_mfma_f32_16x16x32_bf16 v[64:67], v[152:155], v[184:187], v[64:67]
	v_mfma_f32_16x16x32_bf16 v[124:127], v[148:151], v[164:167], v[124:127]
	v_mfma_f32_16x16x32_bf16 v[120:123], v[156:159], v[164:167], v[120:123]
	v_mfma_f32_16x16x32_bf16 v[100:103], v[148:151], v[172:175], v[100:103]
	v_mfma_f32_16x16x32_bf16 v[96:99], v[156:159], v[172:175], v[96:99]
	v_mfma_f32_16x16x32_bf16 v[84:87], v[148:151], v[180:183], v[84:87]
	v_mfma_f32_16x16x32_bf16 v[80:83], v[156:159], v[180:183], v[80:83]
	v_mfma_f32_16x16x32_bf16 v[68:71], v[148:151], v[188:191], v[68:71]
	v_mfma_f32_16x16x32_bf16 v[64:67], v[156:159], v[188:191], v[64:67]
	s_barrier
	s_add_i32 s26, s77, s3
	v_lshl_add_u64 v[204:205], v[204:205], 0, s[10:11]
	s_mov_b32 m0, s26
	ds_read_b128 v[160:163], v231 offset:49152
	ds_read_b128 v[164:167], v231 offset:50176
	ds_read_b128 v[168:171], v231 offset:51200
	ds_read_b128 v[172:175], v231 offset:52224
	ds_read_b128 v[176:179], v231 offset:53248
	ds_read_b128 v[180:183], v231 offset:54272
	ds_read_b128 v[184:187], v231 offset:55296
	ds_read_b128 v[188:191], v231 offset:56320
	global_load_lds_dwordx4 v[204:205], off
	s_add_i32 m0, s26, 0x2000
	s_add_u32 s26, s70, 0x40080
	v_lshl_add_u64 v[204:205], v[206:207], 0, s[10:11]
	s_addc_u32 s27, s71, 0
	s_add_i32 s70, s92, s3
	global_load_lds_dwordx4 v[204:205], off
	s_mov_b32 m0, s70
	s_nop 0
	global_load_lds_dwordx4 v194, s[26:27]
	s_add_i32 m0, s70, 0x2000
	s_nop 0
	global_load_lds_dwordx4 v198, s[26:27]
	v_lshl_add_u64 v[204:205], v[208:209], 0, s[10:11]
	s_mov_b32 m0, s81
	s_nop 0
	global_load_lds_dwordx4 v[204:205], off
	v_lshl_add_u64 v[204:205], v[210:211], 0, s[10:11]
	s_mov_b32 m0, s82
	s_nop 0
	global_load_lds_dwordx4 v[204:205], off
	s_waitcnt vmcnt(8)
	s_waitcnt lgkmcnt(0)
	s_barrier
	s_waitcnt lgkmcnt(0)
	v_mfma_f32_16x16x32_bf16 v[60:63], v[104:107], v[160:163], v[60:63]
	v_mfma_f32_16x16x32_bf16 v[56:59], v[128:131], v[160:163], v[56:59]
	v_mfma_f32_16x16x32_bf16 v[44:47], v[104:107], v[168:171], v[44:47]
	v_mfma_f32_16x16x32_bf16 v[40:43], v[128:131], v[168:171], v[40:43]
	v_mfma_f32_16x16x32_bf16 v[28:31], v[104:107], v[176:179], v[28:31]
	v_mfma_f32_16x16x32_bf16 v[24:27], v[128:131], v[176:179], v[24:27]
	v_mfma_f32_16x16x32_bf16 v[12:15], v[104:107], v[184:187], v[12:15]
	v_mfma_f32_16x16x32_bf16 v[8:11], v[128:131], v[184:187], v[8:11]
	v_mfma_f32_16x16x32_bf16 v[60:63], v[108:111], v[164:167], v[60:63]
	v_mfma_f32_16x16x32_bf16 v[56:59], v[132:135], v[164:167], v[56:59]
	v_mfma_f32_16x16x32_bf16 v[44:47], v[108:111], v[172:175], v[44:47]
	v_mfma_f32_16x16x32_bf16 v[40:43], v[132:135], v[172:175], v[40:43]
	v_mfma_f32_16x16x32_bf16 v[28:31], v[108:111], v[180:183], v[28:31]
	v_mfma_f32_16x16x32_bf16 v[24:27], v[132:135], v[180:183], v[24:27]
	v_mfma_f32_16x16x32_bf16 v[12:15], v[108:111], v[188:191], v[12:15]
	v_mfma_f32_16x16x32_bf16 v[8:11], v[132:135], v[188:191], v[8:11]
	v_mfma_f32_16x16x32_bf16 v[52:55], v[144:147], v[160:163], v[52:55]
	v_mfma_f32_16x16x32_bf16 v[48:51], v[152:155], v[160:163], v[48:51]
	v_mfma_f32_16x16x32_bf16 v[36:39], v[144:147], v[168:171], v[36:39]
	v_mfma_f32_16x16x32_bf16 v[32:35], v[152:155], v[168:171], v[32:35]
	v_mfma_f32_16x16x32_bf16 v[20:23], v[144:147], v[176:179], v[20:23]
	v_mfma_f32_16x16x32_bf16 v[16:19], v[152:155], v[176:179], v[16:19]
	v_mfma_f32_16x16x32_bf16 v[4:7], v[144:147], v[184:187], v[4:7]
	v_mfma_f32_16x16x32_bf16 v[0:3], v[152:155], v[184:187], v[0:3]
	v_mfma_f32_16x16x32_bf16 v[52:55], v[148:151], v[164:167], v[52:55]
	v_mfma_f32_16x16x32_bf16 v[48:51], v[156:159], v[164:167], v[48:51]
	v_mfma_f32_16x16x32_bf16 v[36:39], v[148:151], v[172:175], v[36:39]
	v_mfma_f32_16x16x32_bf16 v[32:35], v[156:159], v[172:175], v[32:35]
	v_mfma_f32_16x16x32_bf16 v[20:23], v[148:151], v[180:183], v[20:23]
	v_mfma_f32_16x16x32_bf16 v[16:19], v[156:159], v[180:183], v[16:19]
	v_mfma_f32_16x16x32_bf16 v[4:7], v[148:151], v[188:191], v[4:7]
	v_mfma_f32_16x16x32_bf16 v[0:3], v[156:159], v[188:191], v[0:3]
	s_barrier
	s_add_i32 s91, s91, 2
	s_add_u32 s5, s5, 0x100
	s_addc_u32 s61, s61, 0
	s_add_u32 s68, s68, 0x100
	s_addc_u32 s69, s69, 0
	s_cmp_gt_u32 s91, 13
	s_cbranch_scc0 .LBB0_819
	s_and_b64 vcc, exec, s[8:9]
	s_cbranch_vccz .LBB0_822
	s_barrier

.LBB0_947:
	s_lshl_b32 s7, s41, 2
	s_add_i32 s90, s7, 0
	s_lshl_b32 s7, s12, 2
	s_mov_b64 s[18:19], 0x80
	s_add_i32 s89, s7, 0
	v_lshl_add_u64 v[6:7], v[6:7], 0, s[18:19]
	s_add_i32 m0, s84, 0x18000
	s_add_i32 s88, s90, 0x20000
	s_add_i32 s89, s89, 0x20600
	s_add_i32 s90, s90, 0x20200
	s_waitcnt vmcnt(2)
	s_barrier
	global_load_lds_dwordx4 v[6:7], off
	v_lshl_add_u64 v[4:5], v[4:5], 0, s[18:19]
	s_add_i32 m0, s84, 0x1a000
	s_add_i32 s91, s84, 0x8000
	s_add_i32 s92, s84, 0xa000
	global_load_lds_dwordx4 v[4:5], off
	v_lshl_add_u64 v[2:3], v[2:3], 0, s[18:19]
	s_mov_b32 m0, s91
	s_add_u32 s26, s10, 0x40080
	global_load_lds_dwordx4 v[2:3], off
	v_lshl_add_u64 v[0:1], v[0:1], 0, s[18:19]
	s_mov_b32 m0, s92
	s_addc_u32 s27, s11, 0
	global_load_lds_dwordx4 v[0:1], off
	s_add_i32 m0, s84, 0x1c000
	v_ashrrev_i32_e32 v2, 6, v8
	global_load_lds_dwordx4 v148, s[26:27]
	s_add_i32 m0, s84, 0x1e000
	v_and_b32_e32 v4, 48, v8
	global_load_lds_dwordx4 v152, s[26:27]
	v_and_b32_e32 v0, 15, v8
	v_or_b32_e32 v1, s41, v0
	v_lshlrev_b32_e32 v3, 6, v1
	s_movk_i32 s7, 0x3c0
	v_lshlrev_b32_e32 v1, 2, v1
	v_and_or_b32 v3, v3, s7, v4
	v_lshl_add_u32 v5, v2, 10, s80
	v_and_b32_e32 v1, 32, v1
	v_bitop3_b32 v1, v3, v5, v1 bitop3:0xde
	v_lshlrev_b32_e32 v3, 2, v8
	v_lshl_or_b32 v0, v0, 6, v4
	v_add_lshl_u32 v2, v2, s79, 10
	v_and_b32_e32 v3, 32, v3
	v_bitop3_b32 v166, v0, v2, v3 bitop3:0xde
	v_lshlrev_b32_e32 v0, 14, v12
	v_and_b32_e32 v0, 0xffff8000, v0
	v_lshl_add_u32 v0, v13, 11, v0
	v_and_b32_e32 v2, 1, v12
	v_lshl_or_b32 v0, v2, 6, v0
	v_lshl_add_u32 v156, v14, 1, v0
	v_lshlrev_b32_e32 v0, 14, v9
	v_and_b32_e32 v0, 0xffff8000, v0
	s_waitcnt vmcnt(6)
	v_lshl_add_u32 v0, v10, 11, v0
	v_and_b32_e32 v2, 1, v9
	v_lshl_or_b32 v0, v2, 6, v0
	s_add_i32 s94, 0, 0x10000
	s_add_i32 s95, 0, 0x14000
	s_mov_b32 s93, 0
	v_mov_b32_e32 v157, v155
	v_lshl_add_u32 v158, v11, 1, v0
	v_mov_b32_e32 v159, v155
	v_add_u32_e32 v167, s94, v166
	v_add_u32_e32 v168, s95, v166
	v_add_u32_e32 v169, 0, v1
	v_mov_b32_e32 v170, 0x358637bd
	s_mov_b32 s96, 0x800000
	s_lshl_b32 s97, s12, 2
	s_mov_b64 s[34:35], 0x139100
	s_mov_b32 s28, 0x3e6d3388
	s_mov_b32 s36, 0x3f07dc22
	s_mov_b32 s38, 0x3f35f0e3
	s_mov_b32 s40, 0xbe11a98e
	s_mov_b32 s42, 0x3e027906
	s_mov_b64 s[44:45], 0x90
	s_mov_b64 s[46:47], 0xa0
	s_mov_b64 s[48:49], 0xb0
	v_mov_b32_e32 v0, 0xbf3a00e3
	s_mov_b64 s[56:57], s[10:11]
	s_mov_b64 s[52:53], s[8:9]
	s_barrier
	s_branch .LBB0_950

.LBB0_952:
	s_add_u32 s7, s10, 0x100
	s_addc_u32 s31, s11, 0
	s_add_u32 s8, s8, 0x40080
	v_mov_b32_e32 v2, 0
	s_addc_u32 s9, s9, 0
	s_mov_b32 s51, -2
	ds_read_b128 v[130:133], v167
	ds_read_b128 v[134:137], v167 offset:1024
	ds_read_b128 v[138:141], v167 offset:2048
	ds_read_b128 v[142:145], v167 offset:3072
	ds_read_b128 v[160:163], v168
	ds_read_b128 v[172:175], v168 offset:1024
	ds_read_b128 v[176:179], v168 offset:2048
	ds_read_b128 v[180:183], v168 offset:3072
	s_add_u32 s10, s8, 0xfffc0080
	s_addc_u32 s11, s9, -1
	s_cmp_eq_u32 s51, 12
	s_cselect_b32 s59, s53, s11
	s_cselect_b32 s58, s52, s10
	s_cselect_b32 s11, s57, s31
	s_cselect_b32 s10, s56, s7
	s_add_i32 m0, s84, 0xc000
	ds_read_b128 v[184:187], v169
	ds_read_b128 v[188:191], v169 offset:1024
	ds_read_b128 v[192:195], v169 offset:2048
	ds_read_b128 v[196:199], v169 offset:3072
	ds_read_b128 v[200:203], v169 offset:4096
	ds_read_b128 v[204:207], v169 offset:5120
	ds_read_b128 v[208:211], v169 offset:6144
	ds_read_b128 v[212:215], v169 offset:7168
	global_load_lds_dwordx4 v158, s[8:9]
	s_add_i32 m0, s84, 0xe000
	s_nop 0
	global_load_lds_dwordx4 v156, s[8:9]
	s_waitcnt vmcnt(8)
	s_waitcnt lgkmcnt(0)
	s_barrier
	s_waitcnt lgkmcnt(0)
	v_mfma_f32_16x16x32_bf16 v[126:129], v[130:133], v[184:187], 0
	v_mfma_f32_16x16x32_bf16 v[122:125], v[138:141], v[184:187], 0
	v_mfma_f32_16x16x32_bf16 v[110:113], v[130:133], v[192:195], 0
	v_mfma_f32_16x16x32_bf16 v[106:109], v[138:141], v[192:195], 0
	v_mfma_f32_16x16x32_bf16 v[94:97], v[130:133], v[200:203], 0
	v_mfma_f32_16x16x32_bf16 v[90:93], v[138:141], v[200:203], 0
	v_mfma_f32_16x16x32_bf16 v[78:81], v[130:133], v[208:211], 0
	v_mfma_f32_16x16x32_bf16 v[74:77], v[138:141], v[208:211], 0
	v_mfma_f32_16x16x32_bf16 v[126:129], v[134:137], v[188:191], v[126:129]
	v_mfma_f32_16x16x32_bf16 v[122:125], v[142:145], v[188:191], v[122:125]
	v_mfma_f32_16x16x32_bf16 v[110:113], v[134:137], v[196:199], v[110:113]
	v_mfma_f32_16x16x32_bf16 v[106:109], v[142:145], v[196:199], v[106:109]
	v_mfma_f32_16x16x32_bf16 v[94:97], v[134:137], v[204:207], v[94:97]
	v_mfma_f32_16x16x32_bf16 v[90:93], v[142:145], v[204:207], v[90:93]
	v_mfma_f32_16x16x32_bf16 v[78:81], v[134:137], v[212:215], v[78:81]
	v_mfma_f32_16x16x32_bf16 v[74:77], v[142:145], v[212:215], v[74:77]
	v_mfma_f32_16x16x32_bf16 v[118:121], v[160:163], v[184:187], 0
	v_mfma_f32_16x16x32_bf16 v[114:117], v[176:179], v[184:187], 0
	v_mfma_f32_16x16x32_bf16 v[102:105], v[160:163], v[192:195], 0
	v_mfma_f32_16x16x32_bf16 v[98:101], v[176:179], v[192:195], 0
	v_mfma_f32_16x16x32_bf16 v[86:89], v[160:163], v[200:203], 0
	v_mfma_f32_16x16x32_bf16 v[82:85], v[176:179], v[200:203], 0
	v_mfma_f32_16x16x32_bf16 v[70:73], v[160:163], v[208:211], 0
	v_mfma_f32_16x16x32_bf16 v[66:69], v[176:179], v[208:211], 0
	v_mfma_f32_16x16x32_bf16 v[118:121], v[172:175], v[188:191], v[118:121]
	v_mfma_f32_16x16x32_bf16 v[114:117], v[180:183], v[188:191], v[114:117]
	v_mfma_f32_16x16x32_bf16 v[102:105], v[172:175], v[196:199], v[102:105]
	v_mfma_f32_16x16x32_bf16 v[98:101], v[180:183], v[196:199], v[98:101]
	v_mfma_f32_16x16x32_bf16 v[86:89], v[172:175], v[204:207], v[86:89]
	v_mfma_f32_16x16x32_bf16 v[82:85], v[180:183], v[204:207], v[82:85]
	v_mfma_f32_16x16x32_bf16 v[70:73], v[172:175], v[212:215], v[70:73]
	v_mfma_f32_16x16x32_bf16 v[66:69], v[180:183], v[212:215], v[66:69]
	s_barrier
	s_add_i32 s26, s94, s39
	v_lshl_add_u64 v[164:165], s[10:11], 0, v[148:149]
	s_mov_b32 m0, s26
	ds_read_b128 v[184:187], v169 offset:16384
	ds_read_b128 v[188:191], v169 offset:17408
	ds_read_b128 v[192:195], v169 offset:18432
	ds_read_b128 v[196:199], v169 offset:19456
	ds_read_b128 v[200:203], v169 offset:20480
	ds_read_b128 v[204:207], v169 offset:21504
	ds_read_b128 v[208:211], v169 offset:22528
	ds_read_b128 v[212:215], v169 offset:23552
	global_load_lds_dwordx4 v[164:165], off
	s_add_i32 m0, s26, 0x2000
	s_add_u32 s26, s10, 0x40000
	v_lshl_add_u64 v[216:217], s[10:11], 0, v[152:153]
	s_addc_u32 s27, s11, 0
	s_add_i32 s60, s95, s39
	global_load_lds_dwordx4 v[216:217], off
	s_mov_b32 m0, s60
	v_lshl_add_u64 v[220:221], s[58:59], 0, v[150:151]
	global_load_lds_dwordx4 v148, s[26:27]
	s_add_i32 m0, s60, 0x2000
	s_nop 0
	global_load_lds_dwordx4 v152, s[26:27]
	v_lshl_add_u64 v[218:219], s[58:59], 0, v[146:147]
	s_mov_b32 m0, s84
	s_nop 0
	global_load_lds_dwordx4 v[218:219], off
	s_mov_b32 m0, s85
	s_nop 0
	global_load_lds_dwordx4 v[220:221], off
	s_waitcnt vmcnt(8)
	s_waitcnt lgkmcnt(0)
	s_barrier
	s_waitcnt lgkmcnt(0)
	v_mfma_f32_16x16x32_bf16 v[62:65], v[130:133], v[184:187], 0
	v_mfma_f32_16x16x32_bf16 v[58:61], v[138:141], v[184:187], 0
	v_mfma_f32_16x16x32_bf16 v[46:49], v[130:133], v[192:195], 0
	v_mfma_f32_16x16x32_bf16 v[42:45], v[138:141], v[192:195], 0
	v_mfma_f32_16x16x32_bf16 v[30:33], v[130:133], v[200:203], 0
	v_mfma_f32_16x16x32_bf16 v[26:29], v[138:141], v[200:203], 0
	v_mfma_f32_16x16x32_bf16 v[14:17], v[130:133], v[208:211], 0
	v_mfma_f32_16x16x32_bf16 v[10:13], v[138:141], v[208:211], 0
	v_mfma_f32_16x16x32_bf16 v[62:65], v[134:137], v[188:191], v[62:65]
	v_mfma_f32_16x16x32_bf16 v[58:61], v[142:145], v[188:191], v[58:61]
	v_mfma_f32_16x16x32_bf16 v[46:49], v[134:137], v[196:199], v[46:49]
	v_mfma_f32_16x16x32_bf16 v[42:45], v[142:145], v[196:199], v[42:45]
	v_mfma_f32_16x16x32_bf16 v[30:33], v[134:137], v[204:207], v[30:33]
	v_mfma_f32_16x16x32_bf16 v[26:29], v[142:145], v[204:207], v[26:29]
	v_mfma_f32_16x16x32_bf16 v[14:17], v[134:137], v[212:215], v[14:17]
	v_mfma_f32_16x16x32_bf16 v[10:13], v[142:145], v[212:215], v[10:13]
	v_mfma_f32_16x16x32_bf16 v[54:57], v[160:163], v[184:187], 0
	v_mfma_f32_16x16x32_bf16 v[50:53], v[176:179], v[184:187], 0
	v_mfma_f32_16x16x32_bf16 v[38:41], v[160:163], v[192:195], 0
	v_mfma_f32_16x16x32_bf16 v[34:37], v[176:179], v[192:195], 0
	v_mfma_f32_16x16x32_bf16 v[22:25], v[160:163], v[200:203], 0
	v_mfma_f32_16x16x32_bf16 v[18:21], v[176:179], v[200:203], 0
	v_mfma_f32_16x16x32_bf16 v[6:9], v[160:163], v[208:211], 0
	v_mfma_f32_16x16x32_bf16 v[2:5], v[176:179], v[208:211], 0
	v_mfma_f32_16x16x32_bf16 v[54:57], v[172:175], v[188:191], v[54:57]
	v_mfma_f32_16x16x32_bf16 v[50:53], v[180:183], v[188:191], v[50:53]
	v_mfma_f32_16x16x32_bf16 v[38:41], v[172:175], v[196:199], v[38:41]
	v_mfma_f32_16x16x32_bf16 v[34:37], v[180:183], v[196:199], v[34:37]
	v_mfma_f32_16x16x32_bf16 v[22:25], v[172:175], v[204:207], v[22:25]
	v_mfma_f32_16x16x32_bf16 v[18:21], v[180:183], v[204:207], v[18:21]
	v_mfma_f32_16x16x32_bf16 v[6:9], v[172:175], v[212:215], v[6:9]
	v_mfma_f32_16x16x32_bf16 v[2:5], v[180:183], v[212:215], v[2:5]
	s_barrier
	s_add_i32 s60, 0, 0x18000
	v_add_u32_e32 v1, s60, v166
	s_add_i32 s61, 0, 0x1c000
	ds_read_b128 v[130:133], v1
	ds_read_b128 v[134:137], v1 offset:1024
	ds_read_b128 v[138:141], v1 offset:2048
	ds_read_b128 v[142:145], v1 offset:3072
	v_add_u32_e32 v1, s61, v166
	ds_read_b128 v[160:163], v1
	ds_read_b128 v[172:175], v1 offset:1024
	ds_read_b128 v[176:179], v1 offset:2048
	ds_read_b128 v[180:183], v1 offset:3072
	s_add_u32 s26, s58, 0x40000
	s_addc_u32 s27, s59, 0
	s_mov_b32 m0, s86
	ds_read_b128 v[184:187], v169 offset:32768
	ds_read_b128 v[188:191], v169 offset:33792
	ds_read_b128 v[192:195], v169 offset:34816
	ds_read_b128 v[196:199], v169 offset:35840
	ds_read_b128 v[200:203], v169 offset:36864
	ds_read_b128 v[204:207], v169 offset:37888
	ds_read_b128 v[208:211], v169 offset:38912
	ds_read_b128 v[212:215], v169 offset:39936
	global_load_lds_dwordx4 v146, s[26:27]
	s_mov_b32 m0, s87
	s_nop 0
	global_load_lds_dwordx4 v150, s[26:27]
	s_waitcnt vmcnt(8)
	s_waitcnt lgkmcnt(0)
	s_barrier
	s_waitcnt lgkmcnt(0)
	v_mfma_f32_16x16x32_bf16 v[126:129], v[130:133], v[184:187], v[126:129]
	v_mfma_f32_16x16x32_bf16 v[122:125], v[138:141], v[184:187], v[122:125]
	v_mfma_f32_16x16x32_bf16 v[110:113], v[130:133], v[192:195], v[110:113]
	v_mfma_f32_16x16x32_bf16 v[106:109], v[138:141], v[192:195], v[106:109]
	v_mfma_f32_16x16x32_bf16 v[94:97], v[130:133], v[200:203], v[94:97]
	v_mfma_f32_16x16x32_bf16 v[90:93], v[138:141], v[200:203], v[90:93]
	v_mfma_f32_16x16x32_bf16 v[78:81], v[130:133], v[208:211], v[78:81]
	v_mfma_f32_16x16x32_bf16 v[74:77], v[138:141], v[208:211], v[74:77]
	v_mfma_f32_16x16x32_bf16 v[126:129], v[134:137], v[188:191], v[126:129]
	v_mfma_f32_16x16x32_bf16 v[122:125], v[142:145], v[188:191], v[122:125]
	v_mfma_f32_16x16x32_bf16 v[110:113], v[134:137], v[196:199], v[110:113]
	v_mfma_f32_16x16x32_bf16 v[106:109], v[142:145], v[196:199], v[106:109]
	v_mfma_f32_16x16x32_bf16 v[94:97], v[134:137], v[204:207], v[94:97]
	v_mfma_f32_16x16x32_bf16 v[90:93], v[142:145], v[204:207], v[90:93]
	v_mfma_f32_16x16x32_bf16 v[78:81], v[134:137], v[212:215], v[78:81]
	v_mfma_f32_16x16x32_bf16 v[74:77], v[142:145], v[212:215], v[74:77]
	v_mfma_f32_16x16x32_bf16 v[118:121], v[160:163], v[184:187], v[118:121]
	v_mfma_f32_16x16x32_bf16 v[114:117], v[176:179], v[184:187], v[114:117]
	v_mfma_f32_16x16x32_bf16 v[102:105], v[160:163], v[192:195], v[102:105]
	v_mfma_f32_16x16x32_bf16 v[98:101], v[176:179], v[192:195], v[98:101]
	v_mfma_f32_16x16x32_bf16 v[86:89], v[160:163], v[200:203], v[86:89]
	v_mfma_f32_16x16x32_bf16 v[82:85], v[176:179], v[200:203], v[82:85]
	v_mfma_f32_16x16x32_bf16 v[70:73], v[160:163], v[208:211], v[70:73]
	v_mfma_f32_16x16x32_bf16 v[66:69], v[176:179], v[208:211], v[66:69]
	v_mfma_f32_16x16x32_bf16 v[118:121], v[172:175], v[188:191], v[118:121]
	v_mfma_f32_16x16x32_bf16 v[114:117], v[180:183], v[188:191], v[114:117]
	v_mfma_f32_16x16x32_bf16 v[102:105], v[172:175], v[196:199], v[102:105]
	v_mfma_f32_16x16x32_bf16 v[98:101], v[180:183], v[196:199], v[98:101]
	v_mfma_f32_16x16x32_bf16 v[86:89], v[172:175], v[204:207], v[86:89]
	v_mfma_f32_16x16x32_bf16 v[82:85], v[180:183], v[204:207], v[82:85]
	v_mfma_f32_16x16x32_bf16 v[70:73], v[172:175], v[212:215], v[70:73]
	v_mfma_f32_16x16x32_bf16 v[66:69], v[180:183], v[212:215], v[66:69]
	s_barrier
	s_add_i32 s26, s60, s39
	v_lshl_add_u64 v[164:165], v[164:165], 0, s[18:19]
	s_mov_b32 m0, s26
	ds_read_b128 v[184:187], v169 offset:49152
	ds_read_b128 v[188:191], v169 offset:50176
	ds_read_b128 v[192:195], v169 offset:51200
	ds_read_b128 v[196:199], v169 offset:52224
	ds_read_b128 v[200:203], v169 offset:53248
	ds_read_b128 v[204:207], v169 offset:54272
	ds_read_b128 v[208:211], v169 offset:55296
	ds_read_b128 v[212:215], v169 offset:56320
	global_load_lds_dwordx4 v[164:165], off
	s_add_i32 m0, s26, 0x2000
	s_add_u32 s10, s10, 0x40080
	v_lshl_add_u64 v[164:165], v[216:217], 0, s[18:19]
	s_addc_u32 s11, s11, 0
	s_add_i32 s26, s61, s39
	global_load_lds_dwordx4 v[164:165], off
	s_mov_b32 m0, s26
	s_nop 0
	global_load_lds_dwordx4 v148, s[10:11]
	s_add_i32 m0, s26, 0x2000
	s_nop 0
	global_load_lds_dwordx4 v152, s[10:11]
	v_lshl_add_u64 v[164:165], v[218:219], 0, s[18:19]
	s_mov_b32 m0, s91
	s_nop 0
	global_load_lds_dwordx4 v[164:165], off
	v_lshl_add_u64 v[164:165], v[220:221], 0, s[18:19]
	s_mov_b32 m0, s92
	s_nop 0
	global_load_lds_dwordx4 v[164:165], off
	s_waitcnt vmcnt(8)
	s_waitcnt lgkmcnt(0)
	s_barrier
	s_waitcnt lgkmcnt(0)
	v_mfma_f32_16x16x32_bf16 v[62:65], v[130:133], v[184:187], v[62:65]
	v_mfma_f32_16x16x32_bf16 v[58:61], v[138:141], v[184:187], v[58:61]
	v_mfma_f32_16x16x32_bf16 v[46:49], v[130:133], v[192:195], v[46:49]
	v_mfma_f32_16x16x32_bf16 v[42:45], v[138:141], v[192:195], v[42:45]
	v_mfma_f32_16x16x32_bf16 v[30:33], v[130:133], v[200:203], v[30:33]
	v_mfma_f32_16x16x32_bf16 v[26:29], v[138:141], v[200:203], v[26:29]
	v_mfma_f32_16x16x32_bf16 v[14:17], v[130:133], v[208:211], v[14:17]
	v_mfma_f32_16x16x32_bf16 v[10:13], v[138:141], v[208:211], v[10:13]
	v_mfma_f32_16x16x32_bf16 v[62:65], v[134:137], v[188:191], v[62:65]
	v_mfma_f32_16x16x32_bf16 v[58:61], v[142:145], v[188:191], v[58:61]
	v_mfma_f32_16x16x32_bf16 v[46:49], v[134:137], v[196:199], v[46:49]
	v_mfma_f32_16x16x32_bf16 v[42:45], v[142:145], v[196:199], v[42:45]
	v_mfma_f32_16x16x32_bf16 v[30:33], v[134:137], v[204:207], v[30:33]
	v_mfma_f32_16x16x32_bf16 v[26:29], v[142:145], v[204:207], v[26:29]
	v_mfma_f32_16x16x32_bf16 v[14:17], v[134:137], v[212:215], v[14:17]
	v_mfma_f32_16x16x32_bf16 v[10:13], v[142:145], v[212:215], v[10:13]
	v_mfma_f32_16x16x32_bf16 v[54:57], v[160:163], v[184:187], v[54:57]
	v_mfma_f32_16x16x32_bf16 v[50:53], v[176:179], v[184:187], v[50:53]
	v_mfma_f32_16x16x32_bf16 v[38:41], v[160:163], v[192:195], v[38:41]
	v_mfma_f32_16x16x32_bf16 v[34:37], v[176:179], v[192:195], v[34:37]
	v_mfma_f32_16x16x32_bf16 v[22:25], v[160:163], v[200:203], v[22:25]
	v_mfma_f32_16x16x32_bf16 v[18:21], v[176:179], v[200:203], v[18:21]
	v_mfma_f32_16x16x32_bf16 v[6:9], v[160:163], v[208:211], v[6:9]
	v_mfma_f32_16x16x32_bf16 v[2:5], v[176:179], v[208:211], v[2:5]
	v_mfma_f32_16x16x32_bf16 v[54:57], v[172:175], v[188:191], v[54:57]
	v_mfma_f32_16x16x32_bf16 v[50:53], v[180:183], v[188:191], v[50:53]
	v_mfma_f32_16x16x32_bf16 v[38:41], v[172:175], v[196:199], v[38:41]
	v_mfma_f32_16x16x32_bf16 v[34:37], v[180:183], v[196:199], v[34:37]
	v_mfma_f32_16x16x32_bf16 v[22:25], v[172:175], v[204:207], v[22:25]
	v_mfma_f32_16x16x32_bf16 v[18:21], v[180:183], v[204:207], v[18:21]
	v_mfma_f32_16x16x32_bf16 v[6:9], v[172:175], v[212:215], v[6:9]
	v_mfma_f32_16x16x32_bf16 v[2:5], v[180:183], v[212:215], v[2:5]
	s_barrier
	s_add_i32 s51, s51, 2
	s_add_u32 s7, s7, 0x100
	s_addc_u32 s31, s31, 0
	s_add_u32 s8, s8, 0x100
	s_addc_u32 s9, s9, 0
.LBB0_953:
	ds_read_b128 v[130:133], v167
	ds_read_b128 v[134:137], v167 offset:1024
	ds_read_b128 v[138:141], v167 offset:2048
	ds_read_b128 v[142:145], v167 offset:3072
	ds_read_b128 v[160:163], v168
	ds_read_b128 v[172:175], v168 offset:1024
	ds_read_b128 v[176:179], v168 offset:2048
	ds_read_b128 v[180:183], v168 offset:3072
	s_add_u32 s10, s8, 0xfffc0080
	s_addc_u32 s11, s9, -1
	s_cmp_eq_u32 s51, 12
	s_cselect_b32 s59, s53, s11
	s_cselect_b32 s58, s52, s10
	s_cselect_b32 s11, s57, s31
	s_cselect_b32 s10, s56, s7
	s_add_i32 m0, s84, 0xc000
	ds_read_b128 v[184:187], v169
	ds_read_b128 v[188:191], v169 offset:1024
	ds_read_b128 v[192:195], v169 offset:2048
	ds_read_b128 v[196:199], v169 offset:3072
	ds_read_b128 v[200:203], v169 offset:4096
	ds_read_b128 v[204:207], v169 offset:5120
	ds_read_b128 v[208:211], v169 offset:6144
	ds_read_b128 v[212:215], v169 offset:7168
	global_load_lds_dwordx4 v158, s[8:9]
	s_add_i32 m0, s84, 0xe000
	s_nop 0
	global_load_lds_dwordx4 v156, s[8:9]
	s_waitcnt vmcnt(8)
	s_waitcnt lgkmcnt(0)
	s_barrier
	s_waitcnt lgkmcnt(0)
	v_mfma_f32_16x16x32_bf16 v[126:129], v[130:133], v[184:187], v[126:129]
	v_mfma_f32_16x16x32_bf16 v[122:125], v[138:141], v[184:187], v[122:125]
	v_mfma_f32_16x16x32_bf16 v[110:113], v[130:133], v[192:195], v[110:113]
	v_mfma_f32_16x16x32_bf16 v[106:109], v[138:141], v[192:195], v[106:109]
	v_mfma_f32_16x16x32_bf16 v[94:97], v[130:133], v[200:203], v[94:97]
	v_mfma_f32_16x16x32_bf16 v[90:93], v[138:141], v[200:203], v[90:93]
	v_mfma_f32_16x16x32_bf16 v[78:81], v[130:133], v[208:211], v[78:81]
	v_mfma_f32_16x16x32_bf16 v[74:77], v[138:141], v[208:211], v[74:77]
	v_mfma_f32_16x16x32_bf16 v[126:129], v[134:137], v[188:191], v[126:129]
	v_mfma_f32_16x16x32_bf16 v[122:125], v[142:145], v[188:191], v[122:125]
	v_mfma_f32_16x16x32_bf16 v[110:113], v[134:137], v[196:199], v[110:113]
	v_mfma_f32_16x16x32_bf16 v[106:109], v[142:145], v[196:199], v[106:109]
	v_mfma_f32_16x16x32_bf16 v[94:97], v[134:137], v[204:207], v[94:97]
	v_mfma_f32_16x16x32_bf16 v[90:93], v[142:145], v[204:207], v[90:93]
	v_mfma_f32_16x16x32_bf16 v[78:81], v[134:137], v[212:215], v[78:81]
	v_mfma_f32_16x16x32_bf16 v[74:77], v[142:145], v[212:215], v[74:77]
	v_mfma_f32_16x16x32_bf16 v[118:121], v[160:163], v[184:187], v[118:121]
	v_mfma_f32_16x16x32_bf16 v[114:117], v[176:179], v[184:187], v[114:117]
	v_mfma_f32_16x16x32_bf16 v[102:105], v[160:163], v[192:195], v[102:105]
	v_mfma_f32_16x16x32_bf16 v[98:101], v[176:179], v[192:195], v[98:101]
	v_mfma_f32_16x16x32_bf16 v[86:89], v[160:163], v[200:203], v[86:89]
	v_mfma_f32_16x16x32_bf16 v[82:85], v[176:179], v[200:203], v[82:85]
	v_mfma_f32_16x16x32_bf16 v[70:73], v[160:163], v[208:211], v[70:73]
	v_mfma_f32_16x16x32_bf16 v[66:69], v[176:179], v[208:211], v[66:69]
	v_mfma_f32_16x16x32_bf16 v[118:121], v[172:175], v[188:191], v[118:121]
	v_mfma_f32_16x16x32_bf16 v[114:117], v[180:183], v[188:191], v[114:117]
	v_mfma_f32_16x16x32_bf16 v[102:105], v[172:175], v[196:199], v[102:105]
	v_mfma_f32_16x16x32_bf16 v[98:101], v[180:183], v[196:199], v[98:101]
	v_mfma_f32_16x16x32_bf16 v[86:89], v[172:175], v[204:207], v[86:89]
	v_mfma_f32_16x16x32_bf16 v[82:85], v[180:183], v[204:207], v[82:85]
	v_mfma_f32_16x16x32_bf16 v[70:73], v[172:175], v[212:215], v[70:73]
	v_mfma_f32_16x16x32_bf16 v[66:69], v[180:183], v[212:215], v[66:69]
	s_barrier
	s_add_i32 s26, s94, s39
	v_lshl_add_u64 v[164:165], s[10:11], 0, v[148:149]
	s_mov_b32 m0, s26
	ds_read_b128 v[184:187], v169 offset:16384
	ds_read_b128 v[188:191], v169 offset:17408
	ds_read_b128 v[192:195], v169 offset:18432
	ds_read_b128 v[196:199], v169 offset:19456
	ds_read_b128 v[200:203], v169 offset:20480
	ds_read_b128 v[204:207], v169 offset:21504
	ds_read_b128 v[208:211], v169 offset:22528
	ds_read_b128 v[212:215], v169 offset:23552
	global_load_lds_dwordx4 v[164:165], off
	s_add_i32 m0, s26, 0x2000
	s_add_u32 s26, s10, 0x40000
	v_lshl_add_u64 v[216:217], s[10:11], 0, v[152:153]
	s_addc_u32 s27, s11, 0
	s_add_i32 s60, s95, s39
	global_load_lds_dwordx4 v[216:217], off
	s_mov_b32 m0, s60
	v_lshl_add_u64 v[220:221], s[58:59], 0, v[150:151]
	global_load_lds_dwordx4 v148, s[26:27]
	s_add_i32 m0, s60, 0x2000
	s_nop 0
	global_load_lds_dwordx4 v152, s[26:27]
	v_lshl_add_u64 v[218:219], s[58:59], 0, v[146:147]
	s_mov_b32 m0, s84
	s_nop 0
	global_load_lds_dwordx4 v[218:219], off
	s_mov_b32 m0, s85
	s_nop 0
	global_load_lds_dwordx4 v[220:221], off
	s_waitcnt vmcnt(8)
	s_waitcnt lgkmcnt(0)
	s_barrier
	s_waitcnt lgkmcnt(0)
	v_mfma_f32_16x16x32_bf16 v[62:65], v[130:133], v[184:187], v[62:65]
	v_mfma_f32_16x16x32_bf16 v[58:61], v[138:141], v[184:187], v[58:61]
	v_mfma_f32_16x16x32_bf16 v[46:49], v[130:133], v[192:195], v[46:49]
	v_mfma_f32_16x16x32_bf16 v[42:45], v[138:141], v[192:195], v[42:45]
	v_mfma_f32_16x16x32_bf16 v[30:33], v[130:133], v[200:203], v[30:33]
	v_mfma_f32_16x16x32_bf16 v[26:29], v[138:141], v[200:203], v[26:29]
	v_mfma_f32_16x16x32_bf16 v[14:17], v[130:133], v[208:211], v[14:17]
	v_mfma_f32_16x16x32_bf16 v[10:13], v[138:141], v[208:211], v[10:13]
	v_mfma_f32_16x16x32_bf16 v[62:65], v[134:137], v[188:191], v[62:65]
	v_mfma_f32_16x16x32_bf16 v[58:61], v[142:145], v[188:191], v[58:61]
	v_mfma_f32_16x16x32_bf16 v[46:49], v[134:137], v[196:199], v[46:49]
	v_mfma_f32_16x16x32_bf16 v[42:45], v[142:145], v[196:199], v[42:45]
	v_mfma_f32_16x16x32_bf16 v[30:33], v[134:137], v[204:207], v[30:33]
	v_mfma_f32_16x16x32_bf16 v[26:29], v[142:145], v[204:207], v[26:29]
	v_mfma_f32_16x16x32_bf16 v[14:17], v[134:137], v[212:215], v[14:17]
	v_mfma_f32_16x16x32_bf16 v[10:13], v[142:145], v[212:215], v[10:13]
	v_mfma_f32_16x16x32_bf16 v[54:57], v[160:163], v[184:187], v[54:57]
	v_mfma_f32_16x16x32_bf16 v[50:53], v[176:179], v[184:187], v[50:53]
	v_mfma_f32_16x16x32_bf16 v[38:41], v[160:163], v[192:195], v[38:41]
	v_mfma_f32_16x16x32_bf16 v[34:37], v[176:179], v[192:195], v[34:37]
	v_mfma_f32_16x16x32_bf16 v[22:25], v[160:163], v[200:203], v[22:25]
	v_mfma_f32_16x16x32_bf16 v[18:21], v[176:179], v[200:203], v[18:21]
	v_mfma_f32_16x16x32_bf16 v[6:9], v[160:163], v[208:211], v[6:9]
	v_mfma_f32_16x16x32_bf16 v[2:5], v[176:179], v[208:211], v[2:5]
	v_mfma_f32_16x16x32_bf16 v[54:57], v[172:175], v[188:191], v[54:57]
	v_mfma_f32_16x16x32_bf16 v[50:53], v[180:183], v[188:191], v[50:53]
	v_mfma_f32_16x16x32_bf16 v[38:41], v[172:175], v[196:199], v[38:41]
	v_mfma_f32_16x16x32_bf16 v[34:37], v[180:183], v[196:199], v[34:37]
	v_mfma_f32_16x16x32_bf16 v[22:25], v[172:175], v[204:207], v[22:25]
	v_mfma_f32_16x16x32_bf16 v[18:21], v[180:183], v[204:207], v[18:21]
	v_mfma_f32_16x16x32_bf16 v[6:9], v[172:175], v[212:215], v[6:9]
	v_mfma_f32_16x16x32_bf16 v[2:5], v[180:183], v[212:215], v[2:5]
	s_barrier
	s_add_i32 s60, 0, 0x18000
	v_add_u32_e32 v1, s60, v166
	s_add_i32 s61, 0, 0x1c000
	ds_read_b128 v[130:133], v1
	ds_read_b128 v[134:137], v1 offset:1024
	ds_read_b128 v[138:141], v1 offset:2048
	ds_read_b128 v[142:145], v1 offset:3072
	v_add_u32_e32 v1, s61, v166
	ds_read_b128 v[160:163], v1
	ds_read_b128 v[172:175], v1 offset:1024
	ds_read_b128 v[176:179], v1 offset:2048
	ds_read_b128 v[180:183], v1 offset:3072
	s_add_u32 s26, s58, 0x40000
	s_addc_u32 s27, s59, 0
	s_mov_b32 m0, s86
	ds_read_b128 v[184:187], v169 offset:32768
	ds_read_b128 v[188:191], v169 offset:33792
	ds_read_b128 v[192:195], v169 offset:34816
	ds_read_b128 v[196:199], v169 offset:35840
	ds_read_b128 v[200:203], v169 offset:36864
	ds_read_b128 v[204:207], v169 offset:37888
	ds_read_b128 v[208:211], v169 offset:38912
	ds_read_b128 v[212:215], v169 offset:39936
	global_load_lds_dwordx4 v146, s[26:27]
	s_mov_b32 m0, s87
	s_nop 0
	global_load_lds_dwordx4 v150, s[26:27]
	s_waitcnt vmcnt(8)
	s_waitcnt lgkmcnt(0)
	s_barrier
	s_waitcnt lgkmcnt(0)
	v_mfma_f32_16x16x32_bf16 v[126:129], v[130:133], v[184:187], v[126:129]
	v_mfma_f32_16x16x32_bf16 v[122:125], v[138:141], v[184:187], v[122:125]
	v_mfma_f32_16x16x32_bf16 v[110:113], v[130:133], v[192:195], v[110:113]
	v_mfma_f32_16x16x32_bf16 v[106:109], v[138:141], v[192:195], v[106:109]
	v_mfma_f32_16x16x32_bf16 v[94:97], v[130:133], v[200:203], v[94:97]
	v_mfma_f32_16x16x32_bf16 v[90:93], v[138:141], v[200:203], v[90:93]
	v_mfma_f32_16x16x32_bf16 v[78:81], v[130:133], v[208:211], v[78:81]
	v_mfma_f32_16x16x32_bf16 v[74:77], v[138:141], v[208:211], v[74:77]
	v_mfma_f32_16x16x32_bf16 v[126:129], v[134:137], v[188:191], v[126:129]
	v_mfma_f32_16x16x32_bf16 v[122:125], v[142:145], v[188:191], v[122:125]
	v_mfma_f32_16x16x32_bf16 v[110:113], v[134:137], v[196:199], v[110:113]
	v_mfma_f32_16x16x32_bf16 v[106:109], v[142:145], v[196:199], v[106:109]
	v_mfma_f32_16x16x32_bf16 v[94:97], v[134:137], v[204:207], v[94:97]
	v_mfma_f32_16x16x32_bf16 v[90:93], v[142:145], v[204:207], v[90:93]
	v_mfma_f32_16x16x32_bf16 v[78:81], v[134:137], v[212:215], v[78:81]
	v_mfma_f32_16x16x32_bf16 v[74:77], v[142:145], v[212:215], v[74:77]
	v_mfma_f32_16x16x32_bf16 v[118:121], v[160:163], v[184:187], v[118:121]
	v_mfma_f32_16x16x32_bf16 v[114:117], v[176:179], v[184:187], v[114:117]
	v_mfma_f32_16x16x32_bf16 v[102:105], v[160:163], v[192:195], v[102:105]
	v_mfma_f32_16x16x32_bf16 v[98:101], v[176:179], v[192:195], v[98:101]
	v_mfma_f32_16x16x32_bf16 v[86:89], v[160:163], v[200:203], v[86:89]
	v_mfma_f32_16x16x32_bf16 v[82:85], v[176:179], v[200:203], v[82:85]
	v_mfma_f32_16x16x32_bf16 v[70:73], v[160:163], v[208:211], v[70:73]
	v_mfma_f32_16x16x32_bf16 v[66:69], v[176:179], v[208:211], v[66:69]
	v_mfma_f32_16x16x32_bf16 v[118:121], v[172:175], v[188:191], v[118:121]
	v_mfma_f32_16x16x32_bf16 v[114:117], v[180:183], v[188:191], v[114:117]
	v_mfma_f32_16x16x32_bf16 v[102:105], v[172:175], v[196:199], v[102:105]
	v_mfma_f32_16x16x32_bf16 v[98:101], v[180:183], v[196:199], v[98:101]
	v_mfma_f32_16x16x32_bf16 v[86:89], v[172:175], v[204:207], v[86:89]
	v_mfma_f32_16x16x32_bf16 v[82:85], v[180:183], v[204:207], v[82:85]
	v_mfma_f32_16x16x32_bf16 v[70:73], v[172:175], v[212:215], v[70:73]
	v_mfma_f32_16x16x32_bf16 v[66:69], v[180:183], v[212:215], v[66:69]
	s_barrier
	s_add_i32 s26, s60, s39
	v_lshl_add_u64 v[164:165], v[164:165], 0, s[18:19]
	s_mov_b32 m0, s26
	ds_read_b128 v[184:187], v169 offset:49152
	ds_read_b128 v[188:191], v169 offset:50176
	ds_read_b128 v[192:195], v169 offset:51200
	ds_read_b128 v[196:199], v169 offset:52224
	ds_read_b128 v[200:203], v169 offset:53248
	ds_read_b128 v[204:207], v169 offset:54272
	ds_read_b128 v[208:211], v169 offset:55296
	ds_read_b128 v[212:215], v169 offset:56320
	global_load_lds_dwordx4 v[164:165], off
	s_add_i32 m0, s26, 0x2000
	s_add_u32 s10, s10, 0x40080
	v_lshl_add_u64 v[164:165], v[216:217], 0, s[18:19]
	s_addc_u32 s11, s11, 0
	s_add_i32 s26, s61, s39
	global_load_lds_dwordx4 v[164:165], off
	s_mov_b32 m0, s26
	s_nop 0
	global_load_lds_dwordx4 v148, s[10:11]
	s_add_i32 m0, s26, 0x2000
	s_nop 0
	global_load_lds_dwordx4 v152, s[10:11]
	v_lshl_add_u64 v[164:165], v[218:219], 0, s[18:19]
	s_mov_b32 m0, s91
	s_nop 0
	global_load_lds_dwordx4 v[164:165], off
	v_lshl_add_u64 v[164:165], v[220:221], 0, s[18:19]
	s_mov_b32 m0, s92
	s_nop 0
	global_load_lds_dwordx4 v[164:165], off
	s_waitcnt vmcnt(8)
	s_waitcnt lgkmcnt(0)
	s_barrier
	s_waitcnt lgkmcnt(0)
	v_mfma_f32_16x16x32_bf16 v[62:65], v[130:133], v[184:187], v[62:65]
	v_mfma_f32_16x16x32_bf16 v[58:61], v[138:141], v[184:187], v[58:61]
	v_mfma_f32_16x16x32_bf16 v[46:49], v[130:133], v[192:195], v[46:49]
	v_mfma_f32_16x16x32_bf16 v[42:45], v[138:141], v[192:195], v[42:45]
	v_mfma_f32_16x16x32_bf16 v[30:33], v[130:133], v[200:203], v[30:33]
	v_mfma_f32_16x16x32_bf16 v[26:29], v[138:141], v[200:203], v[26:29]
	v_mfma_f32_16x16x32_bf16 v[14:17], v[130:133], v[208:211], v[14:17]
	v_mfma_f32_16x16x32_bf16 v[10:13], v[138:141], v[208:211], v[10:13]
	v_mfma_f32_16x16x32_bf16 v[62:65], v[134:137], v[188:191], v[62:65]
	v_mfma_f32_16x16x32_bf16 v[58:61], v[142:145], v[188:191], v[58:61]
	v_mfma_f32_16x16x32_bf16 v[46:49], v[134:137], v[196:199], v[46:49]
	v_mfma_f32_16x16x32_bf16 v[42:45], v[142:145], v[196:199], v[42:45]
	v_mfma_f32_16x16x32_bf16 v[30:33], v[134:137], v[204:207], v[30:33]
	v_mfma_f32_16x16x32_bf16 v[26:29], v[142:145], v[204:207], v[26:29]
	v_mfma_f32_16x16x32_bf16 v[14:17], v[134:137], v[212:215], v[14:17]
	v_mfma_f32_16x16x32_bf16 v[10:13], v[142:145], v[212:215], v[10:13]
	v_mfma_f32_16x16x32_bf16 v[54:57], v[160:163], v[184:187], v[54:57]
	v_mfma_f32_16x16x32_bf16 v[50:53], v[176:179], v[184:187], v[50:53]
	v_mfma_f32_16x16x32_bf16 v[38:41], v[160:163], v[192:195], v[38:41]
	v_mfma_f32_16x16x32_bf16 v[34:37], v[176:179], v[192:195], v[34:37]
	v_mfma_f32_16x16x32_bf16 v[22:25], v[160:163], v[200:203], v[22:25]
	v_mfma_f32_16x16x32_bf16 v[18:21], v[176:179], v[200:203], v[18:21]
	v_mfma_f32_16x16x32_bf16 v[6:9], v[160:163], v[208:211], v[6:9]
	v_mfma_f32_16x16x32_bf16 v[2:5], v[176:179], v[208:211], v[2:5]
	v_mfma_f32_16x16x32_bf16 v[54:57], v[172:175], v[188:191], v[54:57]
	v_mfma_f32_16x16x32_bf16 v[50:53], v[180:183], v[188:191], v[50:53]
	v_mfma_f32_16x16x32_bf16 v[38:41], v[172:175], v[196:199], v[38:41]
	v_mfma_f32_16x16x32_bf16 v[34:37], v[180:183], v[196:199], v[34:37]
	v_mfma_f32_16x16x32_bf16 v[22:25], v[172:175], v[204:207], v[22:25]
	v_mfma_f32_16x16x32_bf16 v[18:21], v[180:183], v[204:207], v[18:21]
	v_mfma_f32_16x16x32_bf16 v[6:9], v[172:175], v[212:215], v[6:9]
	v_mfma_f32_16x16x32_bf16 v[2:5], v[180:183], v[212:215], v[2:5]
	s_barrier
	s_add_i32 s51, s51, 2
	s_add_u32 s7, s7, 0x100
	s_addc_u32 s31, s31, 0
	s_add_u32 s8, s8, 0x100
	s_addc_u32 s9, s9, 0
	s_cmp_gt_u32 s51, 13
	s_cbranch_scc0 .LBB0_953
	s_and_b64 vcc, exec, s[14:15]
	s_cbranch_vccz .LBB0_956
	s_barrier

.LBB0_1290:
	s_add_u32 s8, s56, 0x100
	s_addc_u32 s45, s57, 0
	s_add_u32 s6, s52, 0x40080
	v_mov_b32_e32 v8, 0
	s_addc_u32 s7, s53, 0
	s_mov_b32 s55, -2
	s_waitcnt lgkmcnt(0)
	ds_read_b128 v[0:3], v96
	ds_read_b128 v[4:7], v96 offset:1024
	ds_read_b128 v[84:87], v96 offset:2048
	ds_read_b128 v[100:103], v96 offset:3072
	s_add_u32 s26, s6, 0xfffc0080
	s_addc_u32 s27, s7, -1
	s_cmp_eq_u32 s55, 12
	s_cselect_b32 s53, s47, s27
	s_cselect_b32 s52, s46, s26
	s_cselect_b32 s27, s49, s45
	s_cselect_b32 s26, s48, s8
	s_add_i32 m0, s28, 0xc000
	ds_read_b128 v[104:107], v97
	ds_read_b128 v[108:111], v97 offset:1024
	ds_read_b128 v[112:115], v97 offset:2048
	ds_read_b128 v[116:119], v97 offset:3072
	ds_read_b128 v[120:123], v97 offset:4096
	ds_read_b128 v[124:127], v97 offset:5120
	ds_read_b128 v[128:131], v97 offset:6144
	ds_read_b128 v[132:135], v97 offset:7168
	global_load_lds_dwordx4 v82, s[6:7]
	s_add_i32 m0, s28, 0xe000
	s_nop 0
	global_load_lds_dwordx4 v80, s[6:7]
	s_waitcnt vmcnt(6)
	s_waitcnt lgkmcnt(0)
	s_barrier
	s_waitcnt lgkmcnt(0)
	v_mfma_f32_16x16x32_bf16 v[68:71], v[0:3], v[104:107], 0
	v_mfma_f32_16x16x32_bf16 v[64:67], v[84:87], v[104:107], 0
	v_mfma_f32_16x16x32_bf16 v[60:63], v[0:3], v[112:115], 0
	v_mfma_f32_16x16x32_bf16 v[56:59], v[84:87], v[112:115], 0
	v_mfma_f32_16x16x32_bf16 v[52:55], v[0:3], v[120:123], 0
	v_mfma_f32_16x16x32_bf16 v[48:51], v[84:87], v[120:123], 0
	v_mfma_f32_16x16x32_bf16 v[44:47], v[0:3], v[128:131], 0
	v_mfma_f32_16x16x32_bf16 v[40:43], v[84:87], v[128:131], 0
	v_mfma_f32_16x16x32_bf16 v[68:71], v[4:7], v[108:111], v[68:71]
	v_mfma_f32_16x16x32_bf16 v[64:67], v[100:103], v[108:111], v[64:67]
	v_mfma_f32_16x16x32_bf16 v[60:63], v[4:7], v[116:119], v[60:63]
	v_mfma_f32_16x16x32_bf16 v[56:59], v[100:103], v[116:119], v[56:59]
	v_mfma_f32_16x16x32_bf16 v[52:55], v[4:7], v[124:127], v[52:55]
	v_mfma_f32_16x16x32_bf16 v[48:51], v[100:103], v[124:127], v[48:51]
	v_mfma_f32_16x16x32_bf16 v[44:47], v[4:7], v[132:135], v[44:47]
	v_mfma_f32_16x16x32_bf16 v[40:43], v[100:103], v[132:135], v[40:43]
	s_barrier
	s_add_i32 s56, s68, s39
	v_lshl_add_u64 v[88:89], s[26:27], 0, v[74:75]
	s_mov_b32 m0, s56
	ds_read_b128 v[104:107], v97 offset:16384
	ds_read_b128 v[108:111], v97 offset:17408
	ds_read_b128 v[112:115], v97 offset:18432
	ds_read_b128 v[116:119], v97 offset:19456
	ds_read_b128 v[120:123], v97 offset:20480
	ds_read_b128 v[124:127], v97 offset:21504
	ds_read_b128 v[128:131], v97 offset:22528
	ds_read_b128 v[132:135], v97 offset:23552
	global_load_lds_dwordx4 v[88:89], off
	v_lshl_add_u64 v[136:137], s[26:27], 0, v[78:79]
	s_add_i32 m0, s56, 0x2000
	v_lshl_add_u64 v[138:139], s[52:53], 0, v[72:73]
	global_load_lds_dwordx4 v[136:137], off
	s_mov_b32 m0, s28
	v_lshl_add_u64 v[140:141], s[52:53], 0, v[76:77]
	global_load_lds_dwordx4 v[138:139], off
	s_mov_b32 m0, s29
	s_nop 0
	global_load_lds_dwordx4 v[140:141], off
	s_waitcnt vmcnt(6)
	s_waitcnt lgkmcnt(0)
	s_barrier
	s_waitcnt lgkmcnt(0)
	v_mfma_f32_16x16x32_bf16 v[36:39], v[0:3], v[104:107], 0
	v_mfma_f32_16x16x32_bf16 v[32:35], v[84:87], v[104:107], 0
	v_mfma_f32_16x16x32_bf16 v[28:31], v[0:3], v[112:115], 0
	v_mfma_f32_16x16x32_bf16 v[24:27], v[84:87], v[112:115], 0
	v_mfma_f32_16x16x32_bf16 v[20:23], v[0:3], v[120:123], 0
	v_mfma_f32_16x16x32_bf16 v[16:19], v[84:87], v[120:123], 0
	v_mfma_f32_16x16x32_bf16 v[0:3], v[0:3], v[128:131], 0
	v_mfma_f32_16x16x32_bf16 v[36:39], v[4:7], v[108:111], v[36:39]
	v_mfma_f32_16x16x32_bf16 v[32:35], v[100:103], v[108:111], v[32:35]
	v_mfma_f32_16x16x32_bf16 v[28:31], v[4:7], v[116:119], v[28:31]
	v_mfma_f32_16x16x32_bf16 v[24:27], v[100:103], v[116:119], v[24:27]
	v_mfma_f32_16x16x32_bf16 v[20:23], v[4:7], v[124:127], v[20:23]
	v_mfma_f32_16x16x32_bf16 v[16:19], v[100:103], v[124:127], v[16:19]
	v_mfma_f32_16x16x32_bf16 v[0:3], v[4:7], v[132:135], v[0:3]
	v_mfma_f32_16x16x32_bf16 v[4:7], v[84:87], v[128:131], 0
	v_mfma_f32_16x16x32_bf16 v[4:7], v[100:103], v[132:135], v[4:7]
	s_barrier
	s_add_i32 s56, 0, 0x18000
	v_add_u32_e32 v90, s56, v91
	ds_read_b128 v[8:11], v90
	ds_read_b128 v[12:15], v90 offset:1024
	ds_read_b128 v[84:87], v90 offset:2048
	ds_read_b128 v[100:103], v90 offset:3072
	s_add_u32 s26, s52, 0x40000
	s_addc_u32 s27, s53, 0
	s_mov_b32 m0, s30
	ds_read_b128 v[104:107], v97 offset:32768
	ds_read_b128 v[108:111], v97 offset:33792
	ds_read_b128 v[112:115], v97 offset:34816
	ds_read_b128 v[116:119], v97 offset:35840
	ds_read_b128 v[120:123], v97 offset:36864
	ds_read_b128 v[124:127], v97 offset:37888
	ds_read_b128 v[128:131], v97 offset:38912
	ds_read_b128 v[132:135], v97 offset:39936
	global_load_lds_dwordx4 v72, s[26:27]
	s_mov_b32 m0, s31
	s_nop 0
	global_load_lds_dwordx4 v76, s[26:27]
	s_waitcnt vmcnt(6)
	s_waitcnt lgkmcnt(0)
	s_barrier
	s_waitcnt lgkmcnt(0)
	v_mfma_f32_16x16x32_bf16 v[68:71], v[8:11], v[104:107], v[68:71]
	v_mfma_f32_16x16x32_bf16 v[64:67], v[84:87], v[104:107], v[64:67]
	v_mfma_f32_16x16x32_bf16 v[60:63], v[8:11], v[112:115], v[60:63]
	v_mfma_f32_16x16x32_bf16 v[56:59], v[84:87], v[112:115], v[56:59]
	v_mfma_f32_16x16x32_bf16 v[52:55], v[8:11], v[120:123], v[52:55]
	v_mfma_f32_16x16x32_bf16 v[48:51], v[84:87], v[120:123], v[48:51]
	v_mfma_f32_16x16x32_bf16 v[44:47], v[8:11], v[128:131], v[44:47]
	v_mfma_f32_16x16x32_bf16 v[40:43], v[84:87], v[128:131], v[40:43]
	v_mfma_f32_16x16x32_bf16 v[68:71], v[12:15], v[108:111], v[68:71]
	v_mfma_f32_16x16x32_bf16 v[64:67], v[100:103], v[108:111], v[64:67]
	v_mfma_f32_16x16x32_bf16 v[60:63], v[12:15], v[116:119], v[60:63]
	v_mfma_f32_16x16x32_bf16 v[56:59], v[100:103], v[116:119], v[56:59]
	v_mfma_f32_16x16x32_bf16 v[52:55], v[12:15], v[124:127], v[52:55]
	v_mfma_f32_16x16x32_bf16 v[48:51], v[100:103], v[124:127], v[48:51]
	v_mfma_f32_16x16x32_bf16 v[44:47], v[12:15], v[132:135], v[44:47]
	v_mfma_f32_16x16x32_bf16 v[40:43], v[100:103], v[132:135], v[40:43]
	s_barrier
	s_add_i32 s26, s56, s39
	v_lshl_add_u64 v[88:89], v[88:89], 0, s[10:11]
	s_mov_b32 m0, s26
	ds_read_b128 v[104:107], v97 offset:49152
	ds_read_b128 v[108:111], v97 offset:50176
	ds_read_b128 v[112:115], v97 offset:51200
	ds_read_b128 v[116:119], v97 offset:52224
	ds_read_b128 v[120:123], v97 offset:53248
	ds_read_b128 v[124:127], v97 offset:54272
	ds_read_b128 v[128:131], v97 offset:55296
	ds_read_b128 v[132:135], v97 offset:56320
	global_load_lds_dwordx4 v[88:89], off
	v_lshl_add_u64 v[88:89], v[136:137], 0, s[10:11]
	s_add_i32 m0, s26, 0x2000
	s_nop 0
	global_load_lds_dwordx4 v[88:89], off
	v_lshl_add_u64 v[88:89], v[138:139], 0, s[10:11]
	s_mov_b32 m0, s62
	s_nop 0
	global_load_lds_dwordx4 v[88:89], off
	v_lshl_add_u64 v[88:89], v[140:141], 0, s[10:11]
	s_mov_b32 m0, s63
	s_nop 0
	global_load_lds_dwordx4 v[88:89], off
	s_waitcnt vmcnt(6)
	s_waitcnt lgkmcnt(0)
	s_barrier
	s_waitcnt lgkmcnt(0)
	v_mfma_f32_16x16x32_bf16 v[36:39], v[8:11], v[104:107], v[36:39]
	v_mfma_f32_16x16x32_bf16 v[28:31], v[8:11], v[112:115], v[28:31]
	v_mfma_f32_16x16x32_bf16 v[20:23], v[8:11], v[120:123], v[20:23]
	v_mfma_f32_16x16x32_bf16 v[0:3], v[8:11], v[128:131], v[0:3]
	v_mfma_f32_16x16x32_bf16 v[36:39], v[12:15], v[108:111], v[36:39]
	v_mfma_f32_16x16x32_bf16 v[32:35], v[84:87], v[104:107], v[32:35]
	v_mfma_f32_16x16x32_bf16 v[28:31], v[12:15], v[116:119], v[28:31]
	v_mfma_f32_16x16x32_bf16 v[24:27], v[84:87], v[112:115], v[24:27]
	v_mfma_f32_16x16x32_bf16 v[20:23], v[12:15], v[124:127], v[20:23]
	v_mfma_f32_16x16x32_bf16 v[16:19], v[84:87], v[120:123], v[16:19]
	v_mfma_f32_16x16x32_bf16 v[12:15], v[12:15], v[132:135], v[0:3]
	v_mfma_f32_16x16x32_bf16 v[0:3], v[84:87], v[128:131], v[4:7]
	v_mfma_f32_16x16x32_bf16 v[32:35], v[100:103], v[108:111], v[32:35]
	v_mfma_f32_16x16x32_bf16 v[24:27], v[100:103], v[116:119], v[24:27]
	v_mfma_f32_16x16x32_bf16 v[16:19], v[100:103], v[124:127], v[16:19]
	v_mfma_f32_16x16x32_bf16 v[8:11], v[100:103], v[132:135], v[0:3]
	s_barrier
	s_add_i32 s55, s55, 2
	s_add_u32 s8, s8, 0x100
	s_addc_u32 s45, s45, 0
	s_add_u32 s6, s6, 0x100
	s_addc_u32 s7, s7, 0
.LBB0_1291:
	s_waitcnt lgkmcnt(0)
	ds_read_b128 v[0:3], v96
	ds_read_b128 v[4:7], v96 offset:1024
	ds_read_b128 v[84:87], v96 offset:2048
	ds_read_b128 v[100:103], v96 offset:3072
	s_add_u32 s26, s6, 0xfffc0080
	s_addc_u32 s27, s7, -1
	s_cmp_eq_u32 s55, 12
	s_cselect_b32 s53, s47, s27
	s_cselect_b32 s52, s46, s26
	s_cselect_b32 s27, s49, s45
	s_cselect_b32 s26, s48, s8
	s_add_i32 m0, s28, 0xc000
	ds_read_b128 v[104:107], v97
	ds_read_b128 v[108:111], v97 offset:1024
	ds_read_b128 v[112:115], v97 offset:2048
	ds_read_b128 v[116:119], v97 offset:3072
	ds_read_b128 v[120:123], v97 offset:4096
	ds_read_b128 v[124:127], v97 offset:5120
	ds_read_b128 v[128:131], v97 offset:6144
	ds_read_b128 v[132:135], v97 offset:7168
	global_load_lds_dwordx4 v82, s[6:7]
	s_add_i32 m0, s28, 0xe000
	s_nop 0
	global_load_lds_dwordx4 v80, s[6:7]
	s_waitcnt vmcnt(6)
	s_waitcnt lgkmcnt(0)
	s_barrier
	s_waitcnt lgkmcnt(0)
	v_mfma_f32_16x16x32_bf16 v[68:71], v[0:3], v[104:107], v[68:71]
	v_mfma_f32_16x16x32_bf16 v[64:67], v[84:87], v[104:107], v[64:67]
	v_mfma_f32_16x16x32_bf16 v[60:63], v[0:3], v[112:115], v[60:63]
	v_mfma_f32_16x16x32_bf16 v[56:59], v[84:87], v[112:115], v[56:59]
	v_mfma_f32_16x16x32_bf16 v[52:55], v[0:3], v[120:123], v[52:55]
	v_mfma_f32_16x16x32_bf16 v[48:51], v[84:87], v[120:123], v[48:51]
	v_mfma_f32_16x16x32_bf16 v[44:47], v[0:3], v[128:131], v[44:47]
	v_mfma_f32_16x16x32_bf16 v[40:43], v[84:87], v[128:131], v[40:43]
	v_mfma_f32_16x16x32_bf16 v[68:71], v[4:7], v[108:111], v[68:71]
	v_mfma_f32_16x16x32_bf16 v[64:67], v[100:103], v[108:111], v[64:67]
	v_mfma_f32_16x16x32_bf16 v[60:63], v[4:7], v[116:119], v[60:63]
	v_mfma_f32_16x16x32_bf16 v[56:59], v[100:103], v[116:119], v[56:59]
	v_mfma_f32_16x16x32_bf16 v[52:55], v[4:7], v[124:127], v[52:55]
	v_mfma_f32_16x16x32_bf16 v[48:51], v[100:103], v[124:127], v[48:51]
	v_mfma_f32_16x16x32_bf16 v[44:47], v[4:7], v[132:135], v[44:47]
	v_mfma_f32_16x16x32_bf16 v[40:43], v[100:103], v[132:135], v[40:43]
	s_barrier
	s_add_i32 s56, s68, s39
	v_lshl_add_u64 v[88:89], s[26:27], 0, v[74:75]
	s_mov_b32 m0, s56
	ds_read_b128 v[104:107], v97 offset:16384
	ds_read_b128 v[108:111], v97 offset:17408
	ds_read_b128 v[112:115], v97 offset:18432
	ds_read_b128 v[116:119], v97 offset:19456
	ds_read_b128 v[120:123], v97 offset:20480
	ds_read_b128 v[124:127], v97 offset:21504
	ds_read_b128 v[128:131], v97 offset:22528
	ds_read_b128 v[132:135], v97 offset:23552
	global_load_lds_dwordx4 v[88:89], off
	v_lshl_add_u64 v[136:137], s[26:27], 0, v[78:79]
	s_add_i32 m0, s56, 0x2000
	v_lshl_add_u64 v[138:139], s[52:53], 0, v[72:73]
	global_load_lds_dwordx4 v[136:137], off
	s_mov_b32 m0, s28
	v_lshl_add_u64 v[140:141], s[52:53], 0, v[76:77]
	global_load_lds_dwordx4 v[138:139], off
	s_mov_b32 m0, s29
	s_nop 0
	global_load_lds_dwordx4 v[140:141], off
	s_waitcnt vmcnt(6)
	s_waitcnt lgkmcnt(0)
	s_barrier
	s_waitcnt lgkmcnt(0)
	v_mfma_f32_16x16x32_bf16 v[36:39], v[0:3], v[104:107], v[36:39]
	v_mfma_f32_16x16x32_bf16 v[32:35], v[84:87], v[104:107], v[32:35]
	v_mfma_f32_16x16x32_bf16 v[28:31], v[0:3], v[112:115], v[28:31]
	v_mfma_f32_16x16x32_bf16 v[24:27], v[84:87], v[112:115], v[24:27]
	v_mfma_f32_16x16x32_bf16 v[20:23], v[0:3], v[120:123], v[20:23]
	v_mfma_f32_16x16x32_bf16 v[16:19], v[84:87], v[120:123], v[16:19]
	v_mfma_f32_16x16x32_bf16 v[0:3], v[0:3], v[128:131], v[12:15]
	v_mfma_f32_16x16x32_bf16 v[36:39], v[4:7], v[108:111], v[36:39]
	v_mfma_f32_16x16x32_bf16 v[32:35], v[100:103], v[108:111], v[32:35]
	v_mfma_f32_16x16x32_bf16 v[28:31], v[4:7], v[116:119], v[28:31]
	v_mfma_f32_16x16x32_bf16 v[24:27], v[100:103], v[116:119], v[24:27]
	v_mfma_f32_16x16x32_bf16 v[20:23], v[4:7], v[124:127], v[20:23]
	v_mfma_f32_16x16x32_bf16 v[16:19], v[100:103], v[124:127], v[16:19]
	v_mfma_f32_16x16x32_bf16 v[0:3], v[4:7], v[132:135], v[0:3]
	v_mfma_f32_16x16x32_bf16 v[4:7], v[84:87], v[128:131], v[8:11]
	v_mfma_f32_16x16x32_bf16 v[4:7], v[100:103], v[132:135], v[4:7]
	s_barrier
	s_add_i32 s56, 0, 0x18000
	v_add_u32_e32 v90, s56, v91
	ds_read_b128 v[8:11], v90
	ds_read_b128 v[12:15], v90 offset:1024
	ds_read_b128 v[84:87], v90 offset:2048
	ds_read_b128 v[100:103], v90 offset:3072
	s_add_u32 s26, s52, 0x40000
	s_addc_u32 s27, s53, 0
	s_mov_b32 m0, s30
	ds_read_b128 v[104:107], v97 offset:32768
	ds_read_b128 v[108:111], v97 offset:33792
	ds_read_b128 v[112:115], v97 offset:34816
	ds_read_b128 v[116:119], v97 offset:35840
	ds_read_b128 v[120:123], v97 offset:36864
	ds_read_b128 v[124:127], v97 offset:37888
	ds_read_b128 v[128:131], v97 offset:38912
	ds_read_b128 v[132:135], v97 offset:39936
	global_load_lds_dwordx4 v72, s[26:27]
	s_mov_b32 m0, s31
	s_nop 0
	global_load_lds_dwordx4 v76, s[26:27]
	s_waitcnt vmcnt(6)
	s_waitcnt lgkmcnt(0)
	s_barrier
	s_waitcnt lgkmcnt(0)
	v_mfma_f32_16x16x32_bf16 v[68:71], v[8:11], v[104:107], v[68:71]
	v_mfma_f32_16x16x32_bf16 v[64:67], v[84:87], v[104:107], v[64:67]
	v_mfma_f32_16x16x32_bf16 v[60:63], v[8:11], v[112:115], v[60:63]
	v_mfma_f32_16x16x32_bf16 v[56:59], v[84:87], v[112:115], v[56:59]
	v_mfma_f32_16x16x32_bf16 v[52:55], v[8:11], v[120:123], v[52:55]
	v_mfma_f32_16x16x32_bf16 v[48:51], v[84:87], v[120:123], v[48:51]
	v_mfma_f32_16x16x32_bf16 v[44:47], v[8:11], v[128:131], v[44:47]
	v_mfma_f32_16x16x32_bf16 v[40:43], v[84:87], v[128:131], v[40:43]
	v_mfma_f32_16x16x32_bf16 v[68:71], v[12:15], v[108:111], v[68:71]
	v_mfma_f32_16x16x32_bf16 v[64:67], v[100:103], v[108:111], v[64:67]
	v_mfma_f32_16x16x32_bf16 v[60:63], v[12:15], v[116:119], v[60:63]
	v_mfma_f32_16x16x32_bf16 v[56:59], v[100:103], v[116:119], v[56:59]
	v_mfma_f32_16x16x32_bf16 v[52:55], v[12:15], v[124:127], v[52:55]
	v_mfma_f32_16x16x32_bf16 v[48:51], v[100:103], v[124:127], v[48:51]
	v_mfma_f32_16x16x32_bf16 v[44:47], v[12:15], v[132:135], v[44:47]
	v_mfma_f32_16x16x32_bf16 v[40:43], v[100:103], v[132:135], v[40:43]
	s_barrier
	s_add_i32 s26, s56, s39
	v_lshl_add_u64 v[88:89], v[88:89], 0, s[10:11]
	s_mov_b32 m0, s26
	ds_read_b128 v[104:107], v97 offset:49152
	ds_read_b128 v[108:111], v97 offset:50176
	ds_read_b128 v[112:115], v97 offset:51200
	ds_read_b128 v[116:119], v97 offset:52224
	ds_read_b128 v[120:123], v97 offset:53248
	ds_read_b128 v[124:127], v97 offset:54272
	ds_read_b128 v[128:131], v97 offset:55296
	ds_read_b128 v[132:135], v97 offset:56320
	global_load_lds_dwordx4 v[88:89], off
	v_lshl_add_u64 v[88:89], v[136:137], 0, s[10:11]
	s_add_i32 m0, s26, 0x2000
	s_nop 0
	global_load_lds_dwordx4 v[88:89], off
	v_lshl_add_u64 v[88:89], v[138:139], 0, s[10:11]
	s_mov_b32 m0, s62
	s_nop 0
	global_load_lds_dwordx4 v[88:89], off
	v_lshl_add_u64 v[88:89], v[140:141], 0, s[10:11]
	s_mov_b32 m0, s63
	s_nop 0
	global_load_lds_dwordx4 v[88:89], off
	s_waitcnt vmcnt(6)
	s_waitcnt lgkmcnt(0)
	s_barrier
	s_waitcnt lgkmcnt(0)
	v_mfma_f32_16x16x32_bf16 v[36:39], v[8:11], v[104:107], v[36:39]
	v_mfma_f32_16x16x32_bf16 v[28:31], v[8:11], v[112:115], v[28:31]
	v_mfma_f32_16x16x32_bf16 v[20:23], v[8:11], v[120:123], v[20:23]
	v_mfma_f32_16x16x32_bf16 v[0:3], v[8:11], v[128:131], v[0:3]
	v_mfma_f32_16x16x32_bf16 v[36:39], v[12:15], v[108:111], v[36:39]
	v_mfma_f32_16x16x32_bf16 v[32:35], v[84:87], v[104:107], v[32:35]
	v_mfma_f32_16x16x32_bf16 v[28:31], v[12:15], v[116:119], v[28:31]
	v_mfma_f32_16x16x32_bf16 v[24:27], v[84:87], v[112:115], v[24:27]
	v_mfma_f32_16x16x32_bf16 v[20:23], v[12:15], v[124:127], v[20:23]
	v_mfma_f32_16x16x32_bf16 v[16:19], v[84:87], v[120:123], v[16:19]
	v_mfma_f32_16x16x32_bf16 v[12:15], v[12:15], v[132:135], v[0:3]
	v_mfma_f32_16x16x32_bf16 v[0:3], v[84:87], v[128:131], v[4:7]
	v_mfma_f32_16x16x32_bf16 v[32:35], v[100:103], v[108:111], v[32:35]
	v_mfma_f32_16x16x32_bf16 v[24:27], v[100:103], v[116:119], v[24:27]
	v_mfma_f32_16x16x32_bf16 v[16:19], v[100:103], v[124:127], v[16:19]
	v_mfma_f32_16x16x32_bf16 v[8:11], v[100:103], v[132:135], v[0:3]
	s_barrier
	s_add_i32 s55, s55, 2
	s_add_u32 s8, s8, 0x100
	s_addc_u32 s45, s45, 0
	s_add_u32 s6, s6, 0x100
	s_addc_u32 s7, s7, 0
	s_cmp_gt_u32 s55, 13
	s_cbranch_scc0 .LBB0_1291
	s_and_b64 vcc, exec, s[14:15]
	s_cbranch_vccz .LBB0_1294
	s_barrier

.LBB0_1513:
	s_lshl_b32 s42, s10, 6
	s_lshl_b32 s13, s10, 13
	s_lshl_b32 s10, s75, 5
	s_and_b32 s43, s10, 0x60
	s_mov_b64 s[10:11], 0x80
	s_add_i32 m0, s36, 0x18000
	v_lshl_add_u64 v[6:7], v[6:7], 0, s[10:11]
	s_lshr_b32 s16, s43, 3
	s_waitcnt vmcnt(2)
	s_barrier
	global_load_lds_dwordx4 v[6:7], off
	v_lshl_add_u64 v[4:5], v[4:5], 0, s[10:11]
	s_add_i32 m0, s36, 0x1a000
	s_add_i32 s44, s36, 0x8000
	s_add_i32 s45, s36, 0xa000
	global_load_lds_dwordx4 v[4:5], off
	v_lshl_add_u64 v[0:1], v[0:1], 0, s[10:11]
	s_mov_b32 m0, s44
	s_add_u32 s14, s6, 0x40080
	global_load_lds_dwordx4 v[0:1], off
	v_lshl_add_u64 v[0:1], v[2:3], 0, s[10:11]
	s_mov_b32 m0, s45
	s_addc_u32 s15, s7, 0
	global_load_lds_dwordx4 v[0:1], off
	s_add_i32 m0, s36, 0x1c000
	s_nop 0
	global_load_lds_dwordx4 v212, s[14:15]
	s_add_i32 m0, s36, 0x1e000
	s_sext_i32_i8 s31, s12
	global_load_lds_dwordx4 v208, s[14:15]
	v_and_b32_e32 v1, 48, v9
	v_lshlrev_b32_e32 v3, 6, v9
	s_movk_i32 s12, 0x3c0
	v_ashrrev_i32_e32 v0, 6, v9
	v_and_or_b32 v1, v3, s12, v1
	v_lshlrev_b32_e32 v3, 2, v9
	v_lshl_add_u32 v2, v0, 10, s13
	v_and_b32_e32 v3, 32, v3
	v_add_lshl_u32 v0, v0, s16, 10
	v_bitop3_b32 v245, v1, v0, v3 bitop3:0xde
	v_lshlrev_b32_e32 v0, 14, v8
	v_and_b32_e32 v0, 0xffff8000, v0
	v_bitop3_b32 v2, v1, v2, v3 bitop3:0xde
	v_lshl_add_u32 v0, v10, 11, v0
	v_and_b32_e32 v1, 1, v8
	v_lshl_or_b32 v0, v1, 6, v0
	v_lshl_add_u32 v216, v11, 1, v0
	v_lshlrev_b32_e32 v0, 14, v12
	v_and_b32_e32 v0, 0xffff8000, v0
	s_waitcnt vmcnt(6)
	s_cmpk_lt_u32 s74, 0x100
	v_lshl_add_u32 v0, v13, 11, v0
	v_and_b32_e32 v1, 1, v12
	s_cselect_b64 s[12:13], -1, 0
	v_lshl_or_b32 v0, v1, 6, v0
	s_add_i32 s48, 0, 0x10000
	s_add_i32 s49, 0, 0x14000
	s_mov_b32 s46, 0x18000
	s_mov_b32 s47, 0x8000
	v_mov_b32_e32 v217, v213
	v_lshl_add_u32 v218, v14, 1, v0
	v_mov_b32_e32 v219, v213
	v_add_u32_e32 v246, s48, v245
	v_add_u32_e32 v247, s49, v245
	v_add_u32_e32 v248, 0, v2
	s_mov_b64 s[14:15], 0x102000
	s_mov_b32 s50, 0x102000
	s_mov_b64 s[16:17], 0x1000
	s_movk_i32 s51, 0x1000
	s_mov_b64 s[18:19], 0x101000
	s_mov_b32 s52, 0x101000
	s_mov_b32 s53, 0x21800000
	s_mov_b64 s[20:21], 0x1800000
	s_mov_b32 s54, 0x20000
	s_mov_b32 s55, 0x30000
	s_mov_b32 s56, 0x90000
	s_mov_b32 s57, 0xa0000
	s_mov_b32 s58, 0xb0000
	v_mov_b32_e32 v253, 0x5d800000
	s_mov_b64 s[26:27], s[6:7]
	s_mov_b64 s[24:25], s[4:5]
	s_barrier
	s_branch .LBB0_1516

.LBB0_1518:
	s_add_u32 s23, s6, 0x100
	s_addc_u32 s60, s7, 0
	s_add_u32 s4, s4, 0x40080
	v_mov_b32_e32 v0, 0
	s_addc_u32 s5, s5, 0
	s_mov_b32 s61, -2
	ds_read_b128 v[128:131], v246
	ds_read_b128 v[132:135], v246 offset:1024
	ds_read_b128 v[136:139], v246 offset:2048
	ds_read_b128 v[140:143], v246 offset:3072
	ds_read_b128 v[144:147], v247
	ds_read_b128 v[148:151], v247 offset:1024
	ds_read_b128 v[152:155], v247 offset:2048
	ds_read_b128 v[156:159], v247 offset:3072
	s_add_u32 s6, s4, 0xfffc0080
	s_addc_u32 s7, s5, -1
	s_cmp_eq_u32 s61, 12
	s_cselect_b32 s35, s25, s7
	s_cselect_b32 s34, s24, s6
	s_cselect_b32 s7, s27, s60
	s_cselect_b32 s6, s26, s23
	s_add_i32 m0, s36, 0xc000
	ds_read_b128 v[160:163], v248
	ds_read_b128 v[164:167], v248 offset:1024
	ds_read_b128 v[168:171], v248 offset:2048
	ds_read_b128 v[172:175], v248 offset:3072
	ds_read_b128 v[176:179], v248 offset:4096
	ds_read_b128 v[180:183], v248 offset:5120
	ds_read_b128 v[184:187], v248 offset:6144
	ds_read_b128 v[188:191], v248 offset:7168
	global_load_lds_dwordx4 v218, s[4:5]
	s_add_i32 m0, s36, 0xe000
	s_nop 0
	global_load_lds_dwordx4 v216, s[4:5]
	s_waitcnt vmcnt(8)
	s_waitcnt lgkmcnt(0)
	s_barrier
	s_waitcnt lgkmcnt(0)
	v_mfma_f32_16x16x32_bf16 v[124:127], v[128:131], v[160:163], 0
	v_mfma_f32_16x16x32_bf16 v[120:123], v[136:139], v[160:163], 0
	v_mfma_f32_16x16x32_bf16 v[112:115], v[128:131], v[168:171], 0
	v_mfma_f32_16x16x32_bf16 v[104:107], v[136:139], v[168:171], 0
	v_mfma_f32_16x16x32_bf16 v[96:99], v[128:131], v[176:179], 0
	v_mfma_f32_16x16x32_bf16 v[88:91], v[136:139], v[176:179], 0
	v_mfma_f32_16x16x32_bf16 v[80:83], v[128:131], v[184:187], 0
	v_mfma_f32_16x16x32_bf16 v[72:75], v[136:139], v[184:187], 0
	v_mfma_f32_16x16x32_bf16 v[124:127], v[132:135], v[164:167], v[124:127]
	v_mfma_f32_16x16x32_bf16 v[120:123], v[140:143], v[164:167], v[120:123]
	v_mfma_f32_16x16x32_bf16 v[112:115], v[132:135], v[172:175], v[112:115]
	v_mfma_f32_16x16x32_bf16 v[104:107], v[140:143], v[172:175], v[104:107]
	v_mfma_f32_16x16x32_bf16 v[96:99], v[132:135], v[180:183], v[96:99]
	v_mfma_f32_16x16x32_bf16 v[88:91], v[140:143], v[180:183], v[88:91]
	v_mfma_f32_16x16x32_bf16 v[80:83], v[132:135], v[188:191], v[80:83]
	v_mfma_f32_16x16x32_bf16 v[72:75], v[140:143], v[188:191], v[72:75]
	v_mfma_f32_16x16x32_bf16 v[116:119], v[144:147], v[160:163], 0
	v_mfma_f32_16x16x32_bf16 v[108:111], v[152:155], v[160:163], 0
	v_mfma_f32_16x16x32_bf16 v[100:103], v[144:147], v[168:171], 0
	v_mfma_f32_16x16x32_bf16 v[92:95], v[152:155], v[168:171], 0
	v_mfma_f32_16x16x32_bf16 v[84:87], v[144:147], v[176:179], 0
	v_mfma_f32_16x16x32_bf16 v[76:79], v[152:155], v[176:179], 0
	v_mfma_f32_16x16x32_bf16 v[68:71], v[144:147], v[184:187], 0
	v_mfma_f32_16x16x32_bf16 v[64:67], v[152:155], v[184:187], 0
	v_mfma_f32_16x16x32_bf16 v[116:119], v[148:151], v[164:167], v[116:119]
	v_mfma_f32_16x16x32_bf16 v[108:111], v[156:159], v[164:167], v[108:111]
	v_mfma_f32_16x16x32_bf16 v[100:103], v[148:151], v[172:175], v[100:103]
	v_mfma_f32_16x16x32_bf16 v[92:95], v[156:159], v[172:175], v[92:95]
	v_mfma_f32_16x16x32_bf16 v[84:87], v[148:151], v[180:183], v[84:87]
	v_mfma_f32_16x16x32_bf16 v[76:79], v[156:159], v[180:183], v[76:79]
	v_mfma_f32_16x16x32_bf16 v[68:71], v[148:151], v[188:191], v[68:71]
	v_mfma_f32_16x16x32_bf16 v[64:67], v[156:159], v[188:191], v[64:67]
	s_barrier
	s_add_i32 s62, s48, s3
	v_lshl_add_u64 v[192:193], s[6:7], 0, v[212:213]
	s_mov_b32 m0, s62
	ds_read_b128 v[160:163], v248 offset:16384
	ds_read_b128 v[164:167], v248 offset:17408
	ds_read_b128 v[168:171], v248 offset:18432
	ds_read_b128 v[172:175], v248 offset:19456
	ds_read_b128 v[176:179], v248 offset:20480
	ds_read_b128 v[180:183], v248 offset:21504
	ds_read_b128 v[184:187], v248 offset:22528
	ds_read_b128 v[188:191], v248 offset:23552
	global_load_lds_dwordx4 v[192:193], off
	s_add_i32 m0, s62, 0x2000
	s_add_u32 s62, s6, 0x40000
	v_lshl_add_u64 v[194:195], s[6:7], 0, v[208:209]
	s_addc_u32 s63, s7, 0
	s_add_i32 s64, s49, s3
	global_load_lds_dwordx4 v[194:195], off
	s_mov_b32 m0, s64
	v_lshl_add_u64 v[198:199], s[34:35], 0, v[210:211]
	global_load_lds_dwordx4 v212, s[62:63]
	s_add_i32 m0, s64, 0x2000
	s_nop 0
	global_load_lds_dwordx4 v208, s[62:63]
	v_lshl_add_u64 v[196:197], s[34:35], 0, v[214:215]
	s_mov_b32 m0, s36
	s_nop 0
	global_load_lds_dwordx4 v[196:197], off
	s_mov_b32 m0, s37
	s_nop 0
	global_load_lds_dwordx4 v[198:199], off
	s_waitcnt vmcnt(8)
	s_waitcnt lgkmcnt(0)
	s_barrier
	s_waitcnt lgkmcnt(0)
	v_mfma_f32_16x16x32_bf16 v[60:63], v[128:131], v[160:163], 0
	v_mfma_f32_16x16x32_bf16 v[56:59], v[136:139], v[160:163], 0
	v_mfma_f32_16x16x32_bf16 v[48:51], v[128:131], v[168:171], 0
	v_mfma_f32_16x16x32_bf16 v[40:43], v[136:139], v[168:171], 0
	v_mfma_f32_16x16x32_bf16 v[32:35], v[128:131], v[176:179], 0
	v_mfma_f32_16x16x32_bf16 v[24:27], v[136:139], v[176:179], 0
	v_mfma_f32_16x16x32_bf16 v[16:19], v[128:131], v[184:187], 0
	v_mfma_f32_16x16x32_bf16 v[8:11], v[136:139], v[184:187], 0
	v_mfma_f32_16x16x32_bf16 v[60:63], v[132:135], v[164:167], v[60:63]
	v_mfma_f32_16x16x32_bf16 v[56:59], v[140:143], v[164:167], v[56:59]
	v_mfma_f32_16x16x32_bf16 v[48:51], v[132:135], v[172:175], v[48:51]
	v_mfma_f32_16x16x32_bf16 v[40:43], v[140:143], v[172:175], v[40:43]
	v_mfma_f32_16x16x32_bf16 v[32:35], v[132:135], v[180:183], v[32:35]
	v_mfma_f32_16x16x32_bf16 v[24:27], v[140:143], v[180:183], v[24:27]
	v_mfma_f32_16x16x32_bf16 v[16:19], v[132:135], v[188:191], v[16:19]
	v_mfma_f32_16x16x32_bf16 v[8:11], v[140:143], v[188:191], v[8:11]
	v_mfma_f32_16x16x32_bf16 v[52:55], v[144:147], v[160:163], 0
	v_mfma_f32_16x16x32_bf16 v[44:47], v[152:155], v[160:163], 0
	v_mfma_f32_16x16x32_bf16 v[36:39], v[144:147], v[168:171], 0
	v_mfma_f32_16x16x32_bf16 v[28:31], v[152:155], v[168:171], 0
	v_mfma_f32_16x16x32_bf16 v[20:23], v[144:147], v[176:179], 0
	v_mfma_f32_16x16x32_bf16 v[12:15], v[152:155], v[176:179], 0
	v_mfma_f32_16x16x32_bf16 v[4:7], v[144:147], v[184:187], 0
	v_mfma_f32_16x16x32_bf16 v[0:3], v[152:155], v[184:187], 0
	v_mfma_f32_16x16x32_bf16 v[52:55], v[148:151], v[164:167], v[52:55]
	v_mfma_f32_16x16x32_bf16 v[44:47], v[156:159], v[164:167], v[44:47]
	v_mfma_f32_16x16x32_bf16 v[36:39], v[148:151], v[172:175], v[36:39]
	v_mfma_f32_16x16x32_bf16 v[28:31], v[156:159], v[172:175], v[28:31]
	v_mfma_f32_16x16x32_bf16 v[20:23], v[148:151], v[180:183], v[20:23]
	v_mfma_f32_16x16x32_bf16 v[12:15], v[156:159], v[180:183], v[12:15]
	v_mfma_f32_16x16x32_bf16 v[4:7], v[148:151], v[188:191], v[4:7]
	v_mfma_f32_16x16x32_bf16 v[0:3], v[156:159], v[188:191], v[0:3]
	s_barrier
	s_add_i32 s62, 0, 0x18000
	s_add_i32 s63, 0, 0x1c000
	v_add_u32_e32 v140, s62, v245
	v_add_u32_e32 v156, s63, v245
	ds_read_b128 v[128:131], v140
	ds_read_b128 v[132:135], v140 offset:1024
	ds_read_b128 v[136:139], v140 offset:2048
	ds_read_b128 v[140:143], v140 offset:3072
	ds_read_b128 v[144:147], v156
	ds_read_b128 v[148:151], v156 offset:1024
	ds_read_b128 v[152:155], v156 offset:2048
	ds_read_b128 v[156:159], v156 offset:3072
	s_add_u32 s34, s34, 0x40000
	s_addc_u32 s35, s35, 0
	s_mov_b32 m0, s38
	ds_read_b128 v[160:163], v248 offset:32768
	ds_read_b128 v[164:167], v248 offset:33792
	ds_read_b128 v[168:171], v248 offset:34816
	ds_read_b128 v[172:175], v248 offset:35840
	ds_read_b128 v[176:179], v248 offset:36864
	ds_read_b128 v[180:183], v248 offset:37888
	ds_read_b128 v[184:187], v248 offset:38912
	ds_read_b128 v[188:191], v248 offset:39936
	global_load_lds_dwordx4 v214, s[34:35]
	s_mov_b32 m0, s39
	s_nop 0
	global_load_lds_dwordx4 v210, s[34:35]
	s_waitcnt vmcnt(8)
	s_waitcnt lgkmcnt(0)
	s_barrier
	s_waitcnt lgkmcnt(0)
	v_mfma_f32_16x16x32_bf16 v[124:127], v[128:131], v[160:163], v[124:127]
	v_mfma_f32_16x16x32_bf16 v[120:123], v[136:139], v[160:163], v[120:123]
	v_mfma_f32_16x16x32_bf16 v[112:115], v[128:131], v[168:171], v[112:115]
	v_mfma_f32_16x16x32_bf16 v[104:107], v[136:139], v[168:171], v[104:107]
	v_mfma_f32_16x16x32_bf16 v[96:99], v[128:131], v[176:179], v[96:99]
	v_mfma_f32_16x16x32_bf16 v[88:91], v[136:139], v[176:179], v[88:91]
	v_mfma_f32_16x16x32_bf16 v[80:83], v[128:131], v[184:187], v[80:83]
	v_mfma_f32_16x16x32_bf16 v[72:75], v[136:139], v[184:187], v[72:75]
	v_mfma_f32_16x16x32_bf16 v[124:127], v[132:135], v[164:167], v[124:127]
	v_mfma_f32_16x16x32_bf16 v[120:123], v[140:143], v[164:167], v[120:123]
	v_mfma_f32_16x16x32_bf16 v[112:115], v[132:135], v[172:175], v[112:115]
	v_mfma_f32_16x16x32_bf16 v[104:107], v[140:143], v[172:175], v[104:107]
	v_mfma_f32_16x16x32_bf16 v[96:99], v[132:135], v[180:183], v[96:99]
	v_mfma_f32_16x16x32_bf16 v[88:91], v[140:143], v[180:183], v[88:91]
	v_mfma_f32_16x16x32_bf16 v[80:83], v[132:135], v[188:191], v[80:83]
	v_mfma_f32_16x16x32_bf16 v[72:75], v[140:143], v[188:191], v[72:75]
	v_mfma_f32_16x16x32_bf16 v[116:119], v[144:147], v[160:163], v[116:119]
	v_mfma_f32_16x16x32_bf16 v[108:111], v[152:155], v[160:163], v[108:111]
	v_mfma_f32_16x16x32_bf16 v[100:103], v[144:147], v[168:171], v[100:103]
	v_mfma_f32_16x16x32_bf16 v[92:95], v[152:155], v[168:171], v[92:95]
	v_mfma_f32_16x16x32_bf16 v[84:87], v[144:147], v[176:179], v[84:87]
	v_mfma_f32_16x16x32_bf16 v[76:79], v[152:155], v[176:179], v[76:79]
	v_mfma_f32_16x16x32_bf16 v[68:71], v[144:147], v[184:187], v[68:71]
	v_mfma_f32_16x16x32_bf16 v[64:67], v[152:155], v[184:187], v[64:67]
	v_mfma_f32_16x16x32_bf16 v[116:119], v[148:151], v[164:167], v[116:119]
	v_mfma_f32_16x16x32_bf16 v[108:111], v[156:159], v[164:167], v[108:111]
	v_mfma_f32_16x16x32_bf16 v[100:103], v[148:151], v[172:175], v[100:103]
	v_mfma_f32_16x16x32_bf16 v[92:95], v[156:159], v[172:175], v[92:95]
	v_mfma_f32_16x16x32_bf16 v[84:87], v[148:151], v[180:183], v[84:87]
	v_mfma_f32_16x16x32_bf16 v[76:79], v[156:159], v[180:183], v[76:79]
	v_mfma_f32_16x16x32_bf16 v[68:71], v[148:151], v[188:191], v[68:71]
	v_mfma_f32_16x16x32_bf16 v[64:67], v[156:159], v[188:191], v[64:67]
	s_barrier
	s_add_i32 s34, s62, s3
	v_lshl_add_u64 v[192:193], v[192:193], 0, s[10:11]
	s_mov_b32 m0, s34
	ds_read_b128 v[160:163], v248 offset:49152
	ds_read_b128 v[164:167], v248 offset:50176
	ds_read_b128 v[168:171], v248 offset:51200
	ds_read_b128 v[172:175], v248 offset:52224
	ds_read_b128 v[176:179], v248 offset:53248
	ds_read_b128 v[180:183], v248 offset:54272
	ds_read_b128 v[184:187], v248 offset:55296
	ds_read_b128 v[188:191], v248 offset:56320
	global_load_lds_dwordx4 v[192:193], off
	s_add_i32 m0, s34, 0x2000
	s_add_u32 s6, s6, 0x40080
	v_lshl_add_u64 v[192:193], v[194:195], 0, s[10:11]
	s_addc_u32 s7, s7, 0
	s_add_i32 s34, s63, s3
	global_load_lds_dwordx4 v[192:193], off
	s_mov_b32 m0, s34
	s_nop 0
	global_load_lds_dwordx4 v212, s[6:7]
	s_add_i32 m0, s34, 0x2000
	s_nop 0
	global_load_lds_dwordx4 v208, s[6:7]
	v_lshl_add_u64 v[192:193], v[196:197], 0, s[10:11]
	s_mov_b32 m0, s44
	s_nop 0
	global_load_lds_dwordx4 v[192:193], off
	v_lshl_add_u64 v[192:193], v[198:199], 0, s[10:11]
	s_mov_b32 m0, s45
	s_nop 0
	global_load_lds_dwordx4 v[192:193], off
	s_waitcnt vmcnt(8)
	s_waitcnt lgkmcnt(0)
	s_barrier
	s_waitcnt lgkmcnt(0)
	v_mfma_f32_16x16x32_bf16 v[60:63], v[128:131], v[160:163], v[60:63]
	v_mfma_f32_16x16x32_bf16 v[56:59], v[136:139], v[160:163], v[56:59]
	v_mfma_f32_16x16x32_bf16 v[48:51], v[128:131], v[168:171], v[48:51]
	v_mfma_f32_16x16x32_bf16 v[40:43], v[136:139], v[168:171], v[40:43]
	v_mfma_f32_16x16x32_bf16 v[32:35], v[128:131], v[176:179], v[32:35]
	v_mfma_f32_16x16x32_bf16 v[24:27], v[136:139], v[176:179], v[24:27]
	v_mfma_f32_16x16x32_bf16 v[16:19], v[128:131], v[184:187], v[16:19]
	v_mfma_f32_16x16x32_bf16 v[8:11], v[136:139], v[184:187], v[8:11]
	v_mfma_f32_16x16x32_bf16 v[60:63], v[132:135], v[164:167], v[60:63]
	v_mfma_f32_16x16x32_bf16 v[56:59], v[140:143], v[164:167], v[56:59]
	v_mfma_f32_16x16x32_bf16 v[48:51], v[132:135], v[172:175], v[48:51]
	v_mfma_f32_16x16x32_bf16 v[40:43], v[140:143], v[172:175], v[40:43]
	v_mfma_f32_16x16x32_bf16 v[32:35], v[132:135], v[180:183], v[32:35]
	v_mfma_f32_16x16x32_bf16 v[24:27], v[140:143], v[180:183], v[24:27]
	v_mfma_f32_16x16x32_bf16 v[16:19], v[132:135], v[188:191], v[16:19]
	v_mfma_f32_16x16x32_bf16 v[8:11], v[140:143], v[188:191], v[8:11]
	v_mfma_f32_16x16x32_bf16 v[52:55], v[144:147], v[160:163], v[52:55]
	v_mfma_f32_16x16x32_bf16 v[44:47], v[152:155], v[160:163], v[44:47]
	v_mfma_f32_16x16x32_bf16 v[36:39], v[144:147], v[168:171], v[36:39]
	v_mfma_f32_16x16x32_bf16 v[28:31], v[152:155], v[168:171], v[28:31]
	v_mfma_f32_16x16x32_bf16 v[20:23], v[144:147], v[176:179], v[20:23]
	v_mfma_f32_16x16x32_bf16 v[12:15], v[152:155], v[176:179], v[12:15]
	v_mfma_f32_16x16x32_bf16 v[4:7], v[144:147], v[184:187], v[4:7]
	v_mfma_f32_16x16x32_bf16 v[0:3], v[152:155], v[184:187], v[0:3]
	v_mfma_f32_16x16x32_bf16 v[52:55], v[148:151], v[164:167], v[52:55]
	v_mfma_f32_16x16x32_bf16 v[44:47], v[156:159], v[164:167], v[44:47]
	v_mfma_f32_16x16x32_bf16 v[36:39], v[148:151], v[172:175], v[36:39]
	v_mfma_f32_16x16x32_bf16 v[28:31], v[156:159], v[172:175], v[28:31]
	v_mfma_f32_16x16x32_bf16 v[20:23], v[148:151], v[180:183], v[20:23]
	v_mfma_f32_16x16x32_bf16 v[12:15], v[156:159], v[180:183], v[12:15]
	v_mfma_f32_16x16x32_bf16 v[4:7], v[148:151], v[188:191], v[4:7]
	v_mfma_f32_16x16x32_bf16 v[0:3], v[156:159], v[188:191], v[0:3]
	s_barrier
	s_add_i32 s61, s61, 2
	s_add_u32 s23, s23, 0x100
	s_addc_u32 s60, s60, 0
	s_add_u32 s4, s4, 0x100
	s_addc_u32 s5, s5, 0
.LBB0_1519:
	ds_read_b128 v[128:131], v246
	ds_read_b128 v[132:135], v246 offset:1024
	ds_read_b128 v[136:139], v246 offset:2048
	ds_read_b128 v[140:143], v246 offset:3072
	ds_read_b128 v[144:147], v247
	ds_read_b128 v[148:151], v247 offset:1024
	ds_read_b128 v[152:155], v247 offset:2048
	ds_read_b128 v[156:159], v247 offset:3072
	s_add_u32 s6, s4, 0xfffc0080
	s_addc_u32 s7, s5, -1
	s_cmp_eq_u32 s61, 12
	s_cselect_b32 s35, s25, s7
	s_cselect_b32 s34, s24, s6
	s_cselect_b32 s7, s27, s60
	s_cselect_b32 s6, s26, s23
	s_add_i32 m0, s36, 0xc000
	ds_read_b128 v[160:163], v248
	ds_read_b128 v[164:167], v248 offset:1024
	ds_read_b128 v[168:171], v248 offset:2048
	ds_read_b128 v[172:175], v248 offset:3072
	ds_read_b128 v[176:179], v248 offset:4096
	ds_read_b128 v[180:183], v248 offset:5120
	ds_read_b128 v[184:187], v248 offset:6144
	ds_read_b128 v[188:191], v248 offset:7168
	global_load_lds_dwordx4 v218, s[4:5]
	s_add_i32 m0, s36, 0xe000
	s_nop 0
	global_load_lds_dwordx4 v216, s[4:5]
	s_waitcnt vmcnt(8)
	s_waitcnt lgkmcnt(0)
	s_barrier
	s_waitcnt lgkmcnt(0)
	v_mfma_f32_16x16x32_bf16 v[124:127], v[128:131], v[160:163], v[124:127]
	v_mfma_f32_16x16x32_bf16 v[120:123], v[136:139], v[160:163], v[120:123]
	v_mfma_f32_16x16x32_bf16 v[112:115], v[128:131], v[168:171], v[112:115]
	v_mfma_f32_16x16x32_bf16 v[104:107], v[136:139], v[168:171], v[104:107]
	v_mfma_f32_16x16x32_bf16 v[96:99], v[128:131], v[176:179], v[96:99]
	v_mfma_f32_16x16x32_bf16 v[88:91], v[136:139], v[176:179], v[88:91]
	v_mfma_f32_16x16x32_bf16 v[80:83], v[128:131], v[184:187], v[80:83]
	v_mfma_f32_16x16x32_bf16 v[72:75], v[136:139], v[184:187], v[72:75]
	v_mfma_f32_16x16x32_bf16 v[124:127], v[132:135], v[164:167], v[124:127]
	v_mfma_f32_16x16x32_bf16 v[120:123], v[140:143], v[164:167], v[120:123]
	v_mfma_f32_16x16x32_bf16 v[112:115], v[132:135], v[172:175], v[112:115]
	v_mfma_f32_16x16x32_bf16 v[104:107], v[140:143], v[172:175], v[104:107]
	v_mfma_f32_16x16x32_bf16 v[96:99], v[132:135], v[180:183], v[96:99]
	v_mfma_f32_16x16x32_bf16 v[88:91], v[140:143], v[180:183], v[88:91]
	v_mfma_f32_16x16x32_bf16 v[80:83], v[132:135], v[188:191], v[80:83]
	v_mfma_f32_16x16x32_bf16 v[72:75], v[140:143], v[188:191], v[72:75]
	v_mfma_f32_16x16x32_bf16 v[116:119], v[144:147], v[160:163], v[116:119]
	v_mfma_f32_16x16x32_bf16 v[108:111], v[152:155], v[160:163], v[108:111]
	v_mfma_f32_16x16x32_bf16 v[100:103], v[144:147], v[168:171], v[100:103]
	v_mfma_f32_16x16x32_bf16 v[92:95], v[152:155], v[168:171], v[92:95]
	v_mfma_f32_16x16x32_bf16 v[84:87], v[144:147], v[176:179], v[84:87]
	v_mfma_f32_16x16x32_bf16 v[76:79], v[152:155], v[176:179], v[76:79]
	v_mfma_f32_16x16x32_bf16 v[68:71], v[144:147], v[184:187], v[68:71]
	v_mfma_f32_16x16x32_bf16 v[64:67], v[152:155], v[184:187], v[64:67]
	v_mfma_f32_16x16x32_bf16 v[116:119], v[148:151], v[164:167], v[116:119]
	v_mfma_f32_16x16x32_bf16 v[108:111], v[156:159], v[164:167], v[108:111]
	v_mfma_f32_16x16x32_bf16 v[100:103], v[148:151], v[172:175], v[100:103]
	v_mfma_f32_16x16x32_bf16 v[92:95], v[156:159], v[172:175], v[92:95]
	v_mfma_f32_16x16x32_bf16 v[84:87], v[148:151], v[180:183], v[84:87]
	v_mfma_f32_16x16x32_bf16 v[76:79], v[156:159], v[180:183], v[76:79]
	v_mfma_f32_16x16x32_bf16 v[68:71], v[148:151], v[188:191], v[68:71]
	v_mfma_f32_16x16x32_bf16 v[64:67], v[156:159], v[188:191], v[64:67]
	s_barrier
	s_add_i32 s62, s48, s3
	v_lshl_add_u64 v[192:193], s[6:7], 0, v[212:213]
	s_mov_b32 m0, s62
	ds_read_b128 v[160:163], v248 offset:16384
	ds_read_b128 v[164:167], v248 offset:17408
	ds_read_b128 v[168:171], v248 offset:18432
	ds_read_b128 v[172:175], v248 offset:19456
	ds_read_b128 v[176:179], v248 offset:20480
	ds_read_b128 v[180:183], v248 offset:21504
	ds_read_b128 v[184:187], v248 offset:22528
	ds_read_b128 v[188:191], v248 offset:23552
	global_load_lds_dwordx4 v[192:193], off
	s_add_i32 m0, s62, 0x2000
	s_add_u32 s62, s6, 0x40000
	v_lshl_add_u64 v[194:195], s[6:7], 0, v[208:209]
	s_addc_u32 s63, s7, 0
	s_add_i32 s64, s49, s3
	global_load_lds_dwordx4 v[194:195], off
	s_mov_b32 m0, s64
	v_lshl_add_u64 v[198:199], s[34:35], 0, v[210:211]
	global_load_lds_dwordx4 v212, s[62:63]
	s_add_i32 m0, s64, 0x2000
	s_nop 0
	global_load_lds_dwordx4 v208, s[62:63]
	v_lshl_add_u64 v[196:197], s[34:35], 0, v[214:215]
	s_mov_b32 m0, s36
	s_nop 0
	global_load_lds_dwordx4 v[196:197], off
	s_mov_b32 m0, s37
	s_nop 0
	global_load_lds_dwordx4 v[198:199], off
	s_waitcnt vmcnt(8)
	s_waitcnt lgkmcnt(0)
	s_barrier
	s_waitcnt lgkmcnt(0)
	v_mfma_f32_16x16x32_bf16 v[60:63], v[128:131], v[160:163], v[60:63]
	v_mfma_f32_16x16x32_bf16 v[56:59], v[136:139], v[160:163], v[56:59]
	v_mfma_f32_16x16x32_bf16 v[48:51], v[128:131], v[168:171], v[48:51]
	v_mfma_f32_16x16x32_bf16 v[40:43], v[136:139], v[168:171], v[40:43]
	v_mfma_f32_16x16x32_bf16 v[32:35], v[128:131], v[176:179], v[32:35]
	v_mfma_f32_16x16x32_bf16 v[24:27], v[136:139], v[176:179], v[24:27]
	v_mfma_f32_16x16x32_bf16 v[16:19], v[128:131], v[184:187], v[16:19]
	v_mfma_f32_16x16x32_bf16 v[8:11], v[136:139], v[184:187], v[8:11]
	v_mfma_f32_16x16x32_bf16 v[60:63], v[132:135], v[164:167], v[60:63]
	v_mfma_f32_16x16x32_bf16 v[56:59], v[140:143], v[164:167], v[56:59]
	v_mfma_f32_16x16x32_bf16 v[48:51], v[132:135], v[172:175], v[48:51]
	v_mfma_f32_16x16x32_bf16 v[40:43], v[140:143], v[172:175], v[40:43]
	v_mfma_f32_16x16x32_bf16 v[32:35], v[132:135], v[180:183], v[32:35]
	v_mfma_f32_16x16x32_bf16 v[24:27], v[140:143], v[180:183], v[24:27]
	v_mfma_f32_16x16x32_bf16 v[16:19], v[132:135], v[188:191], v[16:19]
	v_mfma_f32_16x16x32_bf16 v[8:11], v[140:143], v[188:191], v[8:11]
	v_mfma_f32_16x16x32_bf16 v[52:55], v[144:147], v[160:163], v[52:55]
	v_mfma_f32_16x16x32_bf16 v[44:47], v[152:155], v[160:163], v[44:47]
	v_mfma_f32_16x16x32_bf16 v[36:39], v[144:147], v[168:171], v[36:39]
	v_mfma_f32_16x16x32_bf16 v[28:31], v[152:155], v[168:171], v[28:31]
	v_mfma_f32_16x16x32_bf16 v[20:23], v[144:147], v[176:179], v[20:23]
	v_mfma_f32_16x16x32_bf16 v[12:15], v[152:155], v[176:179], v[12:15]
	v_mfma_f32_16x16x32_bf16 v[4:7], v[144:147], v[184:187], v[4:7]
	v_mfma_f32_16x16x32_bf16 v[0:3], v[152:155], v[184:187], v[0:3]
	v_mfma_f32_16x16x32_bf16 v[52:55], v[148:151], v[164:167], v[52:55]
	v_mfma_f32_16x16x32_bf16 v[44:47], v[156:159], v[164:167], v[44:47]
	v_mfma_f32_16x16x32_bf16 v[36:39], v[148:151], v[172:175], v[36:39]
	v_mfma_f32_16x16x32_bf16 v[28:31], v[156:159], v[172:175], v[28:31]
	v_mfma_f32_16x16x32_bf16 v[20:23], v[148:151], v[180:183], v[20:23]
	v_mfma_f32_16x16x32_bf16 v[12:15], v[156:159], v[180:183], v[12:15]
	v_mfma_f32_16x16x32_bf16 v[4:7], v[148:151], v[188:191], v[4:7]
	v_mfma_f32_16x16x32_bf16 v[0:3], v[156:159], v[188:191], v[0:3]
	s_barrier
	s_add_i32 s62, 0, 0x18000
	s_add_i32 s63, 0, 0x1c000
	v_add_u32_e32 v140, s62, v245
	v_add_u32_e32 v156, s63, v245
	ds_read_b128 v[128:131], v140
	ds_read_b128 v[132:135], v140 offset:1024
	ds_read_b128 v[136:139], v140 offset:2048
	ds_read_b128 v[140:143], v140 offset:3072
	ds_read_b128 v[144:147], v156
	ds_read_b128 v[148:151], v156 offset:1024
	ds_read_b128 v[152:155], v156 offset:2048
	ds_read_b128 v[156:159], v156 offset:3072
	s_add_u32 s34, s34, 0x40000
	s_addc_u32 s35, s35, 0
	s_mov_b32 m0, s38
	ds_read_b128 v[160:163], v248 offset:32768
	ds_read_b128 v[164:167], v248 offset:33792
	ds_read_b128 v[168:171], v248 offset:34816
	ds_read_b128 v[172:175], v248 offset:35840
	ds_read_b128 v[176:179], v248 offset:36864
	ds_read_b128 v[180:183], v248 offset:37888
	ds_read_b128 v[184:187], v248 offset:38912
	ds_read_b128 v[188:191], v248 offset:39936
	global_load_lds_dwordx4 v214, s[34:35]
	s_mov_b32 m0, s39
	s_nop 0
	global_load_lds_dwordx4 v210, s[34:35]
	s_waitcnt vmcnt(8)
	s_waitcnt lgkmcnt(0)
	s_barrier
	s_waitcnt lgkmcnt(0)
	v_mfma_f32_16x16x32_bf16 v[124:127], v[128:131], v[160:163], v[124:127]
	v_mfma_f32_16x16x32_bf16 v[120:123], v[136:139], v[160:163], v[120:123]
	v_mfma_f32_16x16x32_bf16 v[112:115], v[128:131], v[168:171], v[112:115]
	v_mfma_f32_16x16x32_bf16 v[104:107], v[136:139], v[168:171], v[104:107]
	v_mfma_f32_16x16x32_bf16 v[96:99], v[128:131], v[176:179], v[96:99]
	v_mfma_f32_16x16x32_bf16 v[88:91], v[136:139], v[176:179], v[88:91]
	v_mfma_f32_16x16x32_bf16 v[80:83], v[128:131], v[184:187], v[80:83]
	v_mfma_f32_16x16x32_bf16 v[72:75], v[136:139], v[184:187], v[72:75]
	v_mfma_f32_16x16x32_bf16 v[124:127], v[132:135], v[164:167], v[124:127]
	v_mfma_f32_16x16x32_bf16 v[120:123], v[140:143], v[164:167], v[120:123]
	v_mfma_f32_16x16x32_bf16 v[112:115], v[132:135], v[172:175], v[112:115]
	v_mfma_f32_16x16x32_bf16 v[104:107], v[140:143], v[172:175], v[104:107]
	v_mfma_f32_16x16x32_bf16 v[96:99], v[132:135], v[180:183], v[96:99]
	v_mfma_f32_16x16x32_bf16 v[88:91], v[140:143], v[180:183], v[88:91]
	v_mfma_f32_16x16x32_bf16 v[80:83], v[132:135], v[188:191], v[80:83]
	v_mfma_f32_16x16x32_bf16 v[72:75], v[140:143], v[188:191], v[72:75]
	v_mfma_f32_16x16x32_bf16 v[116:119], v[144:147], v[160:163], v[116:119]
	v_mfma_f32_16x16x32_bf16 v[108:111], v[152:155], v[160:163], v[108:111]
	v_mfma_f32_16x16x32_bf16 v[100:103], v[144:147], v[168:171], v[100:103]
	v_mfma_f32_16x16x32_bf16 v[92:95], v[152:155], v[168:171], v[92:95]
	v_mfma_f32_16x16x32_bf16 v[84:87], v[144:147], v[176:179], v[84:87]
	v_mfma_f32_16x16x32_bf16 v[76:79], v[152:155], v[176:179], v[76:79]
	v_mfma_f32_16x16x32_bf16 v[68:71], v[144:147], v[184:187], v[68:71]
	v_mfma_f32_16x16x32_bf16 v[64:67], v[152:155], v[184:187], v[64:67]
	v_mfma_f32_16x16x32_bf16 v[116:119], v[148:151], v[164:167], v[116:119]
	v_mfma_f32_16x16x32_bf16 v[108:111], v[156:159], v[164:167], v[108:111]
	v_mfma_f32_16x16x32_bf16 v[100:103], v[148:151], v[172:175], v[100:103]
	v_mfma_f32_16x16x32_bf16 v[92:95], v[156:159], v[172:175], v[92:95]
	v_mfma_f32_16x16x32_bf16 v[84:87], v[148:151], v[180:183], v[84:87]
	v_mfma_f32_16x16x32_bf16 v[76:79], v[156:159], v[180:183], v[76:79]
	v_mfma_f32_16x16x32_bf16 v[68:71], v[148:151], v[188:191], v[68:71]
	v_mfma_f32_16x16x32_bf16 v[64:67], v[156:159], v[188:191], v[64:67]
	s_barrier
	s_add_i32 s34, s62, s3
	v_lshl_add_u64 v[192:193], v[192:193], 0, s[10:11]
	s_mov_b32 m0, s34
	ds_read_b128 v[160:163], v248 offset:49152
	ds_read_b128 v[164:167], v248 offset:50176
	ds_read_b128 v[168:171], v248 offset:51200
	ds_read_b128 v[172:175], v248 offset:52224
	ds_read_b128 v[176:179], v248 offset:53248
	ds_read_b128 v[180:183], v248 offset:54272
	ds_read_b128 v[184:187], v248 offset:55296
	ds_read_b128 v[188:191], v248 offset:56320
	global_load_lds_dwordx4 v[192:193], off
	s_add_i32 m0, s34, 0x2000
	s_add_u32 s6, s6, 0x40080
	v_lshl_add_u64 v[192:193], v[194:195], 0, s[10:11]
	s_addc_u32 s7, s7, 0
	s_add_i32 s34, s63, s3
	global_load_lds_dwordx4 v[192:193], off
	s_mov_b32 m0, s34
	s_nop 0
	global_load_lds_dwordx4 v212, s[6:7]
	s_add_i32 m0, s34, 0x2000
	s_nop 0
	global_load_lds_dwordx4 v208, s[6:7]
	v_lshl_add_u64 v[192:193], v[196:197], 0, s[10:11]
	s_mov_b32 m0, s44
	s_nop 0
	global_load_lds_dwordx4 v[192:193], off
	v_lshl_add_u64 v[192:193], v[198:199], 0, s[10:11]
	s_mov_b32 m0, s45
	s_nop 0
	global_load_lds_dwordx4 v[192:193], off
	s_waitcnt vmcnt(8)
	s_waitcnt lgkmcnt(0)
	s_barrier
	s_waitcnt lgkmcnt(0)
	v_mfma_f32_16x16x32_bf16 v[60:63], v[128:131], v[160:163], v[60:63]
	v_mfma_f32_16x16x32_bf16 v[56:59], v[136:139], v[160:163], v[56:59]
	v_mfma_f32_16x16x32_bf16 v[48:51], v[128:131], v[168:171], v[48:51]
	v_mfma_f32_16x16x32_bf16 v[40:43], v[136:139], v[168:171], v[40:43]
	v_mfma_f32_16x16x32_bf16 v[32:35], v[128:131], v[176:179], v[32:35]
	v_mfma_f32_16x16x32_bf16 v[24:27], v[136:139], v[176:179], v[24:27]
	v_mfma_f32_16x16x32_bf16 v[16:19], v[128:131], v[184:187], v[16:19]
	v_mfma_f32_16x16x32_bf16 v[8:11], v[136:139], v[184:187], v[8:11]
	v_mfma_f32_16x16x32_bf16 v[60:63], v[132:135], v[164:167], v[60:63]
	v_mfma_f32_16x16x32_bf16 v[56:59], v[140:143], v[164:167], v[56:59]
	v_mfma_f32_16x16x32_bf16 v[48:51], v[132:135], v[172:175], v[48:51]
	v_mfma_f32_16x16x32_bf16 v[40:43], v[140:143], v[172:175], v[40:43]
	v_mfma_f32_16x16x32_bf16 v[32:35], v[132:135], v[180:183], v[32:35]
	v_mfma_f32_16x16x32_bf16 v[24:27], v[140:143], v[180:183], v[24:27]
	v_mfma_f32_16x16x32_bf16 v[16:19], v[132:135], v[188:191], v[16:19]
	v_mfma_f32_16x16x32_bf16 v[8:11], v[140:143], v[188:191], v[8:11]
	v_mfma_f32_16x16x32_bf16 v[52:55], v[144:147], v[160:163], v[52:55]
	v_mfma_f32_16x16x32_bf16 v[44:47], v[152:155], v[160:163], v[44:47]
	v_mfma_f32_16x16x32_bf16 v[36:39], v[144:147], v[168:171], v[36:39]
	v_mfma_f32_16x16x32_bf16 v[28:31], v[152:155], v[168:171], v[28:31]
	v_mfma_f32_16x16x32_bf16 v[20:23], v[144:147], v[176:179], v[20:23]
	v_mfma_f32_16x16x32_bf16 v[12:15], v[152:155], v[176:179], v[12:15]
	v_mfma_f32_16x16x32_bf16 v[4:7], v[144:147], v[184:187], v[4:7]
	v_mfma_f32_16x16x32_bf16 v[0:3], v[152:155], v[184:187], v[0:3]
	v_mfma_f32_16x16x32_bf16 v[52:55], v[148:151], v[164:167], v[52:55]
	v_mfma_f32_16x16x32_bf16 v[44:47], v[156:159], v[164:167], v[44:47]
	v_mfma_f32_16x16x32_bf16 v[36:39], v[148:151], v[172:175], v[36:39]
	v_mfma_f32_16x16x32_bf16 v[28:31], v[156:159], v[172:175], v[28:31]
	v_mfma_f32_16x16x32_bf16 v[20:23], v[148:151], v[180:183], v[20:23]
	v_mfma_f32_16x16x32_bf16 v[12:15], v[156:159], v[180:183], v[12:15]
	v_mfma_f32_16x16x32_bf16 v[4:7], v[148:151], v[188:191], v[4:7]
	v_mfma_f32_16x16x32_bf16 v[0:3], v[156:159], v[188:191], v[0:3]
	s_barrier
	s_add_i32 s61, s61, 2
	s_add_u32 s23, s23, 0x100
	s_addc_u32 s60, s60, 0
	s_add_u32 s4, s4, 0x100
	s_addc_u32 s5, s5, 0
	s_cmp_gt_u32 s61, 13
	s_cbranch_scc0 .LBB0_1519
	s_and_b64 vcc, exec, s[12:13]
	s_cbranch_vccz .LBB0_1522
	s_barrier
